# stack-retout-retstate-prepflush-handwritten-foldexp-gemm-backedge-salu-before-barrier
# speedup vs baseline: 1.0044x; 1.0044x over previous
; #define PG8_STAGE(bufoff, gbase, voff) do { _Pragma("unroll") for (int _i = 0; _i < 2; ++_i) \
;         __builtin_amdgcn_global_load_lds((const unsigned*)((const char*)(gbase) + (voff)[_i]), (PG8_LAS unsigned*)(lds + (bufoff) + ldsw + _i * 8192), 16, 0, 0); } while (0)
; #define PG8_LDA(dst, b, h) do { _Pragma("unroll") for (int m = 0; m < 4; ++m) _Pragma("unroll") for (int k = 0; k < 2; ++k) dst[m][k] = *(const PG8_LAS bf16x8*)(lds + PG8_SA(b, h) + aoff + m * 2048 + k * 1024); } while (0)
; #define PG8_LDB(dst, b, h) do { _Pragma("unroll") for (int n = 0; n < 2; ++n) _Pragma("unroll") for (int k = 0; k < 2; ++k) dst[n][k] = *(const PG8_LAS bf16x8*)(lds + PG8_SB(b, h) + boff + n * 2048 + k * 1024); } while (0)
; #define PG8_MMA(ai, bj, At, Bt) do { __builtin_amdgcn_s_setprio(1); _Pragma("unroll") for (int m = 0; m < 4; ++m) _Pragma("unroll") for (int n = 0; n < 2; ++n) _Pragma("unroll") for (int k = 0; k < 2; ++k) \
;         acc[ai][bj][m][n] = __builtin_amdgcn_mfma_f32_16x16x32_bf16(Bt[n][k], At[m][k], acc[ai][bj][m][n], 0, 0, 0); __builtin_amdgcn_s_setprio(0); } while (0)
; #define PG8_WAIT_V(n) asm volatile("s_waitcnt vmcnt(" #n ")" ::: "memory")
; #define PG8_WAIT_L(n) asm volatile("s_waitcnt lgkmcnt(" #n ")" ::: "memory")
; template <class Epi, class Sched, bool ALIGN_EPI = false, bool SP2 = false>
; __device__ __forceinline__ void gemm_phase(PG8_LAS unsigned char* lds, const Gemm g, const Sched& S, const Epi& E) {
;     ...
;             const bool last = (t == nt - 2);
;             const char* a1 = cA + (size_t)(t + 1) * kstep;
;             const char* a2 = last ? nA : cA + (size_t)(t + 2) * kstep; const char* b2 = last ? nB : cB + (size_t)(t + 2) * kstep;
;             const char* a3 = a2 + kstep; const char* b3 = b2 + kstep;
;             if (last && has_next) S.a_ready(nxt);
;             if constexpr (SP2) {
;             PG8_LDB(B0, 0, 0); PG8_LDB(B1, 0, 1); PG8_SCHED; PG8_LDA(At, 0, 0); PG8_STAGE(PG8_SA(1, 1), a1 + hstep, voffA);
;             PG8_WAIT_V(8); PG8_WAIT_L(0); PG8_BAR; PG8_MMA(0, 0, At, B0); PG8_MMA(0, 1, At, B1); PG8_BAR; PG8_SCHED;
;             PG8_LDA(At, 0, 1); PG8_STAGE(PG8_SB(0, 0), b2, voffB); PG8_STAGE(PG8_SB(0, 1), b2 + hstep, voffB); PG8_STAGE(PG8_SA(0, 0), a2, voffA);
;             PG8_WAIT_V(8); PG8_WAIT_L(0); PG8_BAR; PG8_MMA(1, 0, At, B0); PG8_MMA(1, 1, At, B1); PG8_BAR; PG8_SCHED;
.LBB0_188:
	s_add_u32 s52, s42, 0xfffc0080
	s_addc_u32 s53, s43, -1
	s_add_i32 s70, 0, 0x10000
	s_cmp_eq_u32 s91, 12
	s_cselect_b32 s55, s6, s53
	s_cselect_b32 s54, s7, s52
	s_cselect_b32 s53, s45, s90
	s_cselect_b32 s52, s47, s89
	s_add_i32 s71, 0, 0x14000
	v_add_u32_e32 v158, s70, v147
	v_add_u32_e32 v162, s71, v147
	ds_read_b128 v[142:145], v158
	ds_read_b128 v[150:153], v158 offset:1024
	ds_read_b128 v[154:157], v158 offset:2048
	ds_read_b128 v[158:161], v158 offset:3072
	ds_read_b128 v[180:183], v162
	ds_read_b128 v[184:187], v162 offset:1024
	ds_read_b128 v[188:191], v162 offset:2048
	ds_read_b128 v[192:195], v162 offset:3072
	v_lshl_add_u64 v[162:163], s[42:43], 0, v[138:139]
	s_add_i32 m0, s57, 0xc000
	ds_read_b128 v[208:211], v149
	ds_read_b128 v[212:215], v149 offset:1024
	ds_read_b128 v[216:219], v149 offset:2048
	ds_read_b128 v[224:227], v149 offset:3072
	ds_read_b128 v[228:231], v149 offset:4096
	ds_read_b128 v[232:235], v149 offset:5120
	ds_read_b128 v[236:239], v149 offset:6144
	ds_read_b128 v[240:243], v149 offset:7168
	global_load_lds_dwordx4 v[162:163], off
	v_lshl_add_u64 v[162:163], s[42:43], 0, v[140:141]
	s_add_i32 m0, s57, 0xe000
	s_nop 0
	global_load_lds_dwordx4 v[162:163], off
	s_waitcnt vmcnt(8)
	s_waitcnt lgkmcnt(0)
	s_barrier
	s_setprio 1
	s_waitcnt lgkmcnt(0)
	v_mfma_f32_16x16x32_bf16 v[128:131], v[142:145], v[208:211], v[128:131]
	v_mfma_f32_16x16x32_bf16 v[124:127], v[154:157], v[208:211], v[124:127]
	v_mfma_f32_16x16x32_bf16 v[116:119], v[142:145], v[216:219], v[116:119]
	v_mfma_f32_16x16x32_bf16 v[108:111], v[154:157], v[216:219], v[108:111]
	v_mfma_f32_16x16x32_bf16 v[100:103], v[142:145], v[228:231], v[100:103]
	v_mfma_f32_16x16x32_bf16 v[92:95], v[154:157], v[228:231], v[92:95]
	v_mfma_f32_16x16x32_bf16 v[84:87], v[142:145], v[236:239], v[84:87]
	v_mfma_f32_16x16x32_bf16 v[76:79], v[154:157], v[236:239], v[76:79]
	v_mfma_f32_16x16x32_bf16 v[128:131], v[150:153], v[212:215], v[128:131]
	v_mfma_f32_16x16x32_bf16 v[124:127], v[158:161], v[212:215], v[124:127]
	v_mfma_f32_16x16x32_bf16 v[116:119], v[150:153], v[224:227], v[116:119]
	v_mfma_f32_16x16x32_bf16 v[108:111], v[158:161], v[224:227], v[108:111]
	v_mfma_f32_16x16x32_bf16 v[100:103], v[150:153], v[232:235], v[100:103]
	v_mfma_f32_16x16x32_bf16 v[92:95], v[158:161], v[232:235], v[92:95]
	v_mfma_f32_16x16x32_bf16 v[84:87], v[150:153], v[240:243], v[84:87]
	v_mfma_f32_16x16x32_bf16 v[76:79], v[158:161], v[240:243], v[76:79]
	s_setprio 0
	s_setprio 1
	v_mfma_f32_16x16x32_bf16 v[120:123], v[180:183], v[208:211], v[120:123]
	v_mfma_f32_16x16x32_bf16 v[112:115], v[188:191], v[208:211], v[112:115]
	v_mfma_f32_16x16x32_bf16 v[104:107], v[180:183], v[216:219], v[104:107]
	v_mfma_f32_16x16x32_bf16 v[96:99], v[188:191], v[216:219], v[96:99]
	v_mfma_f32_16x16x32_bf16 v[88:91], v[180:183], v[228:231], v[88:91]
	v_mfma_f32_16x16x32_bf16 v[80:83], v[188:191], v[228:231], v[80:83]
	v_mfma_f32_16x16x32_bf16 v[72:75], v[180:183], v[236:239], v[72:75]
	v_mfma_f32_16x16x32_bf16 v[68:71], v[188:191], v[236:239], v[68:71]
	v_mfma_f32_16x16x32_bf16 v[120:123], v[184:187], v[212:215], v[120:123]
	v_mfma_f32_16x16x32_bf16 v[112:115], v[192:195], v[212:215], v[112:115]
	v_mfma_f32_16x16x32_bf16 v[104:107], v[184:187], v[224:227], v[104:107]
	v_mfma_f32_16x16x32_bf16 v[96:99], v[192:195], v[224:227], v[96:99]
	v_mfma_f32_16x16x32_bf16 v[88:91], v[184:187], v[232:235], v[88:91]
	v_mfma_f32_16x16x32_bf16 v[80:83], v[192:195], v[232:235], v[80:83]
	v_mfma_f32_16x16x32_bf16 v[72:75], v[184:187], v[240:243], v[72:75]
	v_mfma_f32_16x16x32_bf16 v[68:71], v[192:195], v[240:243], v[68:71]
	s_setprio 0
	s_barrier
	s_add_i32 s70, s70, s56
	v_lshl_add_u64 v[162:163], s[52:53], 0, v[2:3]
	s_mov_b32 m0, s70
	ds_read_b128 v[208:211], v149 offset:16384
	ds_read_b128 v[212:215], v149 offset:17408
	ds_read_b128 v[216:219], v149 offset:18432
	ds_read_b128 v[224:227], v149 offset:19456
	ds_read_b128 v[228:231], v149 offset:20480
	ds_read_b128 v[232:235], v149 offset:21504
	ds_read_b128 v[236:239], v149 offset:22528
	ds_read_b128 v[240:243], v149 offset:23552
	global_load_lds_dwordx4 v[162:163], off
	s_add_i32 m0, s70, 0x2000
	s_add_u32 vcc_lo, s52, 0x40000
	v_lshl_add_u64 v[196:197], s[52:53], 0, v[132:133]
	s_addc_u32 vcc_hi, s53, 0
	s_add_i32 s70, s71, s56
	global_load_lds_dwordx4 v[196:197], off
	v_lshl_add_u64 v[244:245], vcc, 0, v[2:3]
	s_mov_b32 m0, s70
	v_lshl_add_u64 v[246:247], s[54:55], 0, v[134:135]
	global_load_lds_dwordx4 v[244:245], off
	v_lshl_add_u64 v[244:245], vcc, 0, v[132:133]
	s_add_i32 m0, s70, 0x2000
	s_nop 0
	global_load_lds_dwordx4 v[244:245], off
	v_lshl_add_u64 v[244:245], s[54:55], 0, v[136:137]
	s_mov_b32 m0, s57
	s_nop 0
	global_load_lds_dwordx4 v[244:245], off
	s_mov_b32 m0, s78
	s_nop 0
	global_load_lds_dwordx4 v[246:247], off
	s_waitcnt vmcnt(8)
	s_waitcnt lgkmcnt(0)
	s_barrier
; #define PG8_STAGE(bufoff, gbase, voff) do { _Pragma("unroll") for (int _i = 0; _i < 2; ++_i) \
;         __builtin_amdgcn_global_load_lds((const unsigned*)((const char*)(gbase) + (voff)[_i]), (PG8_LAS unsigned*)(lds + (bufoff) + ldsw + _i * 8192), 16, 0, 0); } while (0)
; #define PG8_LDA(dst, b, h) do { _Pragma("unroll") for (int m = 0; m < 4; ++m) _Pragma("unroll") for (int k = 0; k < 2; ++k) dst[m][k] = *(const PG8_LAS bf16x8*)(lds + PG8_SA(b, h) + aoff + m * 2048 + k * 1024); } while (0)
; #define PG8_LDB(dst, b, h) do { _Pragma("unroll") for (int n = 0; n < 2; ++n) _Pragma("unroll") for (int k = 0; k < 2; ++k) dst[n][k] = *(const PG8_LAS bf16x8*)(lds + PG8_SB(b, h) + boff + n * 2048 + k * 1024); } while (0)
; #define PG8_MMA(ai, bj, At, Bt) do { __builtin_amdgcn_s_setprio(1); _Pragma("unroll") for (int m = 0; m < 4; ++m) _Pragma("unroll") for (int n = 0; n < 2; ++n) _Pragma("unroll") for (int k = 0; k < 2; ++k) \
;         acc[ai][bj][m][n] = __builtin_amdgcn_mfma_f32_16x16x32_bf16(Bt[n][k], At[m][k], acc[ai][bj][m][n], 0, 0, 0); __builtin_amdgcn_s_setprio(0); } while (0)
; #define PG8_WAIT_V(n) asm volatile("s_waitcnt vmcnt(" #n ")" ::: "memory")
; #define PG8_WAIT_L(n) asm volatile("s_waitcnt lgkmcnt(" #n ")" ::: "memory")
; #define PG8_BAR __builtin_amdgcn_s_barrier()
; #define PG8_SCHED __builtin_amdgcn_sched_barrier(0)
; template <class Epi, class Sched, bool ALIGN_EPI = false, bool SP2 = false>
; __device__ __forceinline__ void gemm_phase(PG8_LAS unsigned char* lds, const Gemm g, const Sched& S, const Epi& E) {
;     ...
;             PG8_WAIT_V(8); PG8_WAIT_L(0); PG8_BAR; PG8_MMA(1, 0, At, B0); PG8_MMA(1, 1, At, B1); PG8_BAR; PG8_SCHED;
;             PG8_LDB(B0, 1, 0); PG8_LDB(B1, 1, 1); PG8_SCHED; PG8_LDA(At, 1, 0); PG8_STAGE(PG8_SA(0, 1), a2 + hstep, voffA);
;             PG8_WAIT_V(8); PG8_WAIT_L(0); PG8_BAR; PG8_MMA(0, 0, At, B0); PG8_MMA(0, 1, At, B1); PG8_BAR; PG8_SCHED;
	s_setprio 1
	s_waitcnt lgkmcnt(0)
	v_mfma_f32_16x16x32_bf16 v[64:67], v[142:145], v[208:211], v[64:67]
	v_mfma_f32_16x16x32_bf16 v[60:63], v[154:157], v[208:211], v[60:63]
	v_mfma_f32_16x16x32_bf16 v[52:55], v[142:145], v[216:219], v[52:55]
	v_mfma_f32_16x16x32_bf16 v[44:47], v[154:157], v[216:219], v[44:47]
	v_mfma_f32_16x16x32_bf16 v[36:39], v[142:145], v[228:231], v[36:39]
	v_mfma_f32_16x16x32_bf16 v[28:31], v[154:157], v[228:231], v[28:31]
	v_mfma_f32_16x16x32_bf16 v[20:23], v[142:145], v[236:239], v[20:23]
	v_mfma_f32_16x16x32_bf16 v[12:15], v[154:157], v[236:239], v[12:15]
	v_mfma_f32_16x16x32_bf16 v[64:67], v[150:153], v[212:215], v[64:67]
	v_mfma_f32_16x16x32_bf16 v[60:63], v[158:161], v[212:215], v[60:63]
	v_mfma_f32_16x16x32_bf16 v[52:55], v[150:153], v[224:227], v[52:55]
	v_mfma_f32_16x16x32_bf16 v[44:47], v[158:161], v[224:227], v[44:47]
	v_mfma_f32_16x16x32_bf16 v[36:39], v[150:153], v[232:235], v[36:39]
	v_mfma_f32_16x16x32_bf16 v[28:31], v[158:161], v[232:235], v[28:31]
	v_mfma_f32_16x16x32_bf16 v[20:23], v[150:153], v[240:243], v[20:23]
	v_mfma_f32_16x16x32_bf16 v[12:15], v[158:161], v[240:243], v[12:15]
	s_setprio 0
	s_setprio 1
	v_mfma_f32_16x16x32_bf16 v[56:59], v[180:183], v[208:211], v[56:59]
	v_mfma_f32_16x16x32_bf16 v[48:51], v[188:191], v[208:211], v[48:51]
	v_mfma_f32_16x16x32_bf16 v[40:43], v[180:183], v[216:219], v[40:43]
	v_mfma_f32_16x16x32_bf16 v[32:35], v[188:191], v[216:219], v[32:35]
	v_mfma_f32_16x16x32_bf16 v[24:27], v[180:183], v[228:231], v[24:27]
	v_mfma_f32_16x16x32_bf16 v[16:19], v[188:191], v[228:231], v[16:19]
	v_mfma_f32_16x16x32_bf16 v[8:11], v[180:183], v[236:239], v[8:11]
	v_mfma_f32_16x16x32_bf16 v[4:7], v[188:191], v[236:239], v[4:7]
	v_mfma_f32_16x16x32_bf16 v[56:59], v[184:187], v[212:215], v[56:59]
	v_mfma_f32_16x16x32_bf16 v[48:51], v[192:195], v[212:215], v[48:51]
	v_mfma_f32_16x16x32_bf16 v[40:43], v[184:187], v[224:227], v[40:43]
	v_mfma_f32_16x16x32_bf16 v[32:35], v[192:195], v[224:227], v[32:35]
	v_mfma_f32_16x16x32_bf16 v[24:27], v[184:187], v[232:235], v[24:27]
	v_mfma_f32_16x16x32_bf16 v[16:19], v[192:195], v[232:235], v[16:19]
	v_mfma_f32_16x16x32_bf16 v[8:11], v[184:187], v[240:243], v[8:11]
	v_mfma_f32_16x16x32_bf16 v[4:7], v[192:195], v[240:243], v[4:7]
	s_setprio 0
	s_barrier
	s_add_i32 s70, 0, 0x18000
	s_add_i32 s71, 0, 0x1c000
	v_add_u32_e32 v158, s70, v147
	v_add_u32_e32 v167, s71, v147
	ds_read_b128 v[142:145], v158
	ds_read_b128 v[150:153], v158 offset:1024
	ds_read_b128 v[154:157], v158 offset:2048
	ds_read_b128 v[158:161], v158 offset:3072
	ds_read_b128 v[180:183], v167
	ds_read_b128 v[184:187], v167 offset:1024
	ds_read_b128 v[188:191], v167 offset:2048
	ds_read_b128 v[192:195], v167 offset:3072
	s_add_u32 s54, s54, 0x40000
	s_addc_u32 s55, s55, 0
	s_mov_b32 m0, s79
	v_lshl_add_u64 v[248:249], s[54:55], 0, v[136:137]
	ds_read_b128 v[208:211], v149 offset:32768
	ds_read_b128 v[212:215], v149 offset:33792
	ds_read_b128 v[216:219], v149 offset:34816
	ds_read_b128 v[224:227], v149 offset:35840
	ds_read_b128 v[228:231], v149 offset:36864
	ds_read_b128 v[232:235], v149 offset:37888
	ds_read_b128 v[236:239], v149 offset:38912
	ds_read_b128 v[240:243], v149 offset:39936
	global_load_lds_dwordx4 v[248:249], off
	v_lshl_add_u64 v[248:249], s[54:55], 0, v[134:135]
	s_mov_b32 m0, s80
	s_nop 0
	global_load_lds_dwordx4 v[248:249], off
	s_waitcnt vmcnt(8)
	s_waitcnt lgkmcnt(0)
	s_barrier
	s_setprio 1
	s_waitcnt lgkmcnt(0)
	v_mfma_f32_16x16x32_bf16 v[128:131], v[142:145], v[208:211], v[128:131]
	v_mfma_f32_16x16x32_bf16 v[124:127], v[154:157], v[208:211], v[124:127]
	v_mfma_f32_16x16x32_bf16 v[116:119], v[142:145], v[216:219], v[116:119]
	v_mfma_f32_16x16x32_bf16 v[108:111], v[154:157], v[216:219], v[108:111]
	v_mfma_f32_16x16x32_bf16 v[100:103], v[142:145], v[228:231], v[100:103]
	v_mfma_f32_16x16x32_bf16 v[92:95], v[154:157], v[228:231], v[92:95]
	v_mfma_f32_16x16x32_bf16 v[84:87], v[142:145], v[236:239], v[84:87]
	v_mfma_f32_16x16x32_bf16 v[76:79], v[154:157], v[236:239], v[76:79]
	v_mfma_f32_16x16x32_bf16 v[128:131], v[150:153], v[212:215], v[128:131]
	v_mfma_f32_16x16x32_bf16 v[124:127], v[158:161], v[212:215], v[124:127]
	v_mfma_f32_16x16x32_bf16 v[116:119], v[150:153], v[224:227], v[116:119]
	v_mfma_f32_16x16x32_bf16 v[108:111], v[158:161], v[224:227], v[108:111]
	v_mfma_f32_16x16x32_bf16 v[100:103], v[150:153], v[232:235], v[100:103]
	v_mfma_f32_16x16x32_bf16 v[92:95], v[158:161], v[232:235], v[92:95]
	v_mfma_f32_16x16x32_bf16 v[84:87], v[150:153], v[240:243], v[84:87]
	v_mfma_f32_16x16x32_bf16 v[76:79], v[158:161], v[240:243], v[76:79]
	s_setprio 0
	s_setprio 1
	v_mfma_f32_16x16x32_bf16 v[120:123], v[180:183], v[208:211], v[120:123]
	v_mfma_f32_16x16x32_bf16 v[112:115], v[188:191], v[208:211], v[112:115]
	v_mfma_f32_16x16x32_bf16 v[104:107], v[180:183], v[216:219], v[104:107]
	v_mfma_f32_16x16x32_bf16 v[96:99], v[188:191], v[216:219], v[96:99]
	v_mfma_f32_16x16x32_bf16 v[88:91], v[180:183], v[228:231], v[88:91]
	v_mfma_f32_16x16x32_bf16 v[80:83], v[188:191], v[228:231], v[80:83]
	v_mfma_f32_16x16x32_bf16 v[72:75], v[180:183], v[236:239], v[72:75]
	v_mfma_f32_16x16x32_bf16 v[68:71], v[188:191], v[236:239], v[68:71]
	v_mfma_f32_16x16x32_bf16 v[120:123], v[184:187], v[212:215], v[120:123]
	v_mfma_f32_16x16x32_bf16 v[112:115], v[192:195], v[212:215], v[112:115]
	v_mfma_f32_16x16x32_bf16 v[104:107], v[184:187], v[224:227], v[104:107]
	v_mfma_f32_16x16x32_bf16 v[96:99], v[192:195], v[224:227], v[96:99]
	v_mfma_f32_16x16x32_bf16 v[88:91], v[184:187], v[232:235], v[88:91]
	v_mfma_f32_16x16x32_bf16 v[80:83], v[192:195], v[232:235], v[80:83]
	v_mfma_f32_16x16x32_bf16 v[72:75], v[184:187], v[240:243], v[72:75]
	v_mfma_f32_16x16x32_bf16 v[68:71], v[192:195], v[240:243], v[68:71]
	s_setprio 0
	s_barrier
; #define PG8_STAGE(bufoff, gbase, voff) do { _Pragma("unroll") for (int _i = 0; _i < 2; ++_i) \
;         __builtin_amdgcn_global_load_lds((const unsigned*)((const char*)(gbase) + (voff)[_i]), (PG8_LAS unsigned*)(lds + (bufoff) + ldsw + _i * 8192), 16, 0, 0); } while (0)
; #define PG8_LDA(dst, b, h) do { _Pragma("unroll") for (int m = 0; m < 4; ++m) _Pragma("unroll") for (int k = 0; k < 2; ++k) dst[m][k] = *(const PG8_LAS bf16x8*)(lds + PG8_SA(b, h) + aoff + m * 2048 + k * 1024); } while (0)
; #define PG8_LDB(dst, b, h) do { _Pragma("unroll") for (int n = 0; n < 2; ++n) _Pragma("unroll") for (int k = 0; k < 2; ++k) dst[n][k] = *(const PG8_LAS bf16x8*)(lds + PG8_SB(b, h) + boff + n * 2048 + k * 1024); } while (0)
; template <class Epi, class Sched, bool ALIGN_EPI = false, bool SP2 = false>
; __device__ __forceinline__ void gemm_phase(PG8_LAS unsigned char* lds, const Gemm g, const Sched& S, const Epi& E) {
;     ...
;         for (int t = 0; t < nt; t += 2) {
;             const bool last = (t == nt - 2);
;             const char* a1 = cA + (size_t)(t + 1) * kstep;
;             const char* a2 = last ? nA : cA + (size_t)(t + 2) * kstep; const char* b2 = last ? nB : cB + (size_t)(t + 2) * kstep;
;             const char* a3 = a2 + kstep; const char* b3 = b2 + kstep;
;             if (last && has_next) S.a_ready(nxt);
;             if constexpr (SP2) {
;             PG8_LDB(B0, 0, 0); PG8_LDB(B1, 0, 1); PG8_SCHED; PG8_LDA(At, 0, 0); PG8_STAGE(PG8_SA(1, 1), a1 + hstep, voffA);
;             PG8_WAIT_V(8); PG8_WAIT_L(0); PG8_BAR; PG8_MMA(0, 0, At, B0); PG8_MMA(0, 1, At, B1); PG8_BAR; PG8_SCHED;
;             PG8_LDA(At, 0, 1); PG8_STAGE(PG8_SB(0, 0), b2, voffB); PG8_STAGE(PG8_SB(0, 1), b2 + hstep, voffB); PG8_STAGE(PG8_SA(0, 0), a2, voffA);
;             PG8_WAIT_V(8); PG8_WAIT_L(0); PG8_BAR; PG8_MMA(1, 0, At, B0); PG8_MMA(1, 1, At, B1); PG8_BAR; PG8_SCHED;
;             PG8_LDB(B0, 1, 0); PG8_LDB(B1, 1, 1); PG8_SCHED; PG8_LDA(At, 1, 0); PG8_STAGE(PG8_SA(0, 1), a2 + hstep, voffA);
;             PG8_WAIT_V(8); PG8_WAIT_L(0); PG8_BAR; PG8_MMA(0, 0, At, B0); PG8_MMA(0, 1, At, B1); PG8_BAR; PG8_SCHED;
;             PG8_LDA(At, 1, 1); PG8_STAGE(PG8_SB(1, 0), b3, voffB); PG8_STAGE(PG8_SB(1, 1), b3 + hstep, voffB); PG8_STAGE(PG8_SA(1, 0), a3, voffA);
;             PG8_WAIT_V(8); PG8_WAIT_L(0); PG8_BAR; PG8_MMA(1, 0, At, B0); PG8_MMA(1, 1, At, B1); PG8_BAR; PG8_SCHED;
	s_add_i32 s54, s70, s56
	v_lshl_add_u64 v[162:163], v[162:163], 0, s[14:15]
	s_mov_b32 m0, s54
	ds_read_b128 v[208:211], v149 offset:49152
	ds_read_b128 v[212:215], v149 offset:50176
	ds_read_b128 v[216:219], v149 offset:51200
	ds_read_b128 v[224:227], v149 offset:52224
	ds_read_b128 v[228:231], v149 offset:53248
	ds_read_b128 v[232:235], v149 offset:54272
	ds_read_b128 v[236:239], v149 offset:55296
	ds_read_b128 v[240:243], v149 offset:56320
	global_load_lds_dwordx4 v[162:163], off
	s_add_i32 m0, s54, 0x2000
	s_add_u32 s52, s52, 0x40080
	v_lshl_add_u64 v[162:163], v[196:197], 0, s[14:15]
	s_addc_u32 s53, s53, 0
	s_add_i32 s54, s71, s56
	global_load_lds_dwordx4 v[162:163], off
	v_lshl_add_u64 v[162:163], s[52:53], 0, v[2:3]
	s_mov_b32 m0, s54
	s_nop 0
	global_load_lds_dwordx4 v[162:163], off
	v_lshl_add_u64 v[162:163], s[52:53], 0, v[132:133]
	s_add_i32 m0, s54, 0x2000
	s_nop 0
	global_load_lds_dwordx4 v[162:163], off
	v_lshl_add_u64 v[162:163], v[244:245], 0, s[14:15]
	s_mov_b32 m0, s81
	s_nop 0
	global_load_lds_dwordx4 v[162:163], off
	v_lshl_add_u64 v[162:163], v[246:247], 0, s[14:15]
	s_mov_b32 m0, s82
	s_nop 0
	global_load_lds_dwordx4 v[162:163], off
	s_waitcnt vmcnt(8)
	s_waitcnt lgkmcnt(0)
	s_barrier
	s_setprio 1
	s_waitcnt lgkmcnt(0)
	v_mfma_f32_16x16x32_bf16 v[64:67], v[142:145], v[208:211], v[64:67]
	v_mfma_f32_16x16x32_bf16 v[60:63], v[154:157], v[208:211], v[60:63]
	v_mfma_f32_16x16x32_bf16 v[52:55], v[142:145], v[216:219], v[52:55]
	v_mfma_f32_16x16x32_bf16 v[44:47], v[154:157], v[216:219], v[44:47]
	v_mfma_f32_16x16x32_bf16 v[36:39], v[142:145], v[228:231], v[36:39]
	v_mfma_f32_16x16x32_bf16 v[28:31], v[154:157], v[228:231], v[28:31]
	v_mfma_f32_16x16x32_bf16 v[20:23], v[142:145], v[236:239], v[20:23]
	v_mfma_f32_16x16x32_bf16 v[12:15], v[154:157], v[236:239], v[12:15]
	v_mfma_f32_16x16x32_bf16 v[64:67], v[150:153], v[212:215], v[64:67]
	v_mfma_f32_16x16x32_bf16 v[60:63], v[158:161], v[212:215], v[60:63]
	v_mfma_f32_16x16x32_bf16 v[52:55], v[150:153], v[224:227], v[52:55]
	v_mfma_f32_16x16x32_bf16 v[44:47], v[158:161], v[224:227], v[44:47]
	v_mfma_f32_16x16x32_bf16 v[36:39], v[150:153], v[232:235], v[36:39]
	v_mfma_f32_16x16x32_bf16 v[28:31], v[158:161], v[232:235], v[28:31]
	v_mfma_f32_16x16x32_bf16 v[20:23], v[150:153], v[240:243], v[20:23]
	v_mfma_f32_16x16x32_bf16 v[12:15], v[158:161], v[240:243], v[12:15]
	s_setprio 0
	s_setprio 1
	v_mfma_f32_16x16x32_bf16 v[56:59], v[180:183], v[208:211], v[56:59]
	v_mfma_f32_16x16x32_bf16 v[48:51], v[188:191], v[208:211], v[48:51]
	v_mfma_f32_16x16x32_bf16 v[40:43], v[180:183], v[216:219], v[40:43]
	v_mfma_f32_16x16x32_bf16 v[32:35], v[188:191], v[216:219], v[32:35]
	v_mfma_f32_16x16x32_bf16 v[24:27], v[180:183], v[228:231], v[24:27]
	v_mfma_f32_16x16x32_bf16 v[16:19], v[188:191], v[228:231], v[16:19]
	v_mfma_f32_16x16x32_bf16 v[8:11], v[180:183], v[236:239], v[8:11]
	v_mfma_f32_16x16x32_bf16 v[4:7], v[188:191], v[236:239], v[4:7]
	v_mfma_f32_16x16x32_bf16 v[56:59], v[184:187], v[212:215], v[56:59]
	v_mfma_f32_16x16x32_bf16 v[48:51], v[192:195], v[212:215], v[48:51]
	v_mfma_f32_16x16x32_bf16 v[40:43], v[184:187], v[224:227], v[40:43]
	v_mfma_f32_16x16x32_bf16 v[32:35], v[192:195], v[224:227], v[32:35]
	v_mfma_f32_16x16x32_bf16 v[24:27], v[184:187], v[232:235], v[24:27]
	v_mfma_f32_16x16x32_bf16 v[16:19], v[192:195], v[232:235], v[16:19]
	v_mfma_f32_16x16x32_bf16 v[8:11], v[184:187], v[240:243], v[8:11]
	v_mfma_f32_16x16x32_bf16 v[4:7], v[192:195], v[240:243], v[4:7]
	s_setprio 0
	s_add_i32 s91, s91, 2
	s_add_u32 s42, s42, 0x100
	s_addc_u32 s43, s43, 0
	s_add_u32 s89, s89, 0x100
	s_addc_u32 s90, s90, 0
	s_cmp_gt_u32 s91, 13
	s_barrier
	s_cbranch_scc0 .LBB0_188
	s_and_b64 vcc, exec, s[36:37]
	s_cbranch_vccz .LBB0_191
	s_barrier

; #define LAS __attribute__((address_space(3)))
; #define ZERO_ENDS4(A) do { if (!pz) A[1] = (u32x4){0u, 0u, 0u, 0u}; if (!nz) A[2] = (u32x4){0u, 0u, 0u, 0u}; } while (0)
; __device__ __forceinline__ void prep_y(int l, int b, int h, int dir, int c, LAS float* rg, const LAS float* cst, int lane) {
;     PREP_COMMON();
;     const bf16* Wi = (const bf16*)(ws + OFF_WIC) + (size_t)dir * DM * 64;
;     u32x4 cir[2][3];
; #pragma unroll
;     for (int ks = 0; ks < 2; ++ks) { const bf16* q = rawA + 3200 + 64 * dir + 32 * ks + 8 * fq; cir[ks][0] = *(const u32x4*)q; cir[ks][1] = *(const u32x4*)(q + dp); cir[ks][2] = *(const u32x4*)(q + dn); }
;     u32x4 wir[4][2]; u32x2 kr[4][3], rr_[4][3];
; #pragma unroll
;     for (int nb = 0; nb < 4; ++nb) { const int chr = h * 64 + nb * 16 + fr;
; #pragma unroll
;         for (int ks = 0; ks < 2; ++ks) wir[nb][ks] = *(const u32x4*)(Wi + (size_t)chr * 64 + 32 * ks + 8 * fq);
;         const bf16* q = rawA + h * 64 + nb * 16 + 4 * fq;
;         rr_[nb][0] = *(const u32x2*)q; rr_[nb][1] = *(const u32x2*)(q + dp); rr_[nb][2] = *(const u32x2*)(q + dn);
;         kr[nb][0] = *(const u32x2*)(q + 1024); kr[nb][1] = *(const u32x2*)(q + 1024 + dp); kr[nb][2] = *(const u32x2*)(q + 1024 + dn); }
;     __builtin_amdgcn_sched_barrier(0);
;     bf16x8 bi[2];
; #pragma unroll
;     for (int ks = 0; ks < 2; ++ks) {
;         float o[8]; const int cc = 128 + 64 * dir + 32 * ks + 8 * fq;
;         ZERO_ENDS4(cir[ks]);
;         mix8p(cir[ks][0], cir[ks][1], cir[ks][2], cst + C_CMP + cc, cst + C_CMN + cc, o);
.LBB0_308:
	s_or_b64 exec, exec, s[52:53]
	s_load_dwordx2 s[100:101], s[0:1], 0xb8
	s_ashr_i32 s34, s57, 4
	s_waitcnt lgkmcnt(0)
	s_ashr_i32 s35, s34, 31
	s_andn2_b64 vcc, exec, s[92:93]
	s_lshl_b64 s[30:31], s[34:35], 11
	s_waitcnt lgkmcnt(0)
	s_barrier
	s_cbranch_vccnz .LBB0_362
	s_mov_b64 s[6:7], -1
	s_and_b64 vcc, exec, s[94:95]
	s_cbranch_vccz .LBB0_313
	s_mov_b64 s[6:7], s[0:1]
	s_load_dwordx2 s[36:37], s[6:7], 0xb8
	v_mov_b32_e32 v112, v160
	s_lshl_b32 s96, s8, 1
	v_and_b32_e32 v113, 15, v112
	v_bitop3_b32 v2, v112, s24, 15 bitop3:0x6c
	v_cndmask_b32_e64 v2, v2, v113, s[38:39]
	v_or_b32_e32 v4, s30, v2
	s_waitcnt lgkmcnt(0)
	v_mov_b64_e32 v[10:11], s[36:37]
	v_ashrrev_i32_e32 v5, 4, v112
	v_mad_u64_u32 v[10:11], s[6:7], v4, s22, v[10:11]
	v_mad_i32_i24 v11, s31, v202, v11
	v_lshlrev_b32_e32 v62, 3, v5
	v_lshl_add_u64 v[10:11], v[10:11], 0, s[12:13]
	v_ashrrev_i32_e32 v63, 31, v62
	v_lshl_add_u64 v[14:15], v[10:11], 0, s[96:97]
	v_lshlrev_b64 v[16:17], 1, v[62:63]
	v_lshl_add_u64 v[14:15], v[14:15], 0, v[16:17]
	s_mov_b64 s[6:7], 0x1900
	v_cmp_eq_u32_e32 vcc, 0, v2
	v_cmp_eq_u32_e64 s[48:49], s24, v2
	v_lshl_add_u64 v[22:23], v[14:15], 0, s[6:7]
	v_add_co_u32_e64 v14, s[50:51], s25, v14
	s_add_u32 s6, s36, s5
	v_cndmask_b32_e64 v13, -1, 0, vcc
	v_cndmask_b32_e64 v12, v203, 0, vcc
	v_cndmask_b32_e64 v2, v202, 0, s[48:49]
	v_addc_co_u32_e64 v15, s[50:51], 0, v15, s[50:51]
	s_addc_u32 s7, s37, 0
	v_lshl_add_u64 v[26:27], v[22:23], 0, v[12:13]
	v_lshl_add_u64 v[28:29], v[22:23], 0, v[2:3]
	global_load_dwordx4 v[18:21], v[14:15], off offset:2304
	s_nop 0
	global_load_dwordx4 v[22:25], v[22:23], off offset:64
	s_nop 0
	global_load_dwordx4 v[88:91], v[26:27], off
	global_load_dwordx4 v[92:95], v[26:27], off offset:64
	global_load_dwordx4 v[114:117], v[28:29], off
	global_load_dwordx4 v[128:131], v[28:29], off offset:64
	v_lshl_add_u64 v[14:15], s[6:7], 0, v[16:17]
	s_lshl_b32 s96, s56, 1
	v_lshlrev_b32_e32 v16, 2, v5
	v_lshl_add_u64 v[10:11], v[10:11], 0, s[96:97]
	v_ashrrev_i32_e32 v17, 31, v16
	v_or_b32_e32 v5, s56, v113
	v_lshl_add_u64 v[44:45], v[16:17], 1, v[10:11]
	v_lshlrev_b32_e32 v10, 7, v5
	v_mov_b32_e32 v11, v3
	v_lshl_add_u64 v[10:11], v[14:15], 0, v[10:11]
	s_mov_b64 s[6:7], 0x1b40000
	v_lshl_add_u64 v[14:15], v[10:11], 0, s[6:7]
	s_mov_b32 s6, 0x1b41000
	v_add_co_u32_e64 v10, s[50:51], s6, v10
	v_lshl_add_u64 v[64:65], v[44:45], 0, v[12:13]
	s_nop 0
	v_addc_co_u32_e64 v11, s[50:51], 0, v11, s[50:51]
	v_lshl_add_u64 v[102:103], v[44:45], 0, v[2:3]
	global_load_dwordx4 v[46:49], v[14:15], off offset:64
	global_load_dwordx4 v[38:41], v[14:15], off offset:2048
	global_load_dwordx2 v[98:99], v[64:65], off
	global_load_dwordx4 v[34:37], v[14:15], off offset:2112
	global_load_dwordx4 v[50:53], v[10:11], off offset:-4096
	global_load_dwordx4 v[30:33], v[10:11], off
	global_load_dwordx4 v[26:29], v[10:11], off offset:64
	s_nop 0
	global_load_dwordx4 v[14:17], v[10:11], off offset:2048
	s_nop 0
	global_load_dwordx4 v[10:13], v[10:11], off offset:2112
	s_nop 0
	global_load_dwordx2 v[96:97], v[44:45], off
	global_load_dwordx2 v[76:77], v[44:45], off offset:32
	global_load_dwordx2 v[66:67], v[44:45], off offset:64
	global_load_dwordx2 v[54:55], v[44:45], off offset:96
	global_load_dwordx2 v[106:107], v[64:65], off offset:2048
	global_load_dwordx2 v[78:79], v[64:65], off offset:32
	global_load_dwordx2 v[68:69], v[64:65], off offset:64
	global_load_dwordx2 v[56:57], v[64:65], off offset:96
	global_load_dwordx2 v[110:111], v[102:103], off offset:2048
	global_load_dwordx2 v[80:81], v[102:103], off offset:32
	global_load_dwordx2 v[70:71], v[102:103], off offset:64
	global_load_dwordx2 v[58:59], v[102:103], off offset:96
	global_load_dwordx2 v[42:43], v[44:45], off offset:2048
	global_load_dwordx2 v[82:83], v[44:45], off offset:2080
	global_load_dwordx2 v[72:73], v[44:45], off offset:2112
	global_load_dwordx2 v[60:61], v[44:45], off offset:2144
	global_load_dwordx2 v[100:101], v[102:103], off
	global_load_dwordx2 v[84:85], v[64:65], off offset:2080
	global_load_dwordx2 v[74:75], v[64:65], off offset:2112
	s_nop 0
	global_load_dwordx2 v[64:65], v[64:65], off offset:2144
	s_nop 0
	global_load_dwordx2 v[86:87], v[102:103], off offset:2080
	global_load_dwordx2 v[104:105], v[102:103], off offset:2112
	global_load_dwordx2 v[108:109], v[102:103], off offset:2144
	v_readlane_b32 s6, v255, 55
	v_mov_b32_e32 v5, s31
	s_nop 0
	v_mov_b32_e32 v2, s6
	v_mad_u32_u24 v63, v113, s72, v2
	v_add_u32_e32 v2, s9, v62
	v_lshl_add_u32 v2, v2, 2, 0
	s_waitcnt vmcnt(35)
	v_cndmask_b32_e64 v103, v88, 0, vcc
	v_add_u32_e32 v142, 0x24800, v2
	v_cndmask_b32_e64 v44, v91, 0, vcc
	v_cndmask_b32_e64 v45, v90, 0, vcc
	v_cndmask_b32_e64 v102, v89, 0, vcc
	s_waitcnt vmcnt(33)
	v_cndmask_b32_e64 v113, v117, 0, s[48:49]
	v_cndmask_b32_e64 v127, v116, 0, s[48:49]
	v_cndmask_b32_e64 v140, v115, 0, s[48:49]
	v_cndmask_b32_e64 v141, v114, 0, s[48:49]
	v_add_u32_e32 v2, 0x24c00, v2
	ds_read_b128 v[88:91], v142
	ds_read_b128 v[114:117], v142 offset:16
	ds_read_b128 v[132:135], v2
	ds_read_b128 v[136:139], v2 offset:16
	v_lshlrev_b32_e32 v143, 16, v18
	v_lshlrev_b32_e32 v145, 16, v103
	v_lshlrev_b32_e32 v144, 16, v141
	v_sub_f32_e32 v145, v145, v143
	v_and_b32_e32 v18, 0xffff0000, v18
	v_and_b32_e32 v103, 0xffff0000, v103
	v_sub_f32_e32 v144, v144, v143
	s_waitcnt lgkmcnt(3)
	v_fmac_f32_e32 v143, v88, v145
	v_and_b32_e32 v88, 0xffff0000, v141
	v_sub_f32_e32 v103, v103, v18
	v_sub_f32_e32 v88, v88, v18
	v_fmac_f32_e32 v18, v89, v103
	s_waitcnt lgkmcnt(1)
; #define LAS __attribute__((address_space(3)))
; __device__ __forceinline__ bf16x8 pack8(const float* f) { return __builtin_bit_cast(bf16x8, pack8u(f)); }
; #define ZERO_ENDS4(A) do { if (!pz) A[1] = (u32x4){0u, 0u, 0u, 0u}; if (!nz) A[2] = (u32x4){0u, 0u, 0u, 0u}; } while (0)
; #define ZERO_ENDS2(A) do { if (!pz) A[1] = (u32x2){0u, 0u}; if (!nz) A[2] = (u32x2){0u, 0u}; } while (0)
; __device__ __forceinline__ void prep_y(int l, int b, int h, int dir, int c, LAS float* rg, const LAS float* cst, int lane) {
;     ...
;     for (int ks = 0; ks < 2; ++ks) {
;         float o[8]; const int cc = 128 + 64 * dir + 32 * ks + 8 * fq;
;         ZERO_ENDS4(cir[ks]);
;         mix8p(cir[ks][0], cir[ks][1], cir[ks][2], cst + C_CMP + cc, cst + C_CMN + cc, o);
;         bi[ks] = pack8(o);
;     }
;     float kk[16]; float ss = 0.f;
; #pragma unroll
;     for (int nb = 0; nb < 4; ++nb) {
;         const int co = nb * 16 + 4 * fq;
;         ZERO_ENDS2(kr[nb]);
;         mix4p(kr[nb][0], kr[nb][1], kr[nb][2], cst + C_RMP + 64 + co, cst + C_RMN + 64 + co, kk + 4 * nb);
;         const f32x4 kkw = *(const LAS f32x4*)(cst + C_KK + co);
; #pragma unroll
;         for (int i = 0; i < 4; ++i) { const float kr_ = kk[4 * nb + i] * kkw[i]; ss += kr_ * kr_; }
	v_fmac_f32_e32 v18, v133, v88
	v_lshlrev_b32_e32 v88, 16, v19
	v_lshlrev_b32_e32 v103, 16, v102
	v_lshlrev_b32_e32 v89, 16, v140
	v_sub_f32_e32 v103, v103, v88
	v_sub_f32_e32 v89, v89, v88
	v_fmac_f32_e32 v88, v90, v103
	v_and_b32_e32 v19, 0xffff0000, v19
	v_and_b32_e32 v90, 0xffff0000, v102
	v_fmac_f32_e32 v88, v134, v89
	v_and_b32_e32 v89, 0xffff0000, v140
	v_sub_f32_e32 v90, v90, v19
	v_sub_f32_e32 v89, v89, v19
	v_fmac_f32_e32 v19, v91, v90
	v_fmac_f32_e32 v19, v135, v89
	v_lshlrev_b32_e32 v89, 16, v20
	v_lshlrev_b32_e32 v91, 16, v45
	v_lshlrev_b32_e32 v90, 16, v127
	v_sub_f32_e32 v91, v91, v89
	v_sub_f32_e32 v90, v90, v89
	v_fmac_f32_e32 v89, v114, v91
	v_and_b32_e32 v20, 0xffff0000, v20
	v_and_b32_e32 v45, 0xffff0000, v45
	s_waitcnt lgkmcnt(0)
	v_fmac_f32_e32 v89, v136, v90
	v_and_b32_e32 v90, 0xffff0000, v127
	v_sub_f32_e32 v45, v45, v20
	v_sub_f32_e32 v90, v90, v20
	v_fmac_f32_e32 v20, v115, v45
	v_lshlrev_b32_e32 v45, 16, v21
	v_lshlrev_b32_e32 v91, 16, v44
	v_fmac_f32_e32 v20, v137, v90
	v_lshlrev_b32_e32 v90, 16, v113
	v_sub_f32_e32 v91, v91, v45
	v_sub_f32_e32 v90, v90, v45
	v_fmac_f32_e32 v45, v116, v91
	v_and_b32_e32 v21, 0xffff0000, v21
	v_and_b32_e32 v44, 0xffff0000, v44
	v_fmac_f32_e32 v45, v138, v90
	v_and_b32_e32 v90, 0xffff0000, v113
	v_sub_f32_e32 v44, v44, v21
	v_sub_f32_e32 v90, v90, v21
	v_fmac_f32_e32 v21, v117, v44
	v_fmac_f32_e32 v21, v139, v90
	v_cndmask_b32_e64 v103, v92, 0, vcc
	v_fmac_f32_e32 v143, v132, v144
	v_cvt_pk_bf16_f32 v19, v88, v19
	v_cvt_pk_bf16_f32 v20, v89, v20
	v_cvt_pk_bf16_f32 v21, v45, v21
	v_cndmask_b32_e64 v44, v95, 0, vcc
	v_cndmask_b32_e64 v45, v94, 0, vcc
	v_cndmask_b32_e64 v102, v93, 0, vcc
	s_waitcnt vmcnt(32)
	v_cndmask_b32_e64 v113, v131, 0, s[48:49]
	v_cndmask_b32_e64 v127, v130, 0, s[48:49]
	v_cndmask_b32_e64 v132, v129, 0, s[48:49]
	v_cndmask_b32_e64 v133, v128, 0, s[48:49]
	ds_read_b128 v[88:91], v142 offset:128
	ds_read_b128 v[92:95], v142 offset:144
	ds_read_b128 v[114:117], v2 offset:128
	ds_read_b128 v[128:131], v2 offset:144
	v_lshlrev_b32_e32 v2, 16, v22
	v_lshlrev_b32_e32 v135, 16, v103
	v_lshlrev_b32_e32 v134, 16, v133
	v_sub_f32_e32 v135, v135, v2
	v_and_b32_e32 v22, 0xffff0000, v22
	v_and_b32_e32 v103, 0xffff0000, v103
	v_sub_f32_e32 v134, v134, v2
	s_waitcnt lgkmcnt(3)
	v_fmac_f32_e32 v2, v88, v135
	v_and_b32_e32 v88, 0xffff0000, v133
	v_sub_f32_e32 v103, v103, v22
	v_sub_f32_e32 v88, v88, v22
	v_fmac_f32_e32 v22, v89, v103
	s_waitcnt lgkmcnt(1)
	v_fmac_f32_e32 v22, v115, v88
	v_lshlrev_b32_e32 v88, 16, v23
	v_lshlrev_b32_e32 v103, 16, v102
	v_lshlrev_b32_e32 v89, 16, v132
	v_sub_f32_e32 v103, v103, v88
	v_sub_f32_e32 v89, v89, v88
	v_fmac_f32_e32 v88, v90, v103
	v_and_b32_e32 v23, 0xffff0000, v23
	v_and_b32_e32 v90, 0xffff0000, v102
	v_fmac_f32_e32 v88, v116, v89
	v_and_b32_e32 v89, 0xffff0000, v132
	v_sub_f32_e32 v90, v90, v23
	v_sub_f32_e32 v89, v89, v23
	v_fmac_f32_e32 v23, v91, v90
	v_fmac_f32_e32 v23, v117, v89
	v_lshlrev_b32_e32 v89, 16, v24
	v_lshlrev_b32_e32 v91, 16, v45
	v_lshlrev_b32_e32 v90, 16, v127
	v_sub_f32_e32 v91, v91, v89
	v_sub_f32_e32 v90, v90, v89
	v_fmac_f32_e32 v89, v92, v91
	v_and_b32_e32 v24, 0xffff0000, v24
	v_and_b32_e32 v45, 0xffff0000, v45
	s_waitcnt lgkmcnt(0)
	v_fmac_f32_e32 v89, v128, v90
	v_and_b32_e32 v90, 0xffff0000, v127
	v_sub_f32_e32 v45, v45, v24
	v_sub_f32_e32 v90, v90, v24
	v_fmac_f32_e32 v24, v93, v45
	v_lshlrev_b32_e32 v45, 16, v25
	v_lshlrev_b32_e32 v91, 16, v44
	v_fmac_f32_e32 v24, v129, v90
	v_lshlrev_b32_e32 v90, 16, v113
	v_sub_f32_e32 v91, v91, v45
	v_sub_f32_e32 v90, v90, v45
	v_fmac_f32_e32 v45, v94, v91
	v_and_b32_e32 v25, 0xffff0000, v25
	v_and_b32_e32 v44, 0xffff0000, v44
	v_and_b32_e32 v115, -16, v112
	v_fmac_f32_e32 v45, v130, v90
	v_and_b32_e32 v90, 0xffff0000, v113
	v_sub_f32_e32 v44, v44, v25
	v_cvt_pk_bf16_f32 v24, v89, v24
	v_add_u32_e32 v89, 0, v115
	v_sub_f32_e32 v90, v90, v25
	v_fmac_f32_e32 v25, v95, v44
	v_add_u32_e32 v91, 0x25100, v89
	v_fmac_f32_e32 v2, v114, v134
	v_fmac_f32_e32 v25, v131, v90
	v_add_u32_e32 v93, 0x25400, v89
	ds_read_b128 v[128:131], v91
	ds_read_b128 v[132:135], v93
	s_waitcnt vmcnt(18)
	v_cndmask_b32_e64 v44, v106, 0, vcc
	v_cvt_pk_bf16_f32 v23, v88, v23
	s_waitcnt vmcnt(14)
	v_cndmask_b32_e64 v88, v110, 0, s[48:49]
	s_waitcnt vmcnt(10)
	v_lshlrev_b32_e32 v90, 16, v42
	v_lshlrev_b32_e32 v94, 16, v44
	v_lshlrev_b32_e32 v92, 16, v88
	v_sub_f32_e32 v94, v94, v90
	v_sub_f32_e32 v92, v92, v90
	s_waitcnt lgkmcnt(1)
	v_fmac_f32_e32 v90, v128, v94
	s_waitcnt lgkmcnt(0)
	v_fmac_f32_e32 v90, v132, v92
	v_and_b32_e32 v92, 0xffff0000, v42
	v_and_b32_e32 v44, 0xffff0000, v44
	v_cvt_pk_bf16_f32 v22, v2, v22
	v_cndmask_b32_e64 v2, v107, 0, vcc
	v_and_b32_e32 v42, 0xffff0000, v88
	v_sub_f32_e32 v44, v44, v92
	v_cvt_pk_bf16_f32 v25, v45, v25
	v_cndmask_b32_e64 v45, v111, 0, s[48:49]
	v_sub_f32_e32 v42, v42, v92
	v_fmac_f32_e32 v92, v129, v44
	v_lshlrev_b32_e32 v94, 16, v43
	v_lshlrev_b32_e32 v44, 16, v2
	v_fmac_f32_e32 v92, v133, v42
	v_lshlrev_b32_e32 v42, 16, v45
	v_sub_f32_e32 v44, v44, v94
	v_sub_f32_e32 v42, v42, v94
	v_fmac_f32_e32 v94, v130, v44
	v_and_b32_e32 v88, 0xffff0000, v43
	v_and_b32_e32 v2, 0xffff0000, v2
	v_fmac_f32_e32 v94, v134, v42
	v_and_b32_e32 v42, 0xffff0000, v45
	v_sub_f32_e32 v2, v2, v88
	v_sub_f32_e32 v42, v42, v88
	v_fmac_f32_e32 v88, v131, v2
	v_add_u32_e32 v2, 0x25a00, v89
	v_fmac_f32_e32 v88, v135, v42
	ds_read_b128 v[42:45], v2
	ds_read_b128 v[128:131], v91 offset:64
	ds_read_b128 v[132:135], v93 offset:64
	s_waitcnt vmcnt(5)
	v_cndmask_b32_e64 v95, v84, 0, vcc
	s_waitcnt vmcnt(2)
; #define LAS __attribute__((address_space(3)))
; #define MFMA16(a, b, c) __builtin_amdgcn_mfma_f32_16x16x32_bf16((a), (b), (c), 0, 0, 0)
; #define ZERO_ENDS2(A) do { if (!pz) A[1] = (u32x2){0u, 0u}; if (!nz) A[2] = (u32x2){0u, 0u}; } while (0)
; __device__ __forceinline__ void prep_y(int l, int b, int h, int dir, int c, LAS float* rg, const LAS float* cst, int lane) {
;     ...
;     for (int nb = 0; nb < 4; ++nb) {
;         const int co = nb * 16 + 4 * fq;
;         ZERO_ENDS2(kr[nb]);
;         mix4p(kr[nb][0], kr[nb][1], kr[nb][2], cst + C_RMP + 64 + co, cst + C_RMN + 64 + co, kk + 4 * nb);
;         const f32x4 kkw = *(const LAS f32x4*)(cst + C_KK + co);
; #pragma unroll
;         for (int i = 0; i < 4; ++i) { const float kr_ = kk[4 * nb + i] * kkw[i]; ss += kr_ * kr_; }
;     }
;     ss += __shfl_xor(ss, 16); ss += __shfl_xor(ss, 32);
;     const float nrm = rsqrtf(ss + 1e-12f);
;     float cs = 0.f;
; #pragma unroll
;     for (int nb = 0; nb < 4; ++nb) {
;         f32x4 aI = {0.f, 0.f, 0.f, 0.f};
; #pragma unroll
;         for (int ks = 0; ks < 2; ++ks) aI = MFMA16(__builtin_bit_cast(bf16x8, wir[nb][ks]), bi[ks], aI);
;         const int co = nb * 16 + 4 * fq;
;         float rr[4];
;         ZERO_ENDS2(rr_[nb]);
;         mix4p(rr_[nb][0], rr_[nb][1], rr_[nb][2], cst + C_RMP + co, cst + C_RMN + co, rr);
	v_cndmask_b32_e64 v102, v86, 0, s[48:49]
	v_lshlrev_b32_e32 v86, 16, v82
	v_lshlrev_b32_e32 v103, 16, v95
	v_lshlrev_b32_e32 v84, 16, v102
	v_sub_f32_e32 v103, v103, v86
	v_sub_f32_e32 v84, v84, v86
	s_waitcnt lgkmcnt(1)
	v_fmac_f32_e32 v86, v128, v103
	s_waitcnt lgkmcnt(0)
	v_fmac_f32_e32 v86, v132, v84
	v_and_b32_e32 v84, 0xffff0000, v82
	v_and_b32_e32 v95, 0xffff0000, v95
	v_and_b32_e32 v82, 0xffff0000, v102
	v_sub_f32_e32 v95, v95, v84
	v_cndmask_b32_e64 v85, v85, 0, vcc
	v_sub_f32_e32 v82, v82, v84
	v_fmac_f32_e32 v84, v129, v95
	v_cndmask_b32_e64 v87, v87, 0, s[48:49]
	v_fmac_f32_e32 v84, v133, v82
	v_lshlrev_b32_e32 v82, 16, v83
	v_lshlrev_b32_e32 v102, 16, v85
	v_and_b32_e32 v83, 0xffff0000, v83
	v_and_b32_e32 v85, 0xffff0000, v85
	v_lshlrev_b32_e32 v95, 16, v87
	v_sub_f32_e32 v102, v102, v82
	v_and_b32_e32 v87, 0xffff0000, v87
	v_sub_f32_e32 v85, v85, v83
	v_sub_f32_e32 v95, v95, v82
	v_fmac_f32_e32 v82, v130, v102
	v_sub_f32_e32 v87, v87, v83
	v_fmac_f32_e32 v83, v131, v85
	ds_read_b128 v[128:131], v2 offset:64
	v_fmac_f32_e32 v82, v134, v95
	v_fmac_f32_e32 v83, v135, v87
	s_waitcnt vmcnt(1)
	v_cndmask_b32_e64 v111, v105, 0, s[48:49]
	s_waitcnt lgkmcnt(0)
	v_mul_f32_e32 v87, v86, v128
	v_mul_f32_e32 v85, v84, v129
	v_pk_mul_f32 v[102:103], v[82:83], v[130:131]
	v_cndmask_b32_e64 v113, v104, 0, s[48:49]
	ds_read_b128 v[104:107], v91 offset:128
	ds_read_b128 v[128:131], v93 offset:128
	v_cndmask_b32_e64 v110, v74, 0, vcc
	v_lshlrev_b32_e32 v74, 16, v72
	v_lshlrev_b32_e32 v114, 16, v110
	v_cndmask_b32_e64 v95, v75, 0, vcc
	v_lshlrev_b32_e32 v75, 16, v113
	v_sub_f32_e32 v114, v114, v74
	v_sub_f32_e32 v75, v75, v74
	s_waitcnt lgkmcnt(1)
	v_fmac_f32_e32 v74, v104, v114
	s_waitcnt lgkmcnt(0)
	v_fmac_f32_e32 v74, v128, v75
	v_and_b32_e32 v75, 0xffff0000, v72
	v_and_b32_e32 v104, 0xffff0000, v110
	v_and_b32_e32 v72, 0xffff0000, v113
	v_sub_f32_e32 v104, v104, v75
	v_sub_f32_e32 v72, v72, v75
	v_fmac_f32_e32 v75, v105, v104
	v_fmac_f32_e32 v75, v129, v72
	v_lshlrev_b32_e32 v72, 16, v73
	v_lshlrev_b32_e32 v105, 16, v95
	v_lshlrev_b32_e32 v104, 16, v111
	v_sub_f32_e32 v105, v105, v72
	v_sub_f32_e32 v104, v104, v72
	v_fmac_f32_e32 v72, v106, v105
	v_and_b32_e32 v73, 0xffff0000, v73
	v_and_b32_e32 v95, 0xffff0000, v95
	v_fmac_f32_e32 v72, v130, v104
	v_and_b32_e32 v104, 0xffff0000, v111
	v_sub_f32_e32 v95, v95, v73
	v_sub_f32_e32 v104, v104, v73
	v_fmac_f32_e32 v73, v107, v95
	v_fmac_f32_e32 v73, v131, v104
	ds_read_b128 v[104:107], v2 offset:128
	s_waitcnt vmcnt(0)
	v_cndmask_b32_e64 v114, v109, 0, s[48:49]
	v_cndmask_b32_e64 v116, v108, 0, s[48:49]
	ds_read_b128 v[108:111], v91 offset:192
	ds_read_b128 v[128:131], v93 offset:192
	v_cndmask_b32_e64 v113, v64, 0, vcc
	v_lshlrev_b32_e32 v64, 16, v60
	v_lshlrev_b32_e32 v91, 16, v113
	v_cndmask_b32_e64 v95, v65, 0, vcc
	v_lshlrev_b32_e32 v65, 16, v116
	v_sub_f32_e32 v91, v91, v64
	v_sub_f32_e32 v65, v65, v64
	s_waitcnt lgkmcnt(1)
	v_fmac_f32_e32 v64, v108, v91
	s_waitcnt lgkmcnt(0)
	v_fmac_f32_e32 v64, v128, v65
	v_and_b32_e32 v65, 0xffff0000, v60
	v_and_b32_e32 v91, 0xffff0000, v113
	v_and_b32_e32 v60, 0xffff0000, v116
	v_sub_f32_e32 v91, v91, v65
	v_sub_f32_e32 v60, v60, v65
	v_fmac_f32_e32 v65, v109, v91
	v_fmac_f32_e32 v65, v129, v60
	v_lshlrev_b32_e32 v60, 16, v61
	v_lshlrev_b32_e32 v93, 16, v95
	v_lshlrev_b32_e32 v91, 16, v114
	v_sub_f32_e32 v93, v93, v60
	v_sub_f32_e32 v91, v91, v60
	v_fmac_f32_e32 v60, v110, v93
	v_and_b32_e32 v61, 0xffff0000, v61
	v_and_b32_e32 v93, 0xffff0000, v95
	v_fmac_f32_e32 v60, v130, v91
	v_and_b32_e32 v91, 0xffff0000, v114
	v_sub_f32_e32 v93, v93, v61
	v_sub_f32_e32 v91, v91, v61
	v_fmac_f32_e32 v61, v111, v93
	v_and_b32_e32 v93, 64, v198
	v_cvt_pk_bf16_f32 v18, v143, v18
	v_fmac_f32_e32 v61, v131, v91
	v_xor_b32_e32 v91, 16, v198
	v_add_u32_e32 v93, 64, v93
	v_cmp_lt_i32_e64 s[50:51], v91, v93
	v_mfma_f32_16x16x32_bf16 v[50:53], v[50:53], v[18:21], 0
	ds_read_b128 v[108:111], v2 offset:192
	v_cndmask_b32_e64 v91, v198, v91, s[50:51]
	v_lshlrev_b32_e32 v114, 2, v91
	v_xor_b32_e32 v91, 32, v198
	v_cmp_lt_i32_e64 s[50:51], v91, v93
	v_mfma_f32_16x16x32_bf16 v[128:131], v[46:49], v[22:25], v[50:53]
	v_cndmask_b32_e64 v93, v100, 0, s[48:49]
	v_cndmask_b32_e64 v91, v198, v91, s[50:51]
	v_lshlrev_b32_e32 v113, 2, v91
	v_add_u32_e32 v52, 0x25000, v89
	v_cndmask_b32_e64 v50, v99, 0, vcc
	v_cndmask_b32_e64 v51, v98, 0, vcc
	v_cndmask_b32_e64 v91, v101, 0, s[48:49]
	v_add_u32_e32 v53, 0x25300, v89
	ds_read_b128 v[46:49], v52
	ds_read_b128 v[98:101], v53
	v_lshlrev_b32_e32 v127, 16, v96
	v_lshlrev_b32_e32 v116, 16, v51
	v_lshlrev_b32_e32 v95, 16, v93
	v_sub_f32_e32 v116, v116, v127
	v_and_b32_e32 v142, 0xffff0000, v96
	v_and_b32_e32 v51, 0xffff0000, v51
	v_sub_f32_e32 v95, v95, v127
	s_waitcnt lgkmcnt(1)
	v_fmac_f32_e32 v127, v46, v116
	v_and_b32_e32 v46, 0xffff0000, v93
	v_sub_f32_e32 v51, v51, v142
	v_sub_f32_e32 v46, v46, v142
	v_fmac_f32_e32 v142, v47, v51
	v_lshlrev_b32_e32 v143, 16, v97
	v_lshlrev_b32_e32 v47, 16, v50
	s_waitcnt lgkmcnt(0)
	v_fmac_f32_e32 v142, v99, v46
	v_lshlrev_b32_e32 v46, 16, v91
	v_sub_f32_e32 v47, v47, v143
	v_sub_f32_e32 v46, v46, v143
	v_fmac_f32_e32 v143, v48, v47
	v_and_b32_e32 v97, 0xffff0000, v97
	v_and_b32_e32 v47, 0xffff0000, v50
	v_fmac_f32_e32 v143, v100, v46
	v_and_b32_e32 v46, 0xffff0000, v91
	v_sub_f32_e32 v47, v47, v97
	v_sub_f32_e32 v46, v46, v97
	v_fmac_f32_e32 v97, v49, v47
	v_add_u32_e32 v96, s68, v115
	v_fmac_f32_e32 v127, v98, v95
	v_fmac_f32_e32 v97, v101, v46
	ds_read_b128 v[98:101], v96
	v_add_u32_e32 v50, 0x25b00, v89
	v_add_u32_e32 v51, 0x25c00, v89
	ds_read_b128 v[132:135], v50
	ds_read_b128 v[46:49], v51
	s_waitcnt lgkmcnt(2)
; #define LAS __attribute__((address_space(3)))
; __device__ __forceinline__ unsigned cvtpk(float lo, float hi) { const f32x2 v = {lo, hi}; const bf16x2_t b = __builtin_convertvector(v, bf16x2_t); return __builtin_bit_cast(unsigned, b); }
; __device__ __forceinline__ float sigm(float x) { return __builtin_amdgcn_rcpf(1.0f + __expf(-x)); }
; #define MFMA16(a, b, c) __builtin_amdgcn_mfma_f32_16x16x32_bf16((a), (b), (c), 0, 0, 0)
; #define ZERO_ENDS2(A) do { if (!pz) A[1] = (u32x2){0u, 0u}; if (!nz) A[2] = (u32x2){0u, 0u}; } while (0)
; __device__ __forceinline__ void prep_y(int l, int b, int h, int dir, int c, LAS float* rg, const LAS float* cst, int lane) {
;     ...
;     ss += __shfl_xor(ss, 16); ss += __shfl_xor(ss, 32);
;     const float nrm = rsqrtf(ss + 1e-12f);
;     float cs = 0.f;
; #pragma unroll
;     for (int nb = 0; nb < 4; ++nb) {
;         f32x4 aI = {0.f, 0.f, 0.f, 0.f};
; #pragma unroll
;         for (int ks = 0; ks < 2; ++ks) aI = MFMA16(__builtin_bit_cast(bf16x8, wir[nb][ks]), bi[ks], aI);
;         const int co = nb * 16 + 4 * fq;
;         float rr[4];
;         ZERO_ENDS2(rr_[nb]);
;         mix4p(rr_[nb][0], rr_[nb][1], rr_[nb][2], cst + C_RMP + co, cst + C_RMN + co, rr);
;         const f32x4 ibias = *(const LAS f32x4*)(cst + C_IB + 64 * dir + co);
;         const f32x4 kkw = *(const LAS f32x4*)(cst + C_KK + co), kaw = *(const LAS f32x4*)(cst + C_KA + co), rkw = *(const LAS f32x4*)(cst + C_RK + co);
;         f32x4 va, vb, vkd, vr;
; #pragma unroll
;         for (int i = 0; i < 4; ++i) {
;             const float al = sigm(ibias[i] + aI[i]);
;             const float kraw = kk[4 * nb + i];
;             const float kn = kraw * kkw[i] * nrm;
;             const float kd = kraw * (1.0f + (al - 1.0f) * kaw[i]);
;             va[i] = -kn; vb[i] = kn * al; vkd[i] = kd; vr[i] = rr[i];
;             cs += rr[i] * kd * rkw[i];
;         }
;         *(LAS u32x4*)(rs_ + 128 + co) = (u32x4){cvtpk(0.25f * vb[0], 0.25f * vkd[0]), cvtpk(0.25f * vb[1], 0.25f * vkd[1]), cvtpk(0.25f * vb[2], 0.25f * vkd[2]), cvtpk(0.25f * vb[3], 0.25f * vkd[3])};
;         *(LAS u32x2*)(rs_ + 192 + (co >> 1)) = (u32x2){cvtpk(va[0], va[1]), cvtpk(va[2], va[3])};
;         *(LAS u32x2*)(rs_ + 224 + (co >> 1)) = (u32x2){cvtpk(vr[0], vr[1]), cvtpk(vr[2], vr[3])};
	v_add_f32_e32 v89, v128, v98
	v_mul_f32_e32 v89, 0xbfb8aa3b, v89
	v_exp_f32_e32 v89, v89
	v_mov_b32_e32 v138, v43
	s_waitcnt lgkmcnt(1)
	v_mov_b32_e32 v43, v132
	v_add_f32_e32 v89, 1.0, v89
	v_rcp_f32_e32 v98, v89
	v_add_f32_e32 v89, v129, v99
	v_mul_f32_e32 v89, 0xbfb8aa3b, v89
	v_exp_f32_e32 v89, v89
	v_add_f32_e32 v91, -1.0, v98
	v_mov_b32_e32 v139, v133
	v_pk_mul_f32 v[132:133], v[90:91], v[42:43]
	v_add_f32_e32 v89, 1.0, v89
	v_rcp_f32_e32 v116, v89
	v_add_f32_e32 v89, v130, v100
	v_mul_f32_e32 v89, 0xbfb8aa3b, v89
	v_exp_f32_e32 v89, v89
	v_add_f32_e32 v93, -1.0, v116
	v_mov_b32_e32 v130, v45
	v_mov_b32_e32 v45, v134
	v_add_f32_e32 v89, 1.0, v89
	v_rcp_f32_e32 v100, v89
	v_add_f32_e32 v89, v131, v101
	v_mul_f32_e32 v89, 0xbfb8aa3b, v89
	v_exp_f32_e32 v89, v89
	v_add_f32_e32 v95, -1.0, v100
	v_pk_mul_f32 v[140:141], v[92:93], v[138:139]
	v_mul_f32_e32 v99, v132, v132
	v_add_f32_e32 v89, 1.0, v89
	v_rcp_f32_e32 v128, v89
	v_mov_b32_e32 v131, v135
	v_pk_mul_f32 v[134:135], v[94:95], v[44:45]
	v_add_f32_e32 v89, -1.0, v128
	v_fmac_f32_e32 v99, v140, v140
	v_pk_mul_f32 v[136:137], v[88:89], v[130:131]
	v_fmac_f32_e32 v99, v134, v134
	v_fmac_f32_e32 v99, v136, v136
	v_fmac_f32_e32 v99, v87, v87
	v_pk_mul_f32 v[102:103], v[102:103], v[102:103]
	v_fmac_f32_e32 v99, v85, v85
	v_add_f32_e32 v85, v102, v99
	v_pk_mul_f32 v[104:105], v[74:75], v[104:105]
	v_add_f32_e32 v85, v103, v85
	v_pk_mul_f32 v[104:105], v[104:105], v[104:105]
	v_pk_fma_f32 v[42:43], v[90:91], v[42:43], s[2:3]
	v_pk_mul_f32 v[106:107], v[72:73], v[106:107]
	v_add_f32_e32 v85, v85, v104
	v_pk_mul_f32 v[106:107], v[106:107], v[106:107]
	v_add_f32_e32 v85, v105, v85
	v_pk_mul_f32 v[108:109], v[64:65], v[108:109]
	v_add_f32_e32 v85, v106, v85
	v_pk_mul_f32 v[108:109], v[108:109], v[108:109]
	v_add_f32_e32 v85, v107, v85
	v_pk_mul_f32 v[110:111], v[60:61], v[110:111]
	v_add_f32_e32 v85, v85, v108
	v_pk_mul_f32 v[110:111], v[110:111], v[110:111]
	v_add_f32_e32 v85, v109, v85
	v_add_f32_e32 v85, v110, v85
	v_add_f32_e32 v85, v111, v85
	ds_bpermute_b32 v87, v114, v85
	v_mov_b32_e32 v99, v90
	v_mov_b32_e32 v117, v92
	v_pk_fma_f32 v[92:93], v[92:93], v[138:139], s[2:3]
	s_waitcnt lgkmcnt(0)
	v_add_f32_e32 v85, v85, v87
	ds_bpermute_b32 v87, v113, v85
	v_pk_fma_f32 v[44:45], v[94:95], v[44:45], s[2:3]
	v_mov_b32_e32 v101, v94
	v_mov_b32_e32 v129, v88
	s_waitcnt lgkmcnt(0)
	v_add_f32_e32 v85, v85, v87
	v_add_f32_e32 v85, 0x2b8cbccc, v85
	v_cmp_gt_f32_e64 s[50:51], s19, v85
	v_mul_f32_e32 v87, 0x4b800000, v85
	v_mfma_f32_16x16x32_bf16 v[38:41], v[38:41], v[18:21], 0
	v_cndmask_b32_e64 v85, v85, v87, s[50:51]
	v_rsq_f32_e32 v85, v85
	v_mfma_f32_16x16x32_bf16 v[34:37], v[34:37], v[22:25], v[38:41]
	v_mul_f32_e32 v87, 0x45800000, v85
	v_cndmask_b32_e64 v168, v85, v87, s[50:51]
	v_pk_mul_f32 v[102:103], v[132:133], v[168:169]
	v_mfma_f32_16x16x32_bf16 v[30:33], v[30:33], v[18:21], 0
	v_mov_b32_e32 v103, v43
	v_pk_mul_f32 v[90:91], v[98:99], v[102:103]
	v_pk_mul_f32 v[98:99], v[140:141], v[168:169]
	v_mul_f32_e32 v42, v127, v91
	v_mov_b32_e32 v99, v93
	v_pk_mul_f32 v[92:93], v[116:117], v[98:99]
	v_fma_f32 v42, v46, v42, 0
	v_mul_f32_e32 v43, v142, v93
	v_fmac_f32_e32 v42, v47, v43
	v_pk_mul_f32 v[46:47], v[134:135], v[168:169]
	v_xor_b32_e32 v85, 0x80000000, v98
	v_mov_b32_e32 v47, v45
	v_pk_mul_f32 v[94:95], v[100:101], v[46:47]
	v_pk_add_f32 v[98:99], v[46:47], 0 neg_lo:[1,1] neg_hi:[1,1]
	v_pk_mul_f32 v[44:45], v[136:137], v[168:169]
	v_pk_fma_f32 v[46:47], v[88:89], v[130:131], s[2:3]
	v_mul_f32_e32 v43, v143, v95
	v_mov_b32_e32 v45, v47
	v_pk_mul_f32 v[88:89], v[128:129], v[44:45]
	v_fmac_f32_e32 v42, v48, v43
	v_xor_b32_e32 v87, 0x80000000, v44
	v_mul_f32_e32 v43, v97, v89
	v_pk_mul_f32 v[44:45], v[90:91], s[20:21] op_sel_hi:[1,0]
	v_pk_mul_f32 v[46:47], v[92:93], s[20:21] op_sel_hi:[1,0]
	v_fmac_f32_e32 v42, v49, v43
	v_cvt_pk_bf16_f32 v44, v44, v45
	v_cvt_pk_bf16_f32 v45, v46, v47
	v_pk_mul_f32 v[46:47], v[94:95], s[20:21] op_sel_hi:[1,0]
	v_pk_mul_f32 v[48:49], v[88:89], s[20:21] op_sel_hi:[1,0]
	v_add_u32_e32 v43, v63, v115
	v_pk_add_f32 v[100:101], v[102:103], 0 neg_lo:[1,1] neg_hi:[1,1]
	v_cvt_pk_bf16_f32 v46, v46, v47
	v_cvt_pk_bf16_f32 v47, v48, v49
	v_sub_u32_e32 v48, v43, v62
	ds_write_b128 v43, v[44:47] offset:33280
	v_cvt_pk_bf16_f32 v44, v100, v85
	v_cvt_pk_bf16_f32 v45, v98, v87
	v_cvt_pk_bf16_f32 v46, v127, v142
	v_cvt_pk_bf16_f32 v47, v143, v97
	v_add_u32_e32 v48, 0x8000, v48
	ds_write2_b64 v48, v[44:45], v[46:47] offset0:96 offset1:112
	ds_read_b128 v[38:41], v52 offset:64
	ds_read_b128 v[44:47], v53 offset:64
	v_cndmask_b32_e64 v49, v78, 0, vcc
	v_cndmask_b32_e64 v48, v79, 0, vcc
	v_cndmask_b32_e64 v78, v81, 0, s[48:49]
	v_cndmask_b32_e64 v79, v80, 0, s[48:49]
	v_lshlrev_b32_e32 v97, 16, v76
	v_lshlrev_b32_e32 v81, 16, v49
	v_lshlrev_b32_e32 v80, 16, v79
	v_sub_f32_e32 v81, v81, v97
	v_sub_f32_e32 v80, v80, v97
	s_waitcnt lgkmcnt(1)
	v_fmac_f32_e32 v97, v38, v81
	s_waitcnt lgkmcnt(0)
	v_fmac_f32_e32 v97, v44, v80
	v_and_b32_e32 v98, 0xffff0000, v76
	v_and_b32_e32 v44, 0xffff0000, v49
	v_and_b32_e32 v38, 0xffff0000, v79
	v_sub_f32_e32 v44, v44, v98
	v_sub_f32_e32 v38, v38, v98
	v_fmac_f32_e32 v98, v39, v44
	v_lshlrev_b32_e32 v99, 16, v77
	v_lshlrev_b32_e32 v39, 16, v48
	v_fmac_f32_e32 v98, v45, v38
	v_lshlrev_b32_e32 v38, 16, v78
	v_sub_f32_e32 v39, v39, v99
	v_sub_f32_e32 v38, v38, v99
	v_fmac_f32_e32 v99, v40, v39
	v_and_b32_e32 v100, 0xffff0000, v77
	v_and_b32_e32 v39, 0xffff0000, v48
	v_fmac_f32_e32 v99, v46, v38
	v_and_b32_e32 v38, 0xffff0000, v78
	v_sub_f32_e32 v39, v39, v100
	v_sub_f32_e32 v38, v38, v100
	v_fmac_f32_e32 v100, v41, v39
	v_fmac_f32_e32 v100, v47, v38
	ds_read_b128 v[44:47], v96 offset:64
	ds_read_b128 v[76:79], v2 offset:64
	ds_read_b128 v[88:91], v50 offset:64
	ds_read_b128 v[38:41], v51 offset:64
	s_waitcnt lgkmcnt(3)
; #define LAS __attribute__((address_space(3)))
; __device__ __forceinline__ unsigned cvtpk(float lo, float hi) { const f32x2 v = {lo, hi}; const bf16x2_t b = __builtin_convertvector(v, bf16x2_t); return __builtin_bit_cast(unsigned, b); }
; __device__ __forceinline__ float sigm(float x) { return __builtin_amdgcn_rcpf(1.0f + __expf(-x)); }
; #define MFMA16(a, b, c) __builtin_amdgcn_mfma_f32_16x16x32_bf16((a), (b), (c), 0, 0, 0)
; #define ZERO_ENDS2(A) do { if (!pz) A[1] = (u32x2){0u, 0u}; if (!nz) A[2] = (u32x2){0u, 0u}; } while (0)
; __device__ __forceinline__ void prep_y(int l, int b, int h, int dir, int c, LAS float* rg, const LAS float* cst, int lane) {
;     ...
;     for (int nb = 0; nb < 4; ++nb) {
;         f32x4 aI = {0.f, 0.f, 0.f, 0.f};
; #pragma unroll
;         for (int ks = 0; ks < 2; ++ks) aI = MFMA16(__builtin_bit_cast(bf16x8, wir[nb][ks]), bi[ks], aI);
;         const int co = nb * 16 + 4 * fq;
;         float rr[4];
;         ZERO_ENDS2(rr_[nb]);
;         mix4p(rr_[nb][0], rr_[nb][1], rr_[nb][2], cst + C_RMP + co, cst + C_RMN + co, rr);
;         const f32x4 ibias = *(const LAS f32x4*)(cst + C_IB + 64 * dir + co);
;         const f32x4 kkw = *(const LAS f32x4*)(cst + C_KK + co), kaw = *(const LAS f32x4*)(cst + C_KA + co), rkw = *(const LAS f32x4*)(cst + C_RK + co);
;         f32x4 va, vb, vkd, vr;
; #pragma unroll
;         for (int i = 0; i < 4; ++i) {
;             const float al = sigm(ibias[i] + aI[i]);
;             const float kraw = kk[4 * nb + i];
;             const float kn = kraw * kkw[i] * nrm;
;             const float kd = kraw * (1.0f + (al - 1.0f) * kaw[i]);
;             va[i] = -kn; vb[i] = kn * al; vkd[i] = kd; vr[i] = rr[i];
;             cs += rr[i] * kd * rkw[i];
;         }
;         *(LAS u32x4*)(rs_ + 128 + co) = (u32x4){cvtpk(0.25f * vb[0], 0.25f * vkd[0]), cvtpk(0.25f * vb[1], 0.25f * vkd[1]), cvtpk(0.25f * vb[2], 0.25f * vkd[2]), cvtpk(0.25f * vb[3], 0.25f * vkd[3])};
;         *(LAS u32x2*)(rs_ + 192 + (co >> 1)) = (u32x2){cvtpk(va[0], va[1]), cvtpk(va[2], va[3])};
;         *(LAS u32x2*)(rs_ + 224 + (co >> 1)) = (u32x2){cvtpk(vr[0], vr[1]), cvtpk(vr[2], vr[3])};
	v_add_f32_e32 v35, v35, v45
	v_mul_f32_e32 v35, 0xbfb8aa3b, v35
	v_exp_f32_e32 v35, v35
	v_add_f32_e32 v34, v34, v44
	v_mul_f32_e32 v34, 0xbfb8aa3b, v34
	v_exp_f32_e32 v34, v34
	v_add_f32_e32 v35, 1.0, v35
	v_rcp_f32_e32 v44, v35
	v_add_f32_e32 v35, v36, v46
	v_mul_f32_e32 v35, 0xbfb8aa3b, v35
	v_exp_f32_e32 v35, v35
	v_add_f32_e32 v34, 1.0, v34
	v_rcp_f32_e32 v34, v34
	v_add_f32_e32 v85, -1.0, v44
	v_add_f32_e32 v35, 1.0, v35
	v_rcp_f32_e32 v36, v35
	v_add_f32_e32 v35, v37, v47
	v_mul_f32_e32 v35, 0xbfb8aa3b, v35
	v_exp_f32_e32 v35, v35
	v_add_f32_e32 v87, -1.0, v34
	s_waitcnt lgkmcnt(2)
	v_mov_b32_e32 v92, v76
	s_waitcnt lgkmcnt(1)
	v_mov_b32_e32 v93, v88
	v_pk_mul_f32 v[94:95], v[86:87], v[76:77]
	v_mov_b32_e32 v88, v77
	v_add_f32_e32 v35, 1.0, v35
	v_pk_mul_f32 v[94:95], v[168:169], v[94:95]
	v_pk_fma_f32 v[92:93], v[86:87], v[92:93], s[2:3]
	v_pk_mul_f32 v[76:77], v[84:85], v[88:89]
	v_rcp_f32_e32 v46, v35
	v_mov_b32_e32 v95, v93
	v_mov_b32_e32 v35, v86
	v_pk_mul_f32 v[76:77], v[168:169], v[76:77]
	v_pk_fma_f32 v[86:87], v[84:85], v[88:89], s[2:3]
	v_pk_mul_f32 v[34:35], v[94:95], v[34:35]
	v_mov_b32_e32 v77, v87
	v_mov_b32_e32 v45, v84
	v_mul_f32_e32 v37, v97, v35
	v_pk_mul_f32 v[34:35], v[34:35], s[20:21] op_sel_hi:[1,0]
	v_pk_mul_f32 v[44:45], v[76:77], v[44:45]
	s_waitcnt lgkmcnt(0)
	v_fmac_f32_e32 v42, v38, v37
	v_cvt_pk_bf16_f32 v34, v34, v35
	v_mul_f32_e32 v35, v98, v45
	v_fmac_f32_e32 v42, v39, v35
	v_pk_mul_f32 v[38:39], v[44:45], s[20:21] op_sel_hi:[1,0]
	v_add_f32_e32 v49, -1.0, v36
	v_cvt_pk_bf16_f32 v35, v38, v39
	v_mov_b32_e32 v48, v82
	v_mov_b32_e32 v38, v78
	v_mov_b32_e32 v39, v90
	v_pk_mul_f32 v[44:45], v[82:83], v[78:79]
	v_pk_fma_f32 v[38:39], v[48:49], v[38:39], s[2:3]
	v_pk_mul_f32 v[44:45], v[168:169], v[44:45]
	v_add_f32_e32 v81, -1.0, v46
	v_mov_b32_e32 v45, v39
	v_mov_b32_e32 v37, v82
	v_mov_b32_e32 v80, v83
	v_mov_b32_e32 v90, v79
	v_pk_add_f32 v[38:39], v[44:45], 0 neg_lo:[1,1] neg_hi:[1,1]
	v_pk_mul_f32 v[36:37], v[44:45], v[36:37]
	v_pk_mul_f32 v[44:45], v[80:81], v[90:91]
	v_pk_fma_f32 v[48:49], v[80:81], v[90:91], s[2:3]
	v_pk_mul_f32 v[44:45], v[168:169], v[44:45]
	v_mov_b32_e32 v47, v83
	v_mul_f32_e32 v39, v99, v37
	v_mov_b32_e32 v45, v49
	v_fmac_f32_e32 v42, v40, v39
	v_pk_mul_f32 v[36:37], v[36:37], s[20:21] op_sel_hi:[1,0]
	v_xor_b32_e32 v39, 0x80000000, v44
	v_pk_mul_f32 v[44:45], v[44:45], v[46:47]
	v_cvt_pk_bf16_f32 v36, v36, v37
	v_mul_f32_e32 v37, v100, v45
	v_fmac_f32_e32 v42, v41, v37
	v_pk_mul_f32 v[40:41], v[44:45], s[20:21] op_sel_hi:[1,0]
	v_pk_add_f32 v[92:93], v[94:95], 0 neg_lo:[1,1] neg_hi:[1,1]
	v_xor_b32_e32 v85, 0x80000000, v76
	v_cvt_pk_bf16_f32 v37, v40, v41
	ds_write_b128 v43, v[34:37] offset:33344
	v_cvt_pk_bf16_f32 v36, v92, v85
	v_cvt_pk_bf16_f32 v37, v38, v39
	v_add_u32_e32 v34, v62, v63
	ds_write_b64 v34, v[36:37] offset:33568
	v_cvt_pk_bf16_f32 v36, v97, v98
	v_cvt_pk_bf16_f32 v37, v99, v100
	ds_write_b64 v34, v[36:37] offset:33696
	v_mfma_f32_16x16x32_bf16 v[26:29], v[26:29], v[22:25], v[30:33]
	s_nop 2
	ds_read_b128 v[30:33], v52 offset:128
	ds_read_b128 v[36:39], v53 offset:128
	v_cndmask_b32_e64 v40, v68, 0, vcc
	v_cndmask_b32_e64 v44, v70, 0, s[48:49]
	v_lshlrev_b32_e32 v80, 16, v66
	v_lshlrev_b32_e32 v46, 16, v40
	v_lshlrev_b32_e32 v45, 16, v44
	v_sub_f32_e32 v46, v46, v80
	v_sub_f32_e32 v45, v45, v80
	s_waitcnt lgkmcnt(1)
	v_fmac_f32_e32 v80, v30, v46
	s_waitcnt lgkmcnt(0)
	v_fmac_f32_e32 v80, v36, v45
	v_and_b32_e32 v81, 0xffff0000, v66
	v_and_b32_e32 v36, 0xffff0000, v40
	v_cndmask_b32_e64 v35, v69, 0, vcc
	v_and_b32_e32 v30, 0xffff0000, v44
	v_sub_f32_e32 v36, v36, v81
	v_cndmask_b32_e64 v41, v71, 0, s[48:49]
	v_sub_f32_e32 v30, v30, v81
	v_fmac_f32_e32 v81, v31, v36
	v_lshlrev_b32_e32 v82, 16, v67
	v_lshlrev_b32_e32 v31, 16, v35
	v_fmac_f32_e32 v81, v37, v30
	v_lshlrev_b32_e32 v30, 16, v41
	v_sub_f32_e32 v31, v31, v82
	v_sub_f32_e32 v30, v30, v82
	v_fmac_f32_e32 v82, v32, v31
	v_and_b32_e32 v83, 0xffff0000, v67
	v_and_b32_e32 v31, 0xffff0000, v35
	v_fmac_f32_e32 v82, v38, v30
	v_and_b32_e32 v30, 0xffff0000, v41
	v_sub_f32_e32 v31, v31, v83
	v_sub_f32_e32 v30, v30, v83
	v_fmac_f32_e32 v83, v33, v31
	v_fmac_f32_e32 v83, v39, v30
	ds_read_b128 v[36:39], v96 offset:128
	ds_read_b128 v[44:47], v2 offset:128
	ds_read_b128 v[66:69], v50 offset:128
	ds_read_b128 v[30:33], v51 offset:128
	v_mov_b32_e32 v40, v74
	s_waitcnt lgkmcnt(3)
	v_add_f32_e32 v27, v27, v37
	v_mul_f32_e32 v27, 0xbfb8aa3b, v27
	v_exp_f32_e32 v27, v27
	v_add_f32_e32 v26, v26, v36
	v_mul_f32_e32 v26, 0xbfb8aa3b, v26
	v_exp_f32_e32 v26, v26
	v_add_f32_e32 v27, 1.0, v27
	v_rcp_f32_e32 v36, v27
	v_add_f32_e32 v27, v28, v38
	v_mul_f32_e32 v27, 0xbfb8aa3b, v27
	v_exp_f32_e32 v27, v27
	v_add_f32_e32 v26, 1.0, v26
	v_rcp_f32_e32 v26, v26
	v_add_f32_e32 v49, -1.0, v36
	v_add_f32_e32 v27, 1.0, v27
	v_rcp_f32_e32 v28, v27
	v_add_f32_e32 v27, v29, v39
	v_mul_f32_e32 v27, 0xbfb8aa3b, v27
	v_exp_f32_e32 v27, v27
	v_add_f32_e32 v41, -1.0, v26
	s_waitcnt lgkmcnt(2)
	v_mov_b32_e32 v76, v44
	s_waitcnt lgkmcnt(1)
	v_mov_b32_e32 v77, v66
	v_pk_mul_f32 v[78:79], v[74:75], v[44:45]
	v_mov_b32_e32 v48, v75
	v_mov_b32_e32 v66, v45
	v_add_f32_e32 v27, 1.0, v27
	v_pk_mul_f32 v[78:79], v[168:169], v[78:79]
	v_pk_fma_f32 v[40:41], v[40:41], v[76:77], s[2:3]
	v_pk_mul_f32 v[44:45], v[48:49], v[66:67]
	v_rcp_f32_e32 v38, v27
	v_mov_b32_e32 v79, v41
	v_mov_b32_e32 v27, v74
	v_pk_mul_f32 v[44:45], v[168:169], v[44:45]
	v_pk_fma_f32 v[48:49], v[48:49], v[66:67], s[2:3]
	v_pk_mul_f32 v[26:27], v[78:79], v[26:27]
	v_mov_b32_e32 v45, v49
	v_mov_b32_e32 v37, v75
	v_pk_mul_f32 v[36:37], v[44:45], v[36:37]
	v_mul_f32_e32 v29, v80, v27
	v_pk_mul_f32 v[26:27], v[26:27], s[20:21] op_sel_hi:[1,0]
	s_waitcnt lgkmcnt(0)
; #define LAS __attribute__((address_space(3)))
; __device__ __forceinline__ unsigned cvtpk(float lo, float hi) { const f32x2 v = {lo, hi}; const bf16x2_t b = __builtin_convertvector(v, bf16x2_t); return __builtin_bit_cast(unsigned, b); }
; __device__ __forceinline__ float sigm(float x) { return __builtin_amdgcn_rcpf(1.0f + __expf(-x)); }
; #define MFMA16(a, b, c) __builtin_amdgcn_mfma_f32_16x16x32_bf16((a), (b), (c), 0, 0, 0)
; #define ZERO_ENDS2(A) do { if (!pz) A[1] = (u32x2){0u, 0u}; if (!nz) A[2] = (u32x2){0u, 0u}; } while (0)
; __device__ __forceinline__ void prep_y(int l, int b, int h, int dir, int c, LAS float* rg, const LAS float* cst, int lane) {
;     ...
;     for (int nb = 0; nb < 4; ++nb) {
;         f32x4 aI = {0.f, 0.f, 0.f, 0.f};
; #pragma unroll
;         for (int ks = 0; ks < 2; ++ks) aI = MFMA16(__builtin_bit_cast(bf16x8, wir[nb][ks]), bi[ks], aI);
;         const int co = nb * 16 + 4 * fq;
;         float rr[4];
;         ZERO_ENDS2(rr_[nb]);
;         mix4p(rr_[nb][0], rr_[nb][1], rr_[nb][2], cst + C_RMP + co, cst + C_RMN + co, rr);
;         const f32x4 ibias = *(const LAS f32x4*)(cst + C_IB + 64 * dir + co);
;         const f32x4 kkw = *(const LAS f32x4*)(cst + C_KK + co), kaw = *(const LAS f32x4*)(cst + C_KA + co), rkw = *(const LAS f32x4*)(cst + C_RK + co);
;         f32x4 va, vb, vkd, vr;
; #pragma unroll
;         for (int i = 0; i < 4; ++i) {
;             const float al = sigm(ibias[i] + aI[i]);
;             const float kraw = kk[4 * nb + i];
;             const float kn = kraw * kkw[i] * nrm;
;             const float kd = kraw * (1.0f + (al - 1.0f) * kaw[i]);
;             va[i] = -kn; vb[i] = kn * al; vkd[i] = kd; vr[i] = rr[i];
;             cs += rr[i] * kd * rkw[i];
;         }
;         *(LAS u32x4*)(rs_ + 128 + co) = (u32x4){cvtpk(0.25f * vb[0], 0.25f * vkd[0]), cvtpk(0.25f * vb[1], 0.25f * vkd[1]), cvtpk(0.25f * vb[2], 0.25f * vkd[2]), cvtpk(0.25f * vb[3], 0.25f * vkd[3])};
;         *(LAS u32x2*)(rs_ + 192 + (co >> 1)) = (u32x2){cvtpk(va[0], va[1]), cvtpk(va[2], va[3])};
;         *(LAS u32x2*)(rs_ + 224 + (co >> 1)) = (u32x2){cvtpk(vr[0], vr[1]), cvtpk(vr[2], vr[3])};
;     }
;     cs += __shfl_xor(cs, 16); cs += __shfl_xor(cs, 32);
;     if (fq == 0) ((float*)(ws + OFF_COEF))[((size_t)dir * T + row) * 16 + h] = cs;
	v_fmac_f32_e32 v42, v30, v29
	v_cvt_pk_bf16_f32 v26, v26, v27
	v_mul_f32_e32 v27, v81, v37
	v_fmac_f32_e32 v42, v31, v27
	v_pk_mul_f32 v[30:31], v[36:37], s[20:21] op_sel_hi:[1,0]
	v_add_f32_e32 v63, -1.0, v28
	v_cvt_pk_bf16_f32 v27, v30, v31
	v_mov_b32_e32 v62, v72
	v_mov_b32_e32 v30, v46
	v_mov_b32_e32 v31, v68
	v_pk_mul_f32 v[36:37], v[72:73], v[46:47]
	v_pk_fma_f32 v[30:31], v[62:63], v[30:31], s[2:3]
	v_pk_mul_f32 v[36:37], v[168:169], v[36:37]
	v_add_f32_e32 v71, -1.0, v38
	v_mov_b32_e32 v37, v31
	v_mov_b32_e32 v29, v72
	v_mov_b32_e32 v70, v73
	v_mov_b32_e32 v68, v47
	v_pk_add_f32 v[30:31], v[36:37], 0 neg_lo:[1,1] neg_hi:[1,1]
	v_pk_mul_f32 v[28:29], v[36:37], v[28:29]
	v_pk_mul_f32 v[36:37], v[70:71], v[68:69]
	v_xor_b32_e32 v35, 0x80000000, v44
	v_pk_mul_f32 v[36:37], v[168:169], v[36:37]
	v_pk_fma_f32 v[44:45], v[70:71], v[68:69], s[2:3]
	v_mov_b32_e32 v39, v73
	v_mul_f32_e32 v31, v82, v29
	v_mov_b32_e32 v37, v45
	v_fmac_f32_e32 v42, v32, v31
	v_pk_mul_f32 v[28:29], v[28:29], s[20:21] op_sel_hi:[1,0]
	v_xor_b32_e32 v31, 0x80000000, v36
	v_pk_mul_f32 v[36:37], v[36:37], v[38:39]
	v_cvt_pk_bf16_f32 v28, v28, v29
	v_mul_f32_e32 v29, v83, v37
	v_fmac_f32_e32 v42, v33, v29
	v_pk_mul_f32 v[32:33], v[36:37], s[20:21] op_sel_hi:[1,0]
	v_pk_add_f32 v[40:41], v[78:79], 0 neg_lo:[1,1] neg_hi:[1,1]
	v_cvt_pk_bf16_f32 v29, v32, v33
	v_mfma_f32_16x16x32_bf16 v[14:17], v[14:17], v[18:21], 0
	ds_write_b128 v43, v[26:29] offset:33408
	v_cvt_pk_bf16_f32 v26, v40, v35
	v_cvt_pk_bf16_f32 v27, v30, v31
	ds_write_b64 v34, v[26:27] offset:33600
	v_cvt_pk_bf16_f32 v26, v80, v81
	v_cvt_pk_bf16_f32 v27, v82, v83
	ds_write_b64 v34, v[26:27] offset:33728
	v_mfma_f32_16x16x32_bf16 v[10:13], v[10:13], v[22:25], v[14:17]
	s_nop 2
	ds_read_b128 v[14:17], v52 offset:192
	ds_read_b128 v[18:21], v53 offset:192
	v_cndmask_b32_e64 v23, v56, 0, vcc
	v_cndmask_b32_e64 v25, v58, 0, s[48:49]
	v_lshlrev_b32_e32 v35, 16, v54
	v_lshlrev_b32_e32 v27, 16, v23
	v_lshlrev_b32_e32 v26, 16, v25
	v_sub_f32_e32 v27, v27, v35
	v_sub_f32_e32 v26, v26, v35
	s_waitcnt lgkmcnt(1)
	v_fmac_f32_e32 v35, v14, v27
	s_waitcnt lgkmcnt(0)
	v_fmac_f32_e32 v35, v18, v26
	v_and_b32_e32 v46, 0xffff0000, v54
	v_and_b32_e32 v18, 0xffff0000, v23
	v_cndmask_b32_e64 v22, v57, 0, vcc
	v_and_b32_e32 v14, 0xffff0000, v25
	v_sub_f32_e32 v18, v18, v46
	v_cndmask_b32_e64 v24, v59, 0, s[48:49]
	v_sub_f32_e32 v14, v14, v46
	v_fmac_f32_e32 v46, v15, v18
	v_lshlrev_b32_e32 v47, 16, v55
	v_lshlrev_b32_e32 v15, 16, v22
	v_fmac_f32_e32 v46, v19, v14
	v_lshlrev_b32_e32 v14, 16, v24
	v_sub_f32_e32 v15, v15, v47
	v_sub_f32_e32 v14, v14, v47
	v_fmac_f32_e32 v47, v16, v15
	v_and_b32_e32 v48, 0xffff0000, v55
	v_and_b32_e32 v15, 0xffff0000, v22
	v_fmac_f32_e32 v47, v20, v14
	v_and_b32_e32 v14, 0xffff0000, v24
	v_sub_f32_e32 v15, v15, v48
	v_sub_f32_e32 v14, v14, v48
	v_fmac_f32_e32 v48, v17, v15
	v_fmac_f32_e32 v48, v21, v14
	ds_read_b128 v[18:21], v96 offset:192
	ds_read_b128 v[22:25], v2 offset:192
	ds_read_b128 v[26:29], v50 offset:192
	ds_read_b128 v[14:17], v51 offset:192
	v_mov_b32_e32 v30, v64
	s_waitcnt lgkmcnt(3)
	v_add_f32_e32 v2, v10, v18
	v_mul_f32_e32 v2, 0xbfb8aa3b, v2
	v_exp_f32_e32 v2, v2
	s_waitcnt lgkmcnt(2)
	v_mov_b32_e32 v40, v22
	s_waitcnt lgkmcnt(1)
	v_mov_b32_e32 v41, v26
	v_pk_mul_f32 v[44:45], v[64:65], v[22:23]
	v_add_f32_e32 v2, 1.0, v2
	v_rcp_f32_e32 v10, v2
	v_add_f32_e32 v2, v11, v19
	v_mul_f32_e32 v2, 0xbfb8aa3b, v2
	v_exp_f32_e32 v2, v2
	v_add_f32_e32 v31, -1.0, v10
	v_mov_b32_e32 v32, v65
	v_mov_b32_e32 v26, v23
	v_add_f32_e32 v2, 1.0, v2
	v_rcp_f32_e32 v18, v2
	v_add_f32_e32 v2, v12, v20
	v_mul_f32_e32 v2, 0xbfb8aa3b, v2
	v_exp_f32_e32 v2, v2
	v_add_f32_e32 v33, -1.0, v18
	v_pk_mul_f32 v[44:45], v[168:169], v[44:45]
	v_pk_fma_f32 v[30:31], v[30:31], v[40:41], s[2:3]
	v_add_f32_e32 v2, 1.0, v2
	v_rcp_f32_e32 v12, v2
	v_add_f32_e32 v2, v13, v21
	v_mul_f32_e32 v2, 0xbfb8aa3b, v2
	v_exp_f32_e32 v2, v2
	v_pk_mul_f32 v[22:23], v[32:33], v[26:27]
	v_mov_b32_e32 v45, v31
	v_mov_b32_e32 v11, v64
	v_pk_mul_f32 v[22:23], v[168:169], v[22:23]
	v_pk_fma_f32 v[26:27], v[32:33], v[26:27], s[2:3]
	v_add_f32_e32 v2, 1.0, v2
	v_pk_mul_f32 v[10:11], v[44:45], v[10:11]
	v_mov_b32_e32 v23, v27
	v_mov_b32_e32 v19, v65
	v_rcp_f32_e32 v20, v2
	v_mul_f32_e32 v2, v35, v11
	v_pk_mul_f32 v[10:11], v[10:11], s[20:21] op_sel_hi:[1,0]
	v_pk_mul_f32 v[18:19], v[22:23], v[18:19]
	s_waitcnt lgkmcnt(0)
	v_fmac_f32_e32 v42, v14, v2
	v_cvt_pk_bf16_f32 v10, v10, v11
	v_mul_f32_e32 v11, v46, v19
	v_fmac_f32_e32 v42, v15, v11
	v_pk_mul_f32 v[14:15], v[18:19], s[20:21] op_sel_hi:[1,0]
	v_add_f32_e32 v37, -1.0, v12
	v_cvt_pk_bf16_f32 v11, v14, v15
	v_mov_b32_e32 v36, v60
	v_mov_b32_e32 v14, v24
	v_mov_b32_e32 v15, v28
	v_pk_mul_f32 v[18:19], v[60:61], v[24:25]
	v_pk_fma_f32 v[14:15], v[36:37], v[14:15], s[2:3]
	v_pk_mul_f32 v[18:19], v[168:169], v[18:19]
	v_add_f32_e32 v39, -1.0, v20
	v_mov_b32_e32 v19, v15
	v_mov_b32_e32 v13, v60
	v_mov_b32_e32 v38, v61
	v_mov_b32_e32 v28, v25
	v_pk_add_f32 v[14:15], v[18:19], 0 neg_lo:[1,1] neg_hi:[1,1]
	v_pk_mul_f32 v[12:13], v[18:19], v[12:13]
	v_pk_mul_f32 v[18:19], v[38:39], v[28:29]
	v_xor_b32_e32 v2, 0x80000000, v22
	v_pk_mul_f32 v[18:19], v[168:169], v[18:19]
	v_pk_fma_f32 v[22:23], v[38:39], v[28:29], s[2:3]
	v_mov_b32_e32 v21, v61
	v_mul_f32_e32 v15, v47, v13
	v_mov_b32_e32 v19, v23
	v_fmac_f32_e32 v42, v16, v15
	v_pk_mul_f32 v[12:13], v[12:13], s[20:21] op_sel_hi:[1,0]
	v_xor_b32_e32 v15, 0x80000000, v18
	v_pk_mul_f32 v[18:19], v[18:19], v[20:21]
	v_cvt_pk_bf16_f32 v12, v12, v13
	v_mul_f32_e32 v13, v48, v19
	v_fmac_f32_e32 v42, v17, v13
	v_pk_mul_f32 v[16:17], v[18:19], s[20:21] op_sel_hi:[1,0]
	v_pk_add_f32 v[30:31], v[44:45], 0 neg_lo:[1,1] neg_hi:[1,1]
	v_cvt_pk_bf16_f32 v13, v16, v17
	ds_write_b128 v43, v[10:13] offset:33472
	v_cvt_pk_bf16_f32 v10, v30, v2
	ds_bpermute_b32 v2, v114, v42
	v_cvt_pk_bf16_f32 v11, v14, v15
	ds_write_b64 v34, v[10:11] offset:33632
	v_cvt_pk_bf16_f32 v10, v35, v46
	v_cvt_pk_bf16_f32 v11, v47, v48
	s_waitcnt lgkmcnt(1)
	v_add_f32_e32 v2, v42, v2
	ds_write_b64 v34, v[10:11] offset:33760
	ds_bpermute_b32 v10, v113, v2
	v_cmp_gt_u32_e32 vcc, 16, v112
	s_and_saveexec_b64 s[6:7], vcc
	s_cbranch_execz .LBB0_312
	v_readlane_b32 s28, v255, 56
	s_add_u32 s28, s36, s28
	s_addc_u32 s29, s37, 0
	v_lshlrev_b64 v[4:5], 6, v[4:5]
	v_lshl_add_u64 v[4:5], s[28:29], 0, v[4:5]
	s_lshl_b32 s96, s89, 2
	v_lshl_add_u64 v[4:5], v[4:5], 0, s[96:97]
	v_add_co_u32_e32 v4, vcc, 0xdd00000, v4
	s_waitcnt lgkmcnt(0)
	v_add_f32_e32 v2, v2, v10
	v_addc_co_u32_e32 v5, vcc, 0, v5, vcc
	global_store_dword v[4:5], v2, off

; __device__ __forceinline__ bf16x8 pack8(const float* f) { return __builtin_bit_cast(bf16x8, pack8u(f)); }
; #define ZERO_ENDS4(A) do { if (!pz) A[1] = (u32x4){0u, 0u, 0u, 0u}; if (!nz) A[2] = (u32x4){0u, 0u, 0u, 0u}; } while (0)
; __device__ __forceinline__ void prep_x(int l, int b, int h, int dir, int c, LAS float* rg, const LAS float* cst, int lane) {
;     ...
;     for (int ks = 0; ks < 2; ++ks) {
;         float o[8]; const int cc = 64 * dir + 32 * ks + 8 * fq;
;         ZERO_ENDS4(cdr[ks]);
;         mix8p(cdr[ks][0], cdr[ks][1], cdr[ks][2], cst + C_CMP + cc, cst + C_CMN + cc, o);
; #pragma unroll
;         for (int i = 0; i < 8; ++i) o[i] = 1.0f - 2.0f * __builtin_amdgcn_rcpf(1.0f + __expf(2.0f * o[i]));
;         bd[ks] = pack8(o);
.LBB0_337:
	v_add_u32_e32 v2, s8, v134
	v_lshl_add_u32 v2, v2, 2, 0
	s_waitcnt vmcnt(23)
	v_cndmask_b32_e64 v134, v84, 0, s[50:51]
	v_add_u32_e32 v148, 0x24800, v2
	v_cndmask_b32_e64 v79, v87, 0, s[50:51]
	v_cndmask_b32_e64 v132, v86, 0, s[50:51]
	v_cndmask_b32_e64 v133, v85, 0, s[50:51]
	s_waitcnt vmcnt(21)
	v_cndmask_b32_e64 v144, v83, 0, s[52:53]
	v_cndmask_b32_e64 v145, v82, 0, s[52:53]
	v_cndmask_b32_e64 v146, v81, 0, s[52:53]
	v_cndmask_b32_e64 v147, v80, 0, s[52:53]
	v_add_u32_e32 v2, 0x24c00, v2
	ds_read_b128 v[80:83], v148
	ds_read_b128 v[84:87], v148 offset:16
	ds_read_b128 v[136:139], v2
	ds_read_b128 v[140:143], v2 offset:16
	v_lshlrev_b32_e32 v150, 16, v38
	v_lshlrev_b32_e32 v151, 16, v134
	v_lshlrev_b32_e32 v149, 16, v147
	v_sub_f32_e32 v151, v151, v150
	v_and_b32_e32 v38, 0xffff0000, v38
	v_and_b32_e32 v134, 0xffff0000, v134
	v_sub_f32_e32 v149, v149, v150
	s_waitcnt lgkmcnt(3)
	v_fmac_f32_e32 v150, v80, v151
	v_and_b32_e32 v80, 0xffff0000, v147
	v_sub_f32_e32 v134, v134, v38
	v_sub_f32_e32 v80, v80, v38
	v_fmac_f32_e32 v38, v81, v134
	v_lshlrev_b32_e32 v81, 16, v39
	v_lshlrev_b32_e32 v134, 16, v133
	s_waitcnt lgkmcnt(1)
	v_fmac_f32_e32 v38, v137, v80
	v_lshlrev_b32_e32 v80, 16, v146
	v_sub_f32_e32 v134, v134, v81
	v_sub_f32_e32 v80, v80, v81
	v_fmac_f32_e32 v81, v82, v134
	v_and_b32_e32 v39, 0xffff0000, v39
	v_and_b32_e32 v82, 0xffff0000, v133
	v_fmac_f32_e32 v81, v138, v80
	v_and_b32_e32 v80, 0xffff0000, v146
	v_sub_f32_e32 v82, v82, v39
	v_sub_f32_e32 v80, v80, v39
	v_fmac_f32_e32 v39, v83, v82
	v_lshlrev_b32_e32 v82, 16, v40
	v_lshlrev_b32_e32 v83, 16, v132
	v_fmac_f32_e32 v39, v139, v80
	v_lshlrev_b32_e32 v80, 16, v145
	v_sub_f32_e32 v83, v83, v82
	v_sub_f32_e32 v80, v80, v82
	v_fmac_f32_e32 v82, v84, v83
	s_waitcnt lgkmcnt(0)
	v_fmac_f32_e32 v82, v140, v80
	v_and_b32_e32 v80, 0xffff0000, v40
	v_and_b32_e32 v83, 0xffff0000, v132
	v_and_b32_e32 v40, 0xffff0000, v145
	v_sub_f32_e32 v83, v83, v80
	v_sub_f32_e32 v40, v40, v80
	v_fmac_f32_e32 v80, v85, v83
	v_lshlrev_b32_e32 v83, 16, v41
	v_lshlrev_b32_e32 v84, 16, v79
	v_fmac_f32_e32 v80, v141, v40
	v_lshlrev_b32_e32 v40, 16, v144
	v_sub_f32_e32 v84, v84, v83
	v_sub_f32_e32 v40, v40, v83
	v_fmac_f32_e32 v83, v86, v84
	v_and_b32_e32 v84, 0xffff0000, v41
	v_and_b32_e32 v41, 0xffff0000, v79
	v_fmac_f32_e32 v150, v136, v149
	v_fmac_f32_e32 v83, v142, v40
	v_and_b32_e32 v40, 0xffff0000, v144
	v_sub_f32_e32 v41, v41, v84
	v_sub_f32_e32 v40, v40, v84
	v_fmac_f32_e32 v84, v87, v41
	v_fmac_f32_e32 v84, v143, v40
	v_mul_f32_e32 v40, 0x4038aa3b, v150
	v_mul_f32_e32 v38, 0x4038aa3b, v38
	v_exp_f32_e32 v40, v40
	v_exp_f32_e32 v41, v38
	v_add_f32_e32 v38, 1.0, v40
	v_add_f32_e32 v40, 1.0, v41
	v_mul_f32_e32 v41, 0x4038aa3b, v81
	v_mul_f32_e32 v39, 0x4038aa3b, v39
	v_exp_f32_e32 v41, v41
	v_exp_f32_e32 v79, v39
	v_rcp_f32_e32 v39, v40
	v_add_f32_e32 v40, 1.0, v41
	v_add_f32_e32 v41, 1.0, v79
	v_mul_f32_e32 v79, 0x4038aa3b, v82
	v_exp_f32_e32 v79, v79
	v_mul_f32_e32 v80, 0x4038aa3b, v80
	v_exp_f32_e32 v81, v80
	v_add_f32_e32 v79, 1.0, v79
	v_rcp_f32_e32 v80, v79
	v_add_f32_e32 v79, 1.0, v81
	v_mul_f32_e32 v81, 0x4038aa3b, v83
	v_exp_f32_e32 v82, v81
	v_mul_f32_e32 v81, 0x4038aa3b, v84
	v_exp_f32_e32 v83, v81
	v_rcp_f32_e32 v81, v79
	v_add_f32_e32 v79, 1.0, v82
	v_rcp_f32_e32 v82, v79
	v_add_f32_e32 v79, 1.0, v83
	v_rcp_f32_e32 v38, v38
	v_rcp_f32_e32 v40, v40
	v_rcp_f32_e32 v41, v41
	v_rcp_f32_e32 v83, v79
	v_pk_fma_f32 v[38:39], v[38:39], 2.0, 1.0 op_sel_hi:[1,0,0] neg_lo:[1,0,0] neg_hi:[1,0,0]
	v_pk_fma_f32 v[80:81], v[80:81], 2.0, 1.0 op_sel_hi:[1,0,0] neg_lo:[1,0,0] neg_hi:[1,0,0]
	v_pk_fma_f32 v[40:41], v[40:41], 2.0, 1.0 op_sel_hi:[1,0,0] neg_lo:[1,0,0] neg_hi:[1,0,0]
	v_pk_fma_f32 v[82:83], v[82:83], 2.0, 1.0 op_sel_hi:[1,0,0] neg_lo:[1,0,0] neg_hi:[1,0,0]
	v_cvt_pk_bf16_f32 v38, v38, v39
	v_cvt_pk_bf16_f32 v39, v40, v41
	v_cvt_pk_bf16_f32 v40, v80, v81
	v_cvt_pk_bf16_f32 v41, v82, v83
	v_cndmask_b32_e64 v79, v77, 0, s[50:51]
	v_cndmask_b32_e64 v132, v76, 0, s[50:51]
	v_cndmask_b32_e64 v133, v75, 0, s[50:51]
	v_cndmask_b32_e64 v134, v74, 0, s[50:51]
	s_waitcnt vmcnt(20)
; __device__ __forceinline__ bf16x8 pack8(const float* f) { return __builtin_bit_cast(bf16x8, pack8u(f)); }
; #define MFMA16(a, b, c) __builtin_amdgcn_mfma_f32_16x16x32_bf16((a), (b), (c), 0, 0, 0)
; #define ZERO_ENDS4(A) do { if (!pz) A[1] = (u32x4){0u, 0u, 0u, 0u}; if (!nz) A[2] = (u32x4){0u, 0u, 0u, 0u}; } while (0)
; __device__ __forceinline__ void prep_x(int l, int b, int h, int dir, int c, LAS float* rg, const LAS float* cst, int lane) {
;     ...
;     for (int ks = 0; ks < 2; ++ks) {
;         float o[8]; const int cc = 64 * dir + 32 * ks + 8 * fq;
;         ZERO_ENDS4(cdr[ks]);
;         mix8p(cdr[ks][0], cdr[ks][1], cdr[ks][2], cst + C_CMP + cc, cst + C_CMN + cc, o);
; #pragma unroll
;         for (int i = 0; i < 8; ++i) o[i] = 1.0f - 2.0f * __builtin_amdgcn_rcpf(1.0f + __expf(2.0f * o[i]));
;         bd[ks] = pack8(o);
;     }
;     const bf16x8 bv = __builtin_bit_cast(bf16x8, bvr);
; #pragma unroll
;     for (int nb = 0; nb < 4; ++nb) {
;         f32x4 aD = {0.f, 0.f, 0.f, 0.f}, aV = aD;
; #pragma unroll
;         for (int ks = 0; ks < 2; ++ks) aD = MFMA16(__builtin_bit_cast(bf16x8, wdr[nb][ks]), bd[ks], aD);
;         if (l > 0) aV = MFMA16(__builtin_bit_cast(bf16x8, wvr[nb]), bv, aV);
	v_cndmask_b32_e64 v136, v73, 0, s[52:53]
	v_cndmask_b32_e64 v137, v72, 0, s[52:53]
	v_cndmask_b32_e64 v138, v71, 0, s[52:53]
	v_cndmask_b32_e64 v139, v70, 0, s[52:53]
	ds_read_b128 v[70:73], v148 offset:128
	ds_read_b128 v[74:77], v148 offset:144
	ds_read_b128 v[80:83], v2 offset:128
	ds_read_b128 v[84:87], v2 offset:144
	v_lshlrev_b32_e32 v140, 16, v54
	v_lshlrev_b32_e32 v141, 16, v134
	v_lshlrev_b32_e32 v2, 16, v139
	v_sub_f32_e32 v141, v141, v140
	v_sub_f32_e32 v2, v2, v140
	s_waitcnt lgkmcnt(3)
	v_fmac_f32_e32 v140, v70, v141
	s_waitcnt lgkmcnt(1)
	v_fmac_f32_e32 v140, v80, v2
	v_and_b32_e32 v2, 0xffff0000, v54
	v_and_b32_e32 v70, 0xffff0000, v134
	v_and_b32_e32 v54, 0xffff0000, v139
	v_sub_f32_e32 v70, v70, v2
	v_sub_f32_e32 v54, v54, v2
	v_fmac_f32_e32 v2, v71, v70
	v_lshlrev_b32_e32 v70, 16, v55
	v_lshlrev_b32_e32 v71, 16, v133
	v_fmac_f32_e32 v2, v81, v54
	v_lshlrev_b32_e32 v54, 16, v138
	v_sub_f32_e32 v71, v71, v70
	v_sub_f32_e32 v54, v54, v70
	v_fmac_f32_e32 v70, v72, v71
	v_and_b32_e32 v55, 0xffff0000, v55
	v_and_b32_e32 v71, 0xffff0000, v133
	v_fmac_f32_e32 v70, v82, v54
	v_and_b32_e32 v54, 0xffff0000, v138
	v_sub_f32_e32 v71, v71, v55
	v_sub_f32_e32 v54, v54, v55
	v_fmac_f32_e32 v55, v73, v71
	v_lshlrev_b32_e32 v71, 16, v56
	v_lshlrev_b32_e32 v72, 16, v132
	v_fmac_f32_e32 v55, v83, v54
	v_lshlrev_b32_e32 v54, 16, v137
	v_sub_f32_e32 v72, v72, v71
	v_sub_f32_e32 v54, v54, v71
	v_fmac_f32_e32 v71, v74, v72
	v_and_b32_e32 v72, 0xffff0000, v56
	v_and_b32_e32 v56, 0xffff0000, v132
	s_waitcnt lgkmcnt(0)
	v_fmac_f32_e32 v71, v84, v54
	v_and_b32_e32 v54, 0xffff0000, v137
	v_sub_f32_e32 v56, v56, v72
	v_sub_f32_e32 v54, v54, v72
	v_fmac_f32_e32 v72, v75, v56
	v_lshlrev_b32_e32 v73, 16, v57
	v_lshlrev_b32_e32 v56, 16, v79
	v_fmac_f32_e32 v72, v85, v54
	v_lshlrev_b32_e32 v54, 16, v136
	v_sub_f32_e32 v56, v56, v73
	v_sub_f32_e32 v54, v54, v73
	v_fmac_f32_e32 v73, v76, v56
	v_and_b32_e32 v74, 0xffff0000, v57
	v_and_b32_e32 v56, 0xffff0000, v79
	v_fmac_f32_e32 v73, v86, v54
	v_and_b32_e32 v54, 0xffff0000, v136
	v_sub_f32_e32 v56, v56, v74
	v_sub_f32_e32 v54, v54, v74
	v_fmac_f32_e32 v74, v77, v56
	v_mul_f32_e32 v2, 0x4038aa3b, v2
	v_exp_f32_e32 v2, v2
	v_mul_f32_e32 v56, 0x4038aa3b, v70
	v_exp_f32_e32 v56, v56
	v_mul_f32_e32 v55, 0x4038aa3b, v55
	v_exp_f32_e32 v57, v55
	v_add_f32_e32 v2, 1.0, v2
	v_rcp_f32_e32 v55, v2
	v_add_f32_e32 v2, 1.0, v56
	v_rcp_f32_e32 v56, v2
	v_add_f32_e32 v2, 1.0, v57
	v_mul_f32_e32 v57, 0x4038aa3b, v71
	v_exp_f32_e32 v70, v57
	v_mul_f32_e32 v57, 0x4038aa3b, v72
	v_exp_f32_e32 v71, v57
	v_fmac_f32_e32 v74, v87, v54
	v_rcp_f32_e32 v57, v2
	v_add_f32_e32 v2, 1.0, v70
	v_rcp_f32_e32 v70, v2
	v_add_f32_e32 v2, 1.0, v71
	v_mul_f32_e32 v71, 0x4038aa3b, v73
	v_exp_f32_e32 v72, v71
	v_mul_f32_e32 v54, 0x4038aa3b, v140
	v_mul_f32_e32 v71, 0x4038aa3b, v74
	v_exp_f32_e32 v54, v54
	v_exp_f32_e32 v73, v71
	v_rcp_f32_e32 v71, v2
	v_add_f32_e32 v2, 1.0, v72
	v_add_f32_e32 v54, 1.0, v54
	v_rcp_f32_e32 v72, v2
	v_add_f32_e32 v2, 1.0, v73
	v_rcp_f32_e32 v54, v54
	v_rcp_f32_e32 v73, v2
	s_waitcnt vmcnt(19)
	v_mfma_f32_16x16x32_bf16 v[66:69], v[66:69], v[38:41], 0
	v_fma_f32 v56, -v56, 2.0, 1.0
	v_fma_f32 v57, -v57, 2.0, 1.0
	v_pk_fma_f32 v[54:55], v[54:55], 2.0, 1.0 op_sel_hi:[1,0,0] neg_lo:[1,0,0] neg_hi:[1,0,0]
	v_pk_fma_f32 v[70:71], v[70:71], 2.0, 1.0 op_sel_hi:[1,0,0] neg_lo:[1,0,0] neg_hi:[1,0,0]
	v_pk_fma_f32 v[72:73], v[72:73], 2.0, 1.0 op_sel_hi:[1,0,0] neg_lo:[1,0,0] neg_hi:[1,0,0]
	v_cvt_pk_bf16_f32 v54, v54, v55
	v_cvt_pk_bf16_f32 v55, v56, v57
	v_cvt_pk_bf16_f32 v56, v70, v71
	v_cvt_pk_bf16_f32 v57, v72, v73
	s_and_b64 vcc, exec, s[48:49]
	v_mov_b32_e32 v79, 0
	s_waitcnt vmcnt(18)
	v_mfma_f32_16x16x32_bf16 v[62:65], v[62:65], v[54:57], v[66:69]
	v_mov_b32_e32 v80, 0
	v_mov_b32_e32 v81, 0
	s_cbranch_vccnz .LBB0_339
	v_mfma_f32_16x16x32_bf16 v[78:81], v[58:61], v[10:13], 0

; __device__ __forceinline__ void yflush_issue(unsigned (&yo)[4], const bf16* yb2  , int dir, int cc, int lane) {
;     const int rg = lane >> 4;
;     if (cc >= NCH / 2) {
; #pragma unroll
;         for (int i = 0; i < 4; ++i) yo[i] = *(const unsigned*)(yb2 + (size_t)Y_T(dir, cc, 4 * i + rg) * DM);
;     } else {
; #pragma unroll
;         for (int i = 0; i < 4; ++i) yo[i] = 0u;
;     }
; }
; __device__ __forceinline__ void scan_phase(int l, LAS unsigned char* lds, int wave, int lane) {
;     ...
;                 unsigned yo[4];
;                 if (c > 0) yflush_issue(yo, yb2, dirw, c - 1, lane);
.LBB0_364:
	s_mov_b64 s[6:7], -1
	s_and_b64 vcc, exec, s[92:93]
	s_cbranch_vccz .LBB0_427
	s_setprio 1
	s_cmp_lg_u32 s81, 0
	v_mov_b64_e32 v[38:39], v[8:9]
	s_cselect_b64 s[78:79], -1, 0
	s_cmp_eq_u32 s81, 0
	v_mov_b64_e32 v[36:37], v[6:7]
	s_cbranch_scc1 .LBB0_370
	s_cmp_lg_u32 s81, 1
	s_cbranch_scc1 .Lpf_init_done
	v_and_b32_e32 v212, 63, v0
	v_lshrrev_b32_e32 v213, 6, v0
	s_nop 0
	v_readfirstlane_b32 s6, v213
	s_sub_i32 s6, s6, 4
	s_lshr_b32 s7, s6, 1
	s_lshr_b32 vcc_lo, s57, 4
	s_lshl_b32 vcc_lo, vcc_lo, 22
	s_add_u32 s98, s100, vcc_lo
	s_addc_u32 s99, s101, 0
	s_and_b32 vcc_lo, s57, 15
	s_lshl_b32 vcc_lo, vcc_lo, 7
	s_lshl_b32 s7, s7, 6
	s_add_i32 vcc_lo, vcc_lo, s7
	s_add_i32 vcc_lo, vcc_lo, 0x9d00000
	s_add_u32 s98, s98, vcc_lo
	s_addc_u32 s99, s99, 0
	s_and_b32 s100, s6, 1
	s_cmp_eq_u32 s100, 0
	s_cselect_b32 s7, 1, -1
	s_lshl_b32 s101, s7, 13
	v_and_b32_e32 v213, 15, v212
	v_lshrrev_b32_e32 v214, 4, v212
	v_mul_i32_i24_e32 v217, s7, v214
	v_lshlrev_b32_e32 v218, 2, v213
	s_lshl_b32 s6, s6, 12
	s_add_i32 s6, s6, 0x20800
	v_lshl_add_u32 v127, v214, 7, s6
	v_lshl_add_u32 v216, v213, 3, v127
.Lpf_init_done:
	s_add_i32 vcc_lo, s81, -1
	s_and_b32 vcc_hi, vcc_lo, 1
	s_lshl_b32 vcc_hi, vcc_hi, 11
	v_add_u32_e32 v215, vcc_hi, v216
	s_lshl_b32 s6, vcc_lo, 4
	s_sub_i32 vcc_hi, 0x7ff, s6
	s_cmp_eq_u32 s100, 0
	s_cselect_b32 s6, s6, vcc_hi
	v_add_u32_e32 v127, s6, v217
	v_lshlrev_b32_e32 v127, 11, v127
	v_add_u32_e32 v30, v127, v218
	v_add_u32_e32 v31, s101, v30
	v_add_u32_e32 v34, s101, v31
	v_add_u32_e32 v35, s101, v34
	s_cmp_lt_u32 vcc_lo, 64
	s_cbranch_scc1 .Lpf_noload
	global_load_dword v24, v30, s[98:99]
	global_load_dword v25, v31, s[98:99]
	global_load_dword v28, v34, s[98:99]
	global_load_dword v29, v35, s[98:99]
	s_branch .LBB0_370
.Lpf_noload:
	v_mov_b32_e32 v24, 0
	v_mov_b32_e32 v25, 0
	v_mov_b32_e32 v28, 0
	v_mov_b32_e32 v29, 0

; __device__ __forceinline__ bf16x8 pack8(const float* f) { return __builtin_bit_cast(bf16x8, pack8u(f)); }
; #define ZERO_ENDS4(A) do { if (!pz) A[1] = (u32x4){0u, 0u, 0u, 0u}; if (!nz) A[2] = (u32x4){0u, 0u, 0u, 0u}; } while (0)
; __device__ __forceinline__ void prep_x(int l, int b, int h, int dir, int c, LAS float* rg, const LAS float* cst, int lane) {
;     ...
;     for (int ks = 0; ks < 2; ++ks) {
;         float o[8]; const int cc = 64 * dir + 32 * ks + 8 * fq;
;         ZERO_ENDS4(cdr[ks]);
;         mix8p(cdr[ks][0], cdr[ks][1], cdr[ks][2], cst + C_CMP + cc, cst + C_CMN + cc, o);
; #pragma unroll
;         for (int i = 0; i < 8; ++i) o[i] = 1.0f - 2.0f * __builtin_amdgcn_rcpf(1.0f + __expf(2.0f * o[i]));
;         bd[ks] = pack8(o);
.LBB0_399:
	v_add_u32_e32 v2, s8, v156
	v_lshl_add_u32 v2, v2, 2, 0
	s_waitcnt vmcnt(23)
	v_cndmask_b32_e64 v156, v114, 0, s[50:51]
	v_add_u32_e32 v219, 0x24800, v2
	v_cndmask_b32_e64 v109, v117, 0, s[50:51]
	v_cndmask_b32_e64 v154, v116, 0, s[50:51]
	v_cndmask_b32_e64 v155, v115, 0, s[50:51]
	s_waitcnt vmcnt(21)
	v_cndmask_b32_e64 v158, 0, v113, s[52:53]
	v_cndmask_b32_e64 v159, 0, v112, s[52:53]
	v_cndmask_b32_e64 v170, 0, v111, s[52:53]
	v_cndmask_b32_e64 v171, 0, v110, s[52:53]
	v_add_u32_e32 v2, 0x24c00, v2
	ds_read_b128 v[110:113], v219
	ds_read_b128 v[114:117], v219 offset:16
	ds_read_b128 v[224:227], v2
	ds_read_b128 v[228:231], v2 offset:16
	v_lshlrev_b32_e32 v233, 16, v68
	v_lshlrev_b32_e32 v234, 16, v156
	v_lshlrev_b32_e32 v232, 16, v171
	v_sub_f32_e32 v234, v234, v233
	v_and_b32_e32 v68, 0xffff0000, v68
	v_and_b32_e32 v156, 0xffff0000, v156
	v_sub_f32_e32 v232, v232, v233
	s_waitcnt lgkmcnt(3)
	v_fmac_f32_e32 v233, v110, v234
	v_and_b32_e32 v110, 0xffff0000, v171
	v_sub_f32_e32 v156, v156, v68
	v_sub_f32_e32 v110, v110, v68
	v_fmac_f32_e32 v68, v111, v156
	v_lshlrev_b32_e32 v111, 16, v69
	v_lshlrev_b32_e32 v156, 16, v155
	s_waitcnt lgkmcnt(1)
	v_fmac_f32_e32 v68, v225, v110
	v_lshlrev_b32_e32 v110, 16, v170
	v_sub_f32_e32 v156, v156, v111
	v_sub_f32_e32 v110, v110, v111
	v_fmac_f32_e32 v111, v112, v156
	v_and_b32_e32 v69, 0xffff0000, v69
	v_and_b32_e32 v112, 0xffff0000, v155
	v_fmac_f32_e32 v111, v226, v110
	v_and_b32_e32 v110, 0xffff0000, v170
	v_sub_f32_e32 v112, v112, v69
	v_sub_f32_e32 v110, v110, v69
	v_fmac_f32_e32 v69, v113, v112
	v_lshlrev_b32_e32 v112, 16, v70
	v_lshlrev_b32_e32 v113, 16, v154
	v_fmac_f32_e32 v69, v227, v110
	v_lshlrev_b32_e32 v110, 16, v159
	v_sub_f32_e32 v113, v113, v112
	v_sub_f32_e32 v110, v110, v112
	v_fmac_f32_e32 v112, v114, v113
	s_waitcnt lgkmcnt(0)
	v_fmac_f32_e32 v112, v228, v110
	v_and_b32_e32 v110, 0xffff0000, v70
	v_and_b32_e32 v113, 0xffff0000, v154
	v_and_b32_e32 v70, 0xffff0000, v159
	v_sub_f32_e32 v113, v113, v110
	v_sub_f32_e32 v70, v70, v110
	v_fmac_f32_e32 v110, v115, v113
	v_lshlrev_b32_e32 v113, 16, v71
	v_lshlrev_b32_e32 v114, 16, v109
	v_fmac_f32_e32 v110, v229, v70
	v_lshlrev_b32_e32 v70, 16, v158
	v_sub_f32_e32 v114, v114, v113
	v_sub_f32_e32 v70, v70, v113
	v_fmac_f32_e32 v113, v116, v114
	v_and_b32_e32 v114, 0xffff0000, v71
	v_and_b32_e32 v71, 0xffff0000, v109
	v_fmac_f32_e32 v233, v224, v232
	v_fmac_f32_e32 v113, v230, v70
	v_and_b32_e32 v70, 0xffff0000, v158
	v_sub_f32_e32 v71, v71, v114
	v_sub_f32_e32 v70, v70, v114
	v_fmac_f32_e32 v114, v117, v71
	v_fmac_f32_e32 v114, v231, v70
	v_mul_f32_e32 v70, 0x4038aa3b, v233
	v_mul_f32_e32 v68, 0x4038aa3b, v68
	v_exp_f32_e32 v70, v70
	v_exp_f32_e32 v71, v68
	v_add_f32_e32 v68, 1.0, v70
	v_add_f32_e32 v70, 1.0, v71
	v_mul_f32_e32 v71, 0x4038aa3b, v111
	v_mul_f32_e32 v69, 0x4038aa3b, v69
	v_exp_f32_e32 v71, v71
	v_exp_f32_e32 v109, v69
	v_rcp_f32_e32 v69, v70
	v_add_f32_e32 v70, 1.0, v71
	v_add_f32_e32 v71, 1.0, v109
	v_mul_f32_e32 v109, 0x4038aa3b, v112
	v_exp_f32_e32 v109, v109
	v_mul_f32_e32 v110, 0x4038aa3b, v110
	v_exp_f32_e32 v111, v110
	v_add_f32_e32 v109, 1.0, v109
	v_rcp_f32_e32 v110, v109
	v_add_f32_e32 v109, 1.0, v111
	v_mul_f32_e32 v111, 0x4038aa3b, v113
	v_exp_f32_e32 v112, v111
	v_mul_f32_e32 v111, 0x4038aa3b, v114
	v_exp_f32_e32 v113, v111
	v_rcp_f32_e32 v111, v109
	v_add_f32_e32 v109, 1.0, v112
	v_rcp_f32_e32 v112, v109
	v_add_f32_e32 v109, 1.0, v113
	v_rcp_f32_e32 v68, v68
	v_rcp_f32_e32 v70, v70
	v_rcp_f32_e32 v71, v71
	v_rcp_f32_e32 v113, v109
	v_pk_fma_f32 v[68:69], v[68:69], 2.0, 1.0 op_sel_hi:[1,0,0] neg_lo:[1,0,0] neg_hi:[1,0,0]
	v_pk_fma_f32 v[110:111], v[110:111], 2.0, 1.0 op_sel_hi:[1,0,0] neg_lo:[1,0,0] neg_hi:[1,0,0]
	v_pk_fma_f32 v[70:71], v[70:71], 2.0, 1.0 op_sel_hi:[1,0,0] neg_lo:[1,0,0] neg_hi:[1,0,0]
	v_pk_fma_f32 v[112:113], v[112:113], 2.0, 1.0 op_sel_hi:[1,0,0] neg_lo:[1,0,0] neg_hi:[1,0,0]
	v_cvt_pk_bf16_f32 v68, v68, v69
	v_cvt_pk_bf16_f32 v69, v70, v71
	v_cvt_pk_bf16_f32 v70, v110, v111
	v_cvt_pk_bf16_f32 v71, v112, v113
	v_cndmask_b32_e64 v109, v107, 0, s[50:51]
	v_cndmask_b32_e64 v154, v106, 0, s[50:51]
	v_cndmask_b32_e64 v155, v105, 0, s[50:51]
	v_cndmask_b32_e64 v156, v104, 0, s[50:51]
	s_waitcnt vmcnt(20)
; __device__ __forceinline__ bf16x8 pack8(const float* f) { return __builtin_bit_cast(bf16x8, pack8u(f)); }
; #define MFMA16(a, b, c) __builtin_amdgcn_mfma_f32_16x16x32_bf16((a), (b), (c), 0, 0, 0)
; #define ZERO_ENDS4(A) do { if (!pz) A[1] = (u32x4){0u, 0u, 0u, 0u}; if (!nz) A[2] = (u32x4){0u, 0u, 0u, 0u}; } while (0)
; __device__ __forceinline__ void prep_x(int l, int b, int h, int dir, int c, LAS float* rg, const LAS float* cst, int lane) {
;     ...
;     for (int ks = 0; ks < 2; ++ks) {
;         float o[8]; const int cc = 64 * dir + 32 * ks + 8 * fq;
;         ZERO_ENDS4(cdr[ks]);
;         mix8p(cdr[ks][0], cdr[ks][1], cdr[ks][2], cst + C_CMP + cc, cst + C_CMN + cc, o);
; #pragma unroll
;         for (int i = 0; i < 8; ++i) o[i] = 1.0f - 2.0f * __builtin_amdgcn_rcpf(1.0f + __expf(2.0f * o[i]));
;         bd[ks] = pack8(o);
;     }
;     const bf16x8 bv = __builtin_bit_cast(bf16x8, bvr);
; #pragma unroll
;     for (int nb = 0; nb < 4; ++nb) {
;         f32x4 aD = {0.f, 0.f, 0.f, 0.f}, aV = aD;
; #pragma unroll
;         for (int ks = 0; ks < 2; ++ks) aD = MFMA16(__builtin_bit_cast(bf16x8, wdr[nb][ks]), bd[ks], aD);
;         if (l > 0) aV = MFMA16(__builtin_bit_cast(bf16x8, wvr[nb]), bv, aV);
	v_cndmask_b32_e64 v158, 0, v103, s[52:53]
	v_cndmask_b32_e64 v159, 0, v102, s[52:53]
	v_cndmask_b32_e64 v170, 0, v101, s[52:53]
	v_cndmask_b32_e64 v171, 0, v100, s[52:53]
	ds_read_b128 v[100:103], v219 offset:128
	ds_read_b128 v[104:107], v219 offset:144
	ds_read_b128 v[110:113], v2 offset:128
	ds_read_b128 v[114:117], v2 offset:144
	v_lshlrev_b32_e32 v219, 16, v84
	v_lshlrev_b32_e32 v224, 16, v156
	v_lshlrev_b32_e32 v2, 16, v171
	v_sub_f32_e32 v224, v224, v219
	v_sub_f32_e32 v2, v2, v219
	s_waitcnt lgkmcnt(3)
	v_fmac_f32_e32 v219, v100, v224
	s_waitcnt lgkmcnt(1)
	v_fmac_f32_e32 v219, v110, v2
	v_and_b32_e32 v2, 0xffff0000, v84
	v_and_b32_e32 v100, 0xffff0000, v156
	v_and_b32_e32 v84, 0xffff0000, v171
	v_sub_f32_e32 v100, v100, v2
	v_sub_f32_e32 v84, v84, v2
	v_fmac_f32_e32 v2, v101, v100
	v_lshlrev_b32_e32 v100, 16, v85
	v_lshlrev_b32_e32 v101, 16, v155
	v_fmac_f32_e32 v2, v111, v84
	v_lshlrev_b32_e32 v84, 16, v170
	v_sub_f32_e32 v101, v101, v100
	v_sub_f32_e32 v84, v84, v100
	v_fmac_f32_e32 v100, v102, v101
	v_and_b32_e32 v85, 0xffff0000, v85
	v_and_b32_e32 v101, 0xffff0000, v155
	v_fmac_f32_e32 v100, v112, v84
	v_and_b32_e32 v84, 0xffff0000, v170
	v_sub_f32_e32 v101, v101, v85
	v_sub_f32_e32 v84, v84, v85
	v_fmac_f32_e32 v85, v103, v101
	v_lshlrev_b32_e32 v101, 16, v86
	v_lshlrev_b32_e32 v102, 16, v154
	v_fmac_f32_e32 v85, v113, v84
	v_lshlrev_b32_e32 v84, 16, v159
	v_sub_f32_e32 v102, v102, v101
	v_sub_f32_e32 v84, v84, v101
	v_fmac_f32_e32 v101, v104, v102
	v_and_b32_e32 v102, 0xffff0000, v86
	v_and_b32_e32 v86, 0xffff0000, v154
	s_waitcnt lgkmcnt(0)
	v_fmac_f32_e32 v101, v114, v84
	v_and_b32_e32 v84, 0xffff0000, v159
	v_sub_f32_e32 v86, v86, v102
	v_sub_f32_e32 v84, v84, v102
	v_fmac_f32_e32 v102, v105, v86
	v_lshlrev_b32_e32 v103, 16, v87
	v_lshlrev_b32_e32 v86, 16, v109
	v_fmac_f32_e32 v102, v115, v84
	v_lshlrev_b32_e32 v84, 16, v158
	v_sub_f32_e32 v86, v86, v103
	v_sub_f32_e32 v84, v84, v103
	v_fmac_f32_e32 v103, v106, v86
	v_and_b32_e32 v104, 0xffff0000, v87
	v_and_b32_e32 v86, 0xffff0000, v109
	v_fmac_f32_e32 v103, v116, v84
	v_and_b32_e32 v84, 0xffff0000, v158
	v_sub_f32_e32 v86, v86, v104
	v_sub_f32_e32 v84, v84, v104
	v_fmac_f32_e32 v104, v107, v86
	v_mul_f32_e32 v2, 0x4038aa3b, v2
	v_exp_f32_e32 v2, v2
	v_mul_f32_e32 v86, 0x4038aa3b, v100
	v_exp_f32_e32 v86, v86
	v_mul_f32_e32 v85, 0x4038aa3b, v85
	v_exp_f32_e32 v87, v85
	v_add_f32_e32 v2, 1.0, v2
	v_rcp_f32_e32 v85, v2
	v_add_f32_e32 v2, 1.0, v86
	v_rcp_f32_e32 v86, v2
	v_add_f32_e32 v2, 1.0, v87
	v_mul_f32_e32 v87, 0x4038aa3b, v101
	v_exp_f32_e32 v100, v87
	v_mul_f32_e32 v87, 0x4038aa3b, v102
	v_exp_f32_e32 v101, v87
	v_fmac_f32_e32 v104, v117, v84
	v_rcp_f32_e32 v87, v2
	v_add_f32_e32 v2, 1.0, v100
	v_rcp_f32_e32 v100, v2
	v_add_f32_e32 v2, 1.0, v101
	v_mul_f32_e32 v101, 0x4038aa3b, v103
	v_exp_f32_e32 v102, v101
	v_mul_f32_e32 v84, 0x4038aa3b, v219
	v_mul_f32_e32 v101, 0x4038aa3b, v104
	v_exp_f32_e32 v84, v84
	v_exp_f32_e32 v103, v101
	v_rcp_f32_e32 v101, v2
	v_add_f32_e32 v2, 1.0, v102
	v_add_f32_e32 v84, 1.0, v84
	v_rcp_f32_e32 v102, v2
	v_add_f32_e32 v2, 1.0, v103
	v_rcp_f32_e32 v84, v84
	v_rcp_f32_e32 v103, v2
	s_waitcnt vmcnt(19)
	v_mfma_f32_16x16x32_bf16 v[96:99], v[96:99], v[68:71], 0
	v_fma_f32 v86, -v86, 2.0, 1.0
	v_fma_f32 v87, -v87, 2.0, 1.0
	v_pk_fma_f32 v[84:85], v[84:85], 2.0, 1.0 op_sel_hi:[1,0,0] neg_lo:[1,0,0] neg_hi:[1,0,0]
	v_pk_fma_f32 v[100:101], v[100:101], 2.0, 1.0 op_sel_hi:[1,0,0] neg_lo:[1,0,0] neg_hi:[1,0,0]
	v_pk_fma_f32 v[102:103], v[102:103], 2.0, 1.0 op_sel_hi:[1,0,0] neg_lo:[1,0,0] neg_hi:[1,0,0]
	v_cvt_pk_bf16_f32 v84, v84, v85
	v_cvt_pk_bf16_f32 v85, v86, v87
	v_cvt_pk_bf16_f32 v86, v100, v101
	v_cvt_pk_bf16_f32 v87, v102, v103
	s_and_b64 vcc, exec, s[48:49]
	v_mov_b32_e32 v109, 0
	s_waitcnt vmcnt(18)
	v_mfma_f32_16x16x32_bf16 v[92:95], v[92:95], v[84:87], v[96:99]
	v_mov_b32_e32 v110, 0
	v_mov_b32_e32 v111, 0
	s_cbranch_vccnz .LBB0_401
	v_mfma_f32_16x16x32_bf16 v[108:111], v[88:91], v[40:43], 0

; #define LAS __attribute__((address_space(3)))
; __device__ __forceinline__ unsigned pk2(float lo, float hi) { return cvtpk(lo, hi); }
; __device__ __forceinline__ void yflush_finish(const unsigned (&yo)[4], bf16* yb2, const LAS float* ybuf  , int dir, int cc, int lane) {
;     const int rg = lane >> 4, cp = lane & 15;
; #pragma unroll
;     for (int i = 0; i < 4; ++i) { const int s = 4 * i + rg; const f32x2 yv = *(const LAS f32x2*)(ybuf + s * 32 + 2 * cp);
;         *(unsigned*)(yb2 + (size_t)Y_T(dir, cc, s) * DM) = pk2(yv.x + bflo(yo[i]), yv.y + bfhi(yo[i])); }
; }
; __device__ __forceinline__ void scan_phase(int l, LAS unsigned char* lds, int wave, int lane) {
;     ...
;                 if (c > 0) yflush_finish(yo, yb2, ybw + ((c - 1) & 1) * CHS * 32, dirw, c - 1, lane);
.LBB0_424:
	s_cmp_eq_u32 s81, 0
	s_cbranch_scc1 .LBB0_426
	ds_read_b64 v[12:13], v215 offset:0
	ds_read_b64 v[16:17], v215 offset:512
	ds_read_b64 v[18:19], v215 offset:1024
	ds_read_b64 v[22:23], v215 offset:1536
	s_waitcnt vmcnt(0)
	v_lshlrev_b32_e32 v208, 16, v24
	v_and_b32_e32 v24, 0xffff0000, v24
	s_waitcnt lgkmcnt(3)
	v_add_f32_e32 v12, v12, v208
	v_add_f32_e32 v13, v13, v24
	v_cvt_pk_bf16_f32 v208, v12, v13
	global_store_dword v30, v208, s[98:99]
	v_lshlrev_b32_e32 v209, 16, v25
	v_and_b32_e32 v25, 0xffff0000, v25
	s_waitcnt lgkmcnt(2)
	v_add_f32_e32 v16, v16, v209
	v_add_f32_e32 v17, v17, v25
	v_cvt_pk_bf16_f32 v209, v16, v17
	global_store_dword v31, v209, s[98:99]
	v_lshlrev_b32_e32 v210, 16, v28
	v_and_b32_e32 v28, 0xffff0000, v28
	s_waitcnt lgkmcnt(1)
	v_add_f32_e32 v18, v18, v210
	v_add_f32_e32 v19, v19, v28
	v_cvt_pk_bf16_f32 v210, v18, v19
	global_store_dword v34, v210, s[98:99]
	v_lshlrev_b32_e32 v211, 16, v29
	v_and_b32_e32 v29, 0xffff0000, v29
	s_waitcnt lgkmcnt(0)
	v_add_f32_e32 v22, v22, v211
	v_add_f32_e32 v23, v23, v29
	v_cvt_pk_bf16_f32 v211, v22, v23
	global_store_dword v35, v211, s[98:99]

; #define PG8_STAGE(bufoff, gbase, voff) do { _Pragma("unroll") for (int _i = 0; _i < 2; ++_i) \
;         __builtin_amdgcn_global_load_lds((const unsigned*)((const char*)(gbase) + (voff)[_i]), (PG8_LAS unsigned*)(lds + (bufoff) + ldsw + _i * 8192), 16, 0, 0); } while (0)
; #define PG8_LDA(dst, b, h) do { _Pragma("unroll") for (int m = 0; m < 4; ++m) _Pragma("unroll") for (int k = 0; k < 2; ++k) dst[m][k] = *(const PG8_LAS bf16x8*)(lds + PG8_SA(b, h) + aoff + m * 2048 + k * 1024); } while (0)
; #define PG8_LDB(dst, b, h) do { _Pragma("unroll") for (int n = 0; n < 2; ++n) _Pragma("unroll") for (int k = 0; k < 2; ++k) dst[n][k] = *(const PG8_LAS bf16x8*)(lds + PG8_SB(b, h) + boff + n * 2048 + k * 1024); } while (0)
; #define PG8_MMA(ai, bj, At, Bt) do { __builtin_amdgcn_s_setprio(1); _Pragma("unroll") for (int m = 0; m < 4; ++m) _Pragma("unroll") for (int n = 0; n < 2; ++n) _Pragma("unroll") for (int k = 0; k < 2; ++k) \
;         acc[ai][bj][m][n] = __builtin_amdgcn_mfma_f32_16x16x32_bf16(Bt[n][k], At[m][k], acc[ai][bj][m][n], 0, 0, 0); __builtin_amdgcn_s_setprio(0); } while (0)
; #define PG8_WAIT_V(n) asm volatile("s_waitcnt vmcnt(" #n ")" ::: "memory")
; #define PG8_WAIT_L(n) asm volatile("s_waitcnt lgkmcnt(" #n ")" ::: "memory")
; template <class Epi, class Sched, bool ALIGN_EPI = false, bool SP2 = false>
; __device__ __forceinline__ void gemm_phase(PG8_LAS unsigned char* lds, const Gemm g, const Sched& S, const Epi& E) {
;     ...
;             const bool last = (t == nt - 2);
;             const char* a1 = cA + (size_t)(t + 1) * kstep;
;             const char* a2 = last ? nA : cA + (size_t)(t + 2) * kstep; const char* b2 = last ? nB : cB + (size_t)(t + 2) * kstep;
;             const char* a3 = a2 + kstep; const char* b3 = b2 + kstep;
;             if (last && has_next) S.a_ready(nxt);
;             if constexpr (SP2) {
;             PG8_LDB(B0, 0, 0); PG8_LDB(B1, 0, 1); PG8_SCHED; PG8_LDA(At, 0, 0); PG8_STAGE(PG8_SA(1, 1), a1 + hstep, voffA);
;             PG8_WAIT_V(8); PG8_WAIT_L(0); PG8_BAR; PG8_MMA(0, 0, At, B0); PG8_MMA(0, 1, At, B1); PG8_BAR; PG8_SCHED;
;             PG8_LDA(At, 0, 1); PG8_STAGE(PG8_SB(0, 0), b2, voffB); PG8_STAGE(PG8_SB(0, 1), b2 + hstep, voffB); PG8_STAGE(PG8_SA(0, 0), a2, voffA);
;             PG8_WAIT_V(8); PG8_WAIT_L(0); PG8_BAR; PG8_MMA(1, 0, At, B0); PG8_MMA(1, 1, At, B1); PG8_BAR; PG8_SCHED;
.LBB0_512:
	s_add_u32 s52, s50, 0xfffc0080
	s_addc_u32 s53, s51, -1
	s_add_i32 s70, 0, 0x10000
	s_cmp_eq_u32 s89, 12
	s_cselect_b32 s55, s6, s53
	s_cselect_b32 s54, s7, s52
	s_cselect_b32 s53, s41, s85
	s_cselect_b32 s52, s45, s84
	s_add_i32 s71, 0, 0x14000
	v_add_u32_e32 v158, s70, v143
	v_add_u32_e32 v162, s71, v143
	ds_read_b128 v[146:149], v158
	ds_read_b128 v[150:153], v158 offset:1024
	ds_read_b128 v[154:157], v158 offset:2048
	ds_read_b128 v[158:161], v158 offset:3072
	ds_read_b128 v[180:183], v162
	ds_read_b128 v[184:187], v162 offset:1024
	ds_read_b128 v[188:191], v162 offset:2048
	ds_read_b128 v[192:195], v162 offset:3072
	v_lshl_add_u64 v[162:163], s[50:51], 0, v[138:139]
	s_add_i32 m0, s57, 0xc000
	ds_read_b128 v[208:211], v145
	ds_read_b128 v[212:215], v145 offset:1024
	ds_read_b128 v[216:219], v145 offset:2048
	ds_read_b128 v[224:227], v145 offset:3072
	ds_read_b128 v[228:231], v145 offset:4096
	ds_read_b128 v[232:235], v145 offset:5120
	ds_read_b128 v[236:239], v145 offset:6144
	ds_read_b128 v[240:243], v145 offset:7168
	global_load_lds_dwordx4 v[162:163], off
	v_lshl_add_u64 v[162:163], s[50:51], 0, v[140:141]
	s_add_i32 m0, s57, 0xe000
	s_nop 0
	global_load_lds_dwordx4 v[162:163], off
	s_waitcnt vmcnt(8)
	s_waitcnt lgkmcnt(0)
	s_barrier
	s_setprio 1
	s_waitcnt lgkmcnt(0)
	v_mfma_f32_16x16x32_bf16 v[128:131], v[146:149], v[208:211], v[128:131]
	v_mfma_f32_16x16x32_bf16 v[124:127], v[154:157], v[208:211], v[124:127]
	v_mfma_f32_16x16x32_bf16 v[120:123], v[146:149], v[216:219], v[120:123]
	v_mfma_f32_16x16x32_bf16 v[116:119], v[154:157], v[216:219], v[116:119]
	v_mfma_f32_16x16x32_bf16 v[104:107], v[146:149], v[228:231], v[104:107]
	v_mfma_f32_16x16x32_bf16 v[100:103], v[154:157], v[228:231], v[100:103]
	v_mfma_f32_16x16x32_bf16 v[88:91], v[146:149], v[236:239], v[88:91]
	v_mfma_f32_16x16x32_bf16 v[84:87], v[154:157], v[236:239], v[84:87]
	v_mfma_f32_16x16x32_bf16 v[128:131], v[150:153], v[212:215], v[128:131]
	v_mfma_f32_16x16x32_bf16 v[124:127], v[158:161], v[212:215], v[124:127]
	v_mfma_f32_16x16x32_bf16 v[120:123], v[150:153], v[224:227], v[120:123]
	v_mfma_f32_16x16x32_bf16 v[116:119], v[158:161], v[224:227], v[116:119]
	v_mfma_f32_16x16x32_bf16 v[104:107], v[150:153], v[232:235], v[104:107]
	v_mfma_f32_16x16x32_bf16 v[100:103], v[158:161], v[232:235], v[100:103]
	v_mfma_f32_16x16x32_bf16 v[88:91], v[150:153], v[240:243], v[88:91]
	v_mfma_f32_16x16x32_bf16 v[84:87], v[158:161], v[240:243], v[84:87]
	s_setprio 0
	s_setprio 1
	v_mfma_f32_16x16x32_bf16 v[112:115], v[180:183], v[208:211], v[112:115]
	v_mfma_f32_16x16x32_bf16 v[108:111], v[188:191], v[208:211], v[108:111]
	v_mfma_f32_16x16x32_bf16 v[96:99], v[180:183], v[216:219], v[96:99]
	v_mfma_f32_16x16x32_bf16 v[92:95], v[188:191], v[216:219], v[92:95]
	v_mfma_f32_16x16x32_bf16 v[80:83], v[180:183], v[228:231], v[80:83]
	v_mfma_f32_16x16x32_bf16 v[76:79], v[188:191], v[228:231], v[76:79]
	v_mfma_f32_16x16x32_bf16 v[72:75], v[180:183], v[236:239], v[72:75]
	v_mfma_f32_16x16x32_bf16 v[68:71], v[188:191], v[236:239], v[68:71]
	v_mfma_f32_16x16x32_bf16 v[112:115], v[184:187], v[212:215], v[112:115]
	v_mfma_f32_16x16x32_bf16 v[108:111], v[192:195], v[212:215], v[108:111]
	v_mfma_f32_16x16x32_bf16 v[96:99], v[184:187], v[224:227], v[96:99]
	v_mfma_f32_16x16x32_bf16 v[92:95], v[192:195], v[224:227], v[92:95]
	v_mfma_f32_16x16x32_bf16 v[80:83], v[184:187], v[232:235], v[80:83]
	v_mfma_f32_16x16x32_bf16 v[76:79], v[192:195], v[232:235], v[76:79]
	v_mfma_f32_16x16x32_bf16 v[72:75], v[184:187], v[240:243], v[72:75]
	v_mfma_f32_16x16x32_bf16 v[68:71], v[192:195], v[240:243], v[68:71]
	s_setprio 0
	s_barrier
	s_add_i32 s70, s70, s56
	v_lshl_add_u64 v[162:163], s[52:53], 0, v[2:3]
	s_mov_b32 m0, s70
	ds_read_b128 v[208:211], v145 offset:16384
	ds_read_b128 v[212:215], v145 offset:17408
	ds_read_b128 v[216:219], v145 offset:18432
	ds_read_b128 v[224:227], v145 offset:19456
	ds_read_b128 v[228:231], v145 offset:20480
	ds_read_b128 v[232:235], v145 offset:21504
	ds_read_b128 v[236:239], v145 offset:22528
	ds_read_b128 v[240:243], v145 offset:23552
	global_load_lds_dwordx4 v[162:163], off
	s_add_i32 m0, s70, 0x2000
	s_add_u32 s90, s52, 0x40000
	v_lshl_add_u64 v[196:197], s[52:53], 0, v[132:133]
	s_addc_u32 s91, s53, 0
	s_add_i32 s70, s71, s56
	global_load_lds_dwordx4 v[196:197], off
	v_lshl_add_u64 v[244:245], s[90:91], 0, v[2:3]
	s_mov_b32 m0, s70
	v_lshl_add_u64 v[246:247], s[54:55], 0, v[134:135]
	global_load_lds_dwordx4 v[244:245], off
	v_lshl_add_u64 v[244:245], s[90:91], 0, v[132:133]
	s_add_i32 m0, s70, 0x2000
	s_nop 0
	global_load_lds_dwordx4 v[244:245], off
	v_lshl_add_u64 v[244:245], s[54:55], 0, v[136:137]
	s_mov_b32 m0, s57
	s_nop 0
	global_load_lds_dwordx4 v[244:245], off
	s_mov_b32 m0, s60
	s_nop 0
	global_load_lds_dwordx4 v[246:247], off
	s_waitcnt vmcnt(8)
	s_waitcnt lgkmcnt(0)
	s_barrier
; #define PG8_STAGE(bufoff, gbase, voff) do { _Pragma("unroll") for (int _i = 0; _i < 2; ++_i) \
;         __builtin_amdgcn_global_load_lds((const unsigned*)((const char*)(gbase) + (voff)[_i]), (PG8_LAS unsigned*)(lds + (bufoff) + ldsw + _i * 8192), 16, 0, 0); } while (0)
; #define PG8_LDA(dst, b, h) do { _Pragma("unroll") for (int m = 0; m < 4; ++m) _Pragma("unroll") for (int k = 0; k < 2; ++k) dst[m][k] = *(const PG8_LAS bf16x8*)(lds + PG8_SA(b, h) + aoff + m * 2048 + k * 1024); } while (0)
; #define PG8_LDB(dst, b, h) do { _Pragma("unroll") for (int n = 0; n < 2; ++n) _Pragma("unroll") for (int k = 0; k < 2; ++k) dst[n][k] = *(const PG8_LAS bf16x8*)(lds + PG8_SB(b, h) + boff + n * 2048 + k * 1024); } while (0)
; #define PG8_MMA(ai, bj, At, Bt) do { __builtin_amdgcn_s_setprio(1); _Pragma("unroll") for (int m = 0; m < 4; ++m) _Pragma("unroll") for (int n = 0; n < 2; ++n) _Pragma("unroll") for (int k = 0; k < 2; ++k) \
;         acc[ai][bj][m][n] = __builtin_amdgcn_mfma_f32_16x16x32_bf16(Bt[n][k], At[m][k], acc[ai][bj][m][n], 0, 0, 0); __builtin_amdgcn_s_setprio(0); } while (0)
; #define PG8_WAIT_V(n) asm volatile("s_waitcnt vmcnt(" #n ")" ::: "memory")
; #define PG8_WAIT_L(n) asm volatile("s_waitcnt lgkmcnt(" #n ")" ::: "memory")
; #define PG8_BAR __builtin_amdgcn_s_barrier()
; #define PG8_SCHED __builtin_amdgcn_sched_barrier(0)
; template <class Epi, class Sched, bool ALIGN_EPI = false, bool SP2 = false>
; __device__ __forceinline__ void gemm_phase(PG8_LAS unsigned char* lds, const Gemm g, const Sched& S, const Epi& E) {
;     ...
;             PG8_WAIT_V(8); PG8_WAIT_L(0); PG8_BAR; PG8_MMA(1, 0, At, B0); PG8_MMA(1, 1, At, B1); PG8_BAR; PG8_SCHED;
;             PG8_LDB(B0, 1, 0); PG8_LDB(B1, 1, 1); PG8_SCHED; PG8_LDA(At, 1, 0); PG8_STAGE(PG8_SA(0, 1), a2 + hstep, voffA);
;             PG8_WAIT_V(8); PG8_WAIT_L(0); PG8_BAR; PG8_MMA(0, 0, At, B0); PG8_MMA(0, 1, At, B1); PG8_BAR; PG8_SCHED;
	s_setprio 1
	s_waitcnt lgkmcnt(0)
	v_mfma_f32_16x16x32_bf16 v[64:67], v[146:149], v[208:211], v[64:67]
	v_mfma_f32_16x16x32_bf16 v[60:63], v[154:157], v[208:211], v[60:63]
	v_mfma_f32_16x16x32_bf16 v[56:59], v[146:149], v[216:219], v[56:59]
	v_mfma_f32_16x16x32_bf16 v[52:55], v[154:157], v[216:219], v[52:55]
	v_mfma_f32_16x16x32_bf16 v[40:43], v[146:149], v[228:231], v[40:43]
	v_mfma_f32_16x16x32_bf16 v[36:39], v[154:157], v[228:231], v[36:39]
	v_mfma_f32_16x16x32_bf16 v[24:27], v[146:149], v[236:239], v[24:27]
	v_mfma_f32_16x16x32_bf16 v[20:23], v[154:157], v[236:239], v[20:23]
	v_mfma_f32_16x16x32_bf16 v[64:67], v[150:153], v[212:215], v[64:67]
	v_mfma_f32_16x16x32_bf16 v[60:63], v[158:161], v[212:215], v[60:63]
	v_mfma_f32_16x16x32_bf16 v[56:59], v[150:153], v[224:227], v[56:59]
	v_mfma_f32_16x16x32_bf16 v[52:55], v[158:161], v[224:227], v[52:55]
	v_mfma_f32_16x16x32_bf16 v[40:43], v[150:153], v[232:235], v[40:43]
	v_mfma_f32_16x16x32_bf16 v[36:39], v[158:161], v[232:235], v[36:39]
	v_mfma_f32_16x16x32_bf16 v[24:27], v[150:153], v[240:243], v[24:27]
	v_mfma_f32_16x16x32_bf16 v[20:23], v[158:161], v[240:243], v[20:23]
	s_setprio 0
	s_setprio 1
	v_mfma_f32_16x16x32_bf16 v[48:51], v[180:183], v[208:211], v[48:51]
	v_mfma_f32_16x16x32_bf16 v[44:47], v[188:191], v[208:211], v[44:47]
	v_mfma_f32_16x16x32_bf16 v[32:35], v[180:183], v[216:219], v[32:35]
	v_mfma_f32_16x16x32_bf16 v[28:31], v[188:191], v[216:219], v[28:31]
	v_mfma_f32_16x16x32_bf16 v[16:19], v[180:183], v[228:231], v[16:19]
	v_mfma_f32_16x16x32_bf16 v[12:15], v[188:191], v[228:231], v[12:15]
	v_mfma_f32_16x16x32_bf16 v[8:11], v[180:183], v[236:239], v[8:11]
	v_mfma_f32_16x16x32_bf16 v[4:7], v[188:191], v[236:239], v[4:7]
	v_mfma_f32_16x16x32_bf16 v[48:51], v[184:187], v[212:215], v[48:51]
	v_mfma_f32_16x16x32_bf16 v[44:47], v[192:195], v[212:215], v[44:47]
	v_mfma_f32_16x16x32_bf16 v[32:35], v[184:187], v[224:227], v[32:35]
	v_mfma_f32_16x16x32_bf16 v[28:31], v[192:195], v[224:227], v[28:31]
	v_mfma_f32_16x16x32_bf16 v[16:19], v[184:187], v[232:235], v[16:19]
	v_mfma_f32_16x16x32_bf16 v[12:15], v[192:195], v[232:235], v[12:15]
	v_mfma_f32_16x16x32_bf16 v[8:11], v[184:187], v[240:243], v[8:11]
	v_mfma_f32_16x16x32_bf16 v[4:7], v[192:195], v[240:243], v[4:7]
	s_setprio 0
	s_barrier
	s_add_i32 s70, 0, 0x18000
	s_add_i32 s71, 0, 0x1c000
	v_add_u32_e32 v158, s70, v143
	v_add_u32_e32 v167, s71, v143
	ds_read_b128 v[146:149], v158
	ds_read_b128 v[150:153], v158 offset:1024
	ds_read_b128 v[154:157], v158 offset:2048
	ds_read_b128 v[158:161], v158 offset:3072
	ds_read_b128 v[180:183], v167
	ds_read_b128 v[184:187], v167 offset:1024
	ds_read_b128 v[188:191], v167 offset:2048
	ds_read_b128 v[192:195], v167 offset:3072
	s_add_u32 s54, s54, 0x40000
	s_addc_u32 s55, s55, 0
	s_mov_b32 m0, s61
	v_lshl_add_u64 v[248:249], s[54:55], 0, v[136:137]
	ds_read_b128 v[208:211], v145 offset:32768
	ds_read_b128 v[212:215], v145 offset:33792
	ds_read_b128 v[216:219], v145 offset:34816
	ds_read_b128 v[224:227], v145 offset:35840
	ds_read_b128 v[228:231], v145 offset:36864
	ds_read_b128 v[232:235], v145 offset:37888
	ds_read_b128 v[236:239], v145 offset:38912
	ds_read_b128 v[240:243], v145 offset:39936
	global_load_lds_dwordx4 v[248:249], off
	v_lshl_add_u64 v[248:249], s[54:55], 0, v[134:135]
	s_mov_b32 m0, s78
	s_nop 0
	global_load_lds_dwordx4 v[248:249], off
	s_waitcnt vmcnt(8)
	s_waitcnt lgkmcnt(0)
	s_barrier
	s_setprio 1
	s_waitcnt lgkmcnt(0)
	v_mfma_f32_16x16x32_bf16 v[128:131], v[146:149], v[208:211], v[128:131]
	v_mfma_f32_16x16x32_bf16 v[124:127], v[154:157], v[208:211], v[124:127]
	v_mfma_f32_16x16x32_bf16 v[120:123], v[146:149], v[216:219], v[120:123]
	v_mfma_f32_16x16x32_bf16 v[116:119], v[154:157], v[216:219], v[116:119]
	v_mfma_f32_16x16x32_bf16 v[104:107], v[146:149], v[228:231], v[104:107]
	v_mfma_f32_16x16x32_bf16 v[100:103], v[154:157], v[228:231], v[100:103]
	v_mfma_f32_16x16x32_bf16 v[88:91], v[146:149], v[236:239], v[88:91]
	v_mfma_f32_16x16x32_bf16 v[84:87], v[154:157], v[236:239], v[84:87]
	v_mfma_f32_16x16x32_bf16 v[128:131], v[150:153], v[212:215], v[128:131]
	v_mfma_f32_16x16x32_bf16 v[124:127], v[158:161], v[212:215], v[124:127]
	v_mfma_f32_16x16x32_bf16 v[120:123], v[150:153], v[224:227], v[120:123]
	v_mfma_f32_16x16x32_bf16 v[116:119], v[158:161], v[224:227], v[116:119]
	v_mfma_f32_16x16x32_bf16 v[104:107], v[150:153], v[232:235], v[104:107]
	v_mfma_f32_16x16x32_bf16 v[100:103], v[158:161], v[232:235], v[100:103]
	v_mfma_f32_16x16x32_bf16 v[88:91], v[150:153], v[240:243], v[88:91]
	v_mfma_f32_16x16x32_bf16 v[84:87], v[158:161], v[240:243], v[84:87]
	s_setprio 0
	s_setprio 1
	v_mfma_f32_16x16x32_bf16 v[112:115], v[180:183], v[208:211], v[112:115]
	v_mfma_f32_16x16x32_bf16 v[108:111], v[188:191], v[208:211], v[108:111]
	v_mfma_f32_16x16x32_bf16 v[96:99], v[180:183], v[216:219], v[96:99]
	v_mfma_f32_16x16x32_bf16 v[92:95], v[188:191], v[216:219], v[92:95]
	v_mfma_f32_16x16x32_bf16 v[80:83], v[180:183], v[228:231], v[80:83]
	v_mfma_f32_16x16x32_bf16 v[76:79], v[188:191], v[228:231], v[76:79]
	v_mfma_f32_16x16x32_bf16 v[72:75], v[180:183], v[236:239], v[72:75]
	v_mfma_f32_16x16x32_bf16 v[68:71], v[188:191], v[236:239], v[68:71]
	v_mfma_f32_16x16x32_bf16 v[112:115], v[184:187], v[212:215], v[112:115]
	v_mfma_f32_16x16x32_bf16 v[108:111], v[192:195], v[212:215], v[108:111]
	v_mfma_f32_16x16x32_bf16 v[96:99], v[184:187], v[224:227], v[96:99]
	v_mfma_f32_16x16x32_bf16 v[92:95], v[192:195], v[224:227], v[92:95]
	v_mfma_f32_16x16x32_bf16 v[80:83], v[184:187], v[232:235], v[80:83]
	v_mfma_f32_16x16x32_bf16 v[76:79], v[192:195], v[232:235], v[76:79]
	v_mfma_f32_16x16x32_bf16 v[72:75], v[184:187], v[240:243], v[72:75]
	v_mfma_f32_16x16x32_bf16 v[68:71], v[192:195], v[240:243], v[68:71]
	s_setprio 0
	s_barrier
; #define PG8_STAGE(bufoff, gbase, voff) do { _Pragma("unroll") for (int _i = 0; _i < 2; ++_i) \
;         __builtin_amdgcn_global_load_lds((const unsigned*)((const char*)(gbase) + (voff)[_i]), (PG8_LAS unsigned*)(lds + (bufoff) + ldsw + _i * 8192), 16, 0, 0); } while (0)
; #define PG8_LDA(dst, b, h) do { _Pragma("unroll") for (int m = 0; m < 4; ++m) _Pragma("unroll") for (int k = 0; k < 2; ++k) dst[m][k] = *(const PG8_LAS bf16x8*)(lds + PG8_SA(b, h) + aoff + m * 2048 + k * 1024); } while (0)
; #define PG8_LDB(dst, b, h) do { _Pragma("unroll") for (int n = 0; n < 2; ++n) _Pragma("unroll") for (int k = 0; k < 2; ++k) dst[n][k] = *(const PG8_LAS bf16x8*)(lds + PG8_SB(b, h) + boff + n * 2048 + k * 1024); } while (0)
; template <class Epi, class Sched, bool ALIGN_EPI = false, bool SP2 = false>
; __device__ __forceinline__ void gemm_phase(PG8_LAS unsigned char* lds, const Gemm g, const Sched& S, const Epi& E) {
;     ...
;         for (int t = 0; t < nt; t += 2) {
;             const bool last = (t == nt - 2);
;             const char* a1 = cA + (size_t)(t + 1) * kstep;
;             const char* a2 = last ? nA : cA + (size_t)(t + 2) * kstep; const char* b2 = last ? nB : cB + (size_t)(t + 2) * kstep;
;             const char* a3 = a2 + kstep; const char* b3 = b2 + kstep;
;             if (last && has_next) S.a_ready(nxt);
;             if constexpr (SP2) {
;             PG8_LDB(B0, 0, 0); PG8_LDB(B1, 0, 1); PG8_SCHED; PG8_LDA(At, 0, 0); PG8_STAGE(PG8_SA(1, 1), a1 + hstep, voffA);
;             PG8_WAIT_V(8); PG8_WAIT_L(0); PG8_BAR; PG8_MMA(0, 0, At, B0); PG8_MMA(0, 1, At, B1); PG8_BAR; PG8_SCHED;
;             PG8_LDA(At, 0, 1); PG8_STAGE(PG8_SB(0, 0), b2, voffB); PG8_STAGE(PG8_SB(0, 1), b2 + hstep, voffB); PG8_STAGE(PG8_SA(0, 0), a2, voffA);
;             PG8_WAIT_V(8); PG8_WAIT_L(0); PG8_BAR; PG8_MMA(1, 0, At, B0); PG8_MMA(1, 1, At, B1); PG8_BAR; PG8_SCHED;
;             PG8_LDB(B0, 1, 0); PG8_LDB(B1, 1, 1); PG8_SCHED; PG8_LDA(At, 1, 0); PG8_STAGE(PG8_SA(0, 1), a2 + hstep, voffA);
;             PG8_WAIT_V(8); PG8_WAIT_L(0); PG8_BAR; PG8_MMA(0, 0, At, B0); PG8_MMA(0, 1, At, B1); PG8_BAR; PG8_SCHED;
;             PG8_LDA(At, 1, 1); PG8_STAGE(PG8_SB(1, 0), b3, voffB); PG8_STAGE(PG8_SB(1, 1), b3 + hstep, voffB); PG8_STAGE(PG8_SA(1, 0), a3, voffA);
;             PG8_WAIT_V(8); PG8_WAIT_L(0); PG8_BAR; PG8_MMA(1, 0, At, B0); PG8_MMA(1, 1, At, B1); PG8_BAR; PG8_SCHED;
	s_add_i32 s54, s70, s56
	v_lshl_add_u64 v[162:163], v[162:163], 0, s[14:15]
	s_mov_b32 m0, s54
	ds_read_b128 v[208:211], v145 offset:49152
	ds_read_b128 v[212:215], v145 offset:50176
	ds_read_b128 v[216:219], v145 offset:51200
	ds_read_b128 v[224:227], v145 offset:52224
	ds_read_b128 v[228:231], v145 offset:53248
	ds_read_b128 v[232:235], v145 offset:54272
	ds_read_b128 v[236:239], v145 offset:55296
	ds_read_b128 v[240:243], v145 offset:56320
	global_load_lds_dwordx4 v[162:163], off
	s_add_i32 m0, s54, 0x2000
	s_add_u32 s52, s52, 0x40080
	v_lshl_add_u64 v[162:163], v[196:197], 0, s[14:15]
	s_addc_u32 s53, s53, 0
	s_add_i32 s54, s71, s56
	global_load_lds_dwordx4 v[162:163], off
	v_lshl_add_u64 v[162:163], s[52:53], 0, v[2:3]
	s_mov_b32 m0, s54
	s_nop 0
	global_load_lds_dwordx4 v[162:163], off
	v_lshl_add_u64 v[162:163], s[52:53], 0, v[132:133]
	s_add_i32 m0, s54, 0x2000
	s_nop 0
	global_load_lds_dwordx4 v[162:163], off
	v_lshl_add_u64 v[162:163], v[244:245], 0, s[14:15]
	s_mov_b32 m0, s79
	s_nop 0
	global_load_lds_dwordx4 v[162:163], off
	v_lshl_add_u64 v[162:163], v[246:247], 0, s[14:15]
	s_mov_b32 m0, s80
	s_nop 0
	global_load_lds_dwordx4 v[162:163], off
	s_waitcnt vmcnt(8)
	s_waitcnt lgkmcnt(0)
	s_barrier
	s_setprio 1
	s_waitcnt lgkmcnt(0)
	v_mfma_f32_16x16x32_bf16 v[64:67], v[146:149], v[208:211], v[64:67]
	v_mfma_f32_16x16x32_bf16 v[60:63], v[154:157], v[208:211], v[60:63]
	v_mfma_f32_16x16x32_bf16 v[56:59], v[146:149], v[216:219], v[56:59]
	v_mfma_f32_16x16x32_bf16 v[52:55], v[154:157], v[216:219], v[52:55]
	v_mfma_f32_16x16x32_bf16 v[40:43], v[146:149], v[228:231], v[40:43]
	v_mfma_f32_16x16x32_bf16 v[36:39], v[154:157], v[228:231], v[36:39]
	v_mfma_f32_16x16x32_bf16 v[24:27], v[146:149], v[236:239], v[24:27]
	v_mfma_f32_16x16x32_bf16 v[20:23], v[154:157], v[236:239], v[20:23]
	v_mfma_f32_16x16x32_bf16 v[64:67], v[150:153], v[212:215], v[64:67]
	v_mfma_f32_16x16x32_bf16 v[60:63], v[158:161], v[212:215], v[60:63]
	v_mfma_f32_16x16x32_bf16 v[56:59], v[150:153], v[224:227], v[56:59]
	v_mfma_f32_16x16x32_bf16 v[52:55], v[158:161], v[224:227], v[52:55]
	v_mfma_f32_16x16x32_bf16 v[40:43], v[150:153], v[232:235], v[40:43]
	v_mfma_f32_16x16x32_bf16 v[36:39], v[158:161], v[232:235], v[36:39]
	v_mfma_f32_16x16x32_bf16 v[24:27], v[150:153], v[240:243], v[24:27]
	v_mfma_f32_16x16x32_bf16 v[20:23], v[158:161], v[240:243], v[20:23]
	s_setprio 0
	s_setprio 1
	v_mfma_f32_16x16x32_bf16 v[48:51], v[180:183], v[208:211], v[48:51]
	v_mfma_f32_16x16x32_bf16 v[44:47], v[188:191], v[208:211], v[44:47]
	v_mfma_f32_16x16x32_bf16 v[32:35], v[180:183], v[216:219], v[32:35]
	v_mfma_f32_16x16x32_bf16 v[28:31], v[188:191], v[216:219], v[28:31]
	v_mfma_f32_16x16x32_bf16 v[16:19], v[180:183], v[228:231], v[16:19]
	v_mfma_f32_16x16x32_bf16 v[12:15], v[188:191], v[228:231], v[12:15]
	v_mfma_f32_16x16x32_bf16 v[8:11], v[180:183], v[236:239], v[8:11]
	v_mfma_f32_16x16x32_bf16 v[4:7], v[188:191], v[236:239], v[4:7]
	v_mfma_f32_16x16x32_bf16 v[48:51], v[184:187], v[212:215], v[48:51]
	v_mfma_f32_16x16x32_bf16 v[44:47], v[192:195], v[212:215], v[44:47]
	v_mfma_f32_16x16x32_bf16 v[32:35], v[184:187], v[224:227], v[32:35]
	v_mfma_f32_16x16x32_bf16 v[28:31], v[192:195], v[224:227], v[28:31]
	v_mfma_f32_16x16x32_bf16 v[16:19], v[184:187], v[232:235], v[16:19]
	v_mfma_f32_16x16x32_bf16 v[12:15], v[192:195], v[232:235], v[12:15]
	v_mfma_f32_16x16x32_bf16 v[8:11], v[184:187], v[240:243], v[8:11]
	v_mfma_f32_16x16x32_bf16 v[4:7], v[192:195], v[240:243], v[4:7]
	s_setprio 0
	s_add_i32 s89, s89, 2
	s_add_u32 s50, s50, 0x100
	s_addc_u32 s51, s51, 0
	s_add_u32 s84, s84, 0x100
	s_addc_u32 s85, s85, 0
	s_cmp_gt_u32 s89, 13
	s_barrier
	s_cbranch_scc0 .LBB0_512
	s_and_b64 vcc, exec, s[36:37]
	s_cbranch_vccz .LBB0_515
	s_barrier

; #define PG8_STAGE(bufoff, gbase, voff) do { _Pragma("unroll") for (int _i = 0; _i < 2; ++_i) \
;         __builtin_amdgcn_global_load_lds((const unsigned*)((const char*)(gbase) + (voff)[_i]), (PG8_LAS unsigned*)(lds + (bufoff) + ldsw + _i * 8192), 16, 0, 0); } while (0)
; #define PG8_LDA(dst, b, h) do { _Pragma("unroll") for (int m = 0; m < 4; ++m) _Pragma("unroll") for (int k = 0; k < 2; ++k) dst[m][k] = *(const PG8_LAS bf16x8*)(lds + PG8_SA(b, h) + aoff + m * 2048 + k * 1024); } while (0)
; #define PG8_LDB(dst, b, h) do { _Pragma("unroll") for (int n = 0; n < 2; ++n) _Pragma("unroll") for (int k = 0; k < 2; ++k) dst[n][k] = *(const PG8_LAS bf16x8*)(lds + PG8_SB(b, h) + boff + n * 2048 + k * 1024); } while (0)
; #define PG8_MMA(ai, bj, At, Bt) do { __builtin_amdgcn_s_setprio(1); _Pragma("unroll") for (int m = 0; m < 4; ++m) _Pragma("unroll") for (int n = 0; n < 2; ++n) _Pragma("unroll") for (int k = 0; k < 2; ++k) \
;         acc[ai][bj][m][n] = __builtin_amdgcn_mfma_f32_16x16x32_bf16(Bt[n][k], At[m][k], acc[ai][bj][m][n], 0, 0, 0); __builtin_amdgcn_s_setprio(0); } while (0)
; #define PG8_WAIT_V(n) asm volatile("s_waitcnt vmcnt(" #n ")" ::: "memory")
; #define PG8_WAIT_L(n) asm volatile("s_waitcnt lgkmcnt(" #n ")" ::: "memory")
; template <class Epi, class Sched, bool ALIGN_EPI = false, bool SP2 = false>
; __device__ __forceinline__ void gemm_phase(PG8_LAS unsigned char* lds, const Gemm g, const Sched& S, const Epi& E) {
;     ...
;             const bool last = (t == nt - 2);
;             const char* a1 = cA + (size_t)(t + 1) * kstep;
;             const char* a2 = last ? nA : cA + (size_t)(t + 2) * kstep; const char* b2 = last ? nB : cB + (size_t)(t + 2) * kstep;
;             const char* a3 = a2 + kstep; const char* b3 = b2 + kstep;
;             if (last && has_next) S.a_ready(nxt);
;             if constexpr (SP2) {
;             PG8_LDB(B0, 0, 0); PG8_LDB(B1, 0, 1); PG8_SCHED; PG8_LDA(At, 0, 0); PG8_STAGE(PG8_SA(1, 1), a1 + hstep, voffA);
;             PG8_WAIT_V(8); PG8_WAIT_L(0); PG8_BAR; PG8_MMA(0, 0, At, B0); PG8_MMA(0, 1, At, B1); PG8_BAR; PG8_SCHED;
;             PG8_LDA(At, 0, 1); PG8_STAGE(PG8_SB(0, 0), b2, voffB); PG8_STAGE(PG8_SB(0, 1), b2 + hstep, voffB); PG8_STAGE(PG8_SA(0, 0), a2, voffA);
;             PG8_WAIT_V(8); PG8_WAIT_L(0); PG8_BAR; PG8_MMA(1, 0, At, B0); PG8_MMA(1, 1, At, B1); PG8_BAR; PG8_SCHED;
.LBB0_698:
	s_add_u32 s52, s50, 0xfffc0080
	s_addc_u32 s53, s51, -1
	s_add_i32 s70, 0, 0x10000
	s_cmp_eq_u32 s89, 12
	s_cselect_b32 s55, s6, s53
	s_cselect_b32 s54, s7, s52
	v_add_u32_e32 v2, s70, v168
	s_cselect_b32 s53, s43, s85
	s_cselect_b32 s52, s45, s84
	s_add_i32 s71, 0, 0x14000
	ds_read_b128 v[100:103], v2
	ds_read_b128 v[112:115], v2 offset:1024
	ds_read_b128 v[124:127], v2 offset:2048
	ds_read_b128 v[136:139], v2 offset:3072
	v_add_u32_e32 v2, s71, v168
	ds_read_b128 v[148:151], v2
	ds_read_b128 v[152:155], v2 offset:1024
	ds_read_b128 v[156:159], v2 offset:2048
	ds_read_b128 v[188:191], v2 offset:3072
	v_lshl_add_u64 v[240:241], s[50:51], 0, v[184:185]
	s_add_i32 m0, s57, 0xc000
	ds_read_b128 v[192:195], v197
	ds_read_b128 v[208:211], v197 offset:1024
	ds_read_b128 v[212:215], v197 offset:2048
	ds_read_b128 v[216:219], v197 offset:3072
	ds_read_b128 v[224:227], v197 offset:4096
	ds_read_b128 v[228:231], v197 offset:5120
	ds_read_b128 v[232:235], v197 offset:6144
	ds_read_b128 v[236:239], v197 offset:7168
	global_load_lds_dwordx4 v[240:241], off
	v_lshl_add_u64 v[240:241], s[50:51], 0, v[186:187]
	s_add_i32 m0, s57, 0xe000
	s_nop 0
	global_load_lds_dwordx4 v[240:241], off
	s_waitcnt vmcnt(8)
	s_waitcnt lgkmcnt(0)
	s_barrier
	s_setprio 1
	s_waitcnt lgkmcnt(0)
	v_mfma_f32_16x16x32_bf16 v[144:147], v[100:103], v[192:195], v[144:147]
	v_mfma_f32_16x16x32_bf16 v[140:143], v[124:127], v[192:195], v[140:143]
	v_mfma_f32_16x16x32_bf16 v[120:123], v[100:103], v[212:215], v[120:123]
	v_mfma_f32_16x16x32_bf16 v[116:119], v[124:127], v[212:215], v[116:119]
	v_mfma_f32_16x16x32_bf16 v[96:99], v[100:103], v[224:227], v[96:99]
	v_mfma_f32_16x16x32_bf16 v[92:95], v[124:127], v[224:227], v[92:95]
	v_mfma_f32_16x16x32_bf16 v[80:83], v[100:103], v[232:235], v[80:83]
	v_mfma_f32_16x16x32_bf16 v[76:79], v[124:127], v[232:235], v[76:79]
	v_mfma_f32_16x16x32_bf16 v[144:147], v[112:115], v[208:211], v[144:147]
	v_mfma_f32_16x16x32_bf16 v[140:143], v[136:139], v[208:211], v[140:143]
	v_mfma_f32_16x16x32_bf16 v[120:123], v[112:115], v[216:219], v[120:123]
	v_mfma_f32_16x16x32_bf16 v[116:119], v[136:139], v[216:219], v[116:119]
	v_mfma_f32_16x16x32_bf16 v[96:99], v[112:115], v[228:231], v[96:99]
	v_mfma_f32_16x16x32_bf16 v[92:95], v[136:139], v[228:231], v[92:95]
	v_mfma_f32_16x16x32_bf16 v[80:83], v[112:115], v[236:239], v[80:83]
	v_mfma_f32_16x16x32_bf16 v[76:79], v[136:139], v[236:239], v[76:79]
	s_setprio 0
	s_setprio 1
	v_mfma_f32_16x16x32_bf16 v[132:135], v[148:151], v[192:195], v[132:135]
	v_mfma_f32_16x16x32_bf16 v[128:131], v[156:159], v[192:195], v[128:131]
	v_mfma_f32_16x16x32_bf16 v[108:111], v[148:151], v[212:215], v[108:111]
	v_mfma_f32_16x16x32_bf16 v[104:107], v[156:159], v[212:215], v[104:107]
	v_mfma_f32_16x16x32_bf16 v[88:91], v[148:151], v[224:227], v[88:91]
	v_mfma_f32_16x16x32_bf16 v[84:87], v[156:159], v[224:227], v[84:87]
	v_mfma_f32_16x16x32_bf16 v[72:75], v[148:151], v[232:235], v[72:75]
	v_mfma_f32_16x16x32_bf16 v[68:71], v[156:159], v[232:235], v[68:71]
	v_mfma_f32_16x16x32_bf16 v[132:135], v[152:155], v[208:211], v[132:135]
	v_mfma_f32_16x16x32_bf16 v[128:131], v[188:191], v[208:211], v[128:131]
	v_mfma_f32_16x16x32_bf16 v[108:111], v[152:155], v[216:219], v[108:111]
	v_mfma_f32_16x16x32_bf16 v[104:107], v[188:191], v[216:219], v[104:107]
	v_mfma_f32_16x16x32_bf16 v[88:91], v[152:155], v[228:231], v[88:91]
	v_mfma_f32_16x16x32_bf16 v[84:87], v[188:191], v[228:231], v[84:87]
	v_mfma_f32_16x16x32_bf16 v[72:75], v[152:155], v[236:239], v[72:75]
	v_mfma_f32_16x16x32_bf16 v[68:71], v[188:191], v[236:239], v[68:71]
	s_setprio 0
	s_barrier
	s_add_i32 s70, s70, s56
	v_lshl_add_u64 v[240:241], s[52:53], 0, v[180:181]
	s_mov_b32 m0, s70
	ds_read_b128 v[192:195], v197 offset:16384
	ds_read_b128 v[208:211], v197 offset:17408
	ds_read_b128 v[212:215], v197 offset:18432
	ds_read_b128 v[216:219], v197 offset:19456
	ds_read_b128 v[224:227], v197 offset:20480
	ds_read_b128 v[228:231], v197 offset:21504
	ds_read_b128 v[232:235], v197 offset:22528
	ds_read_b128 v[236:239], v197 offset:23552
	global_load_lds_dwordx4 v[240:241], off
	s_add_i32 m0, s70, 0x2000
	s_add_u32 s90, s52, 0x40000
	v_lshl_add_u64 v[242:243], s[52:53], 0, v[160:161]
	s_addc_u32 s91, s53, 0
	s_add_i32 s70, s71, s56
	global_load_lds_dwordx4 v[242:243], off
	v_lshl_add_u64 v[244:245], s[90:91], 0, v[180:181]
	s_mov_b32 m0, s70
	v_lshl_add_u64 v[246:247], s[54:55], 0, v[162:163]
	global_load_lds_dwordx4 v[244:245], off
	v_lshl_add_u64 v[244:245], s[90:91], 0, v[160:161]
	s_add_i32 m0, s70, 0x2000
	s_nop 0
	global_load_lds_dwordx4 v[244:245], off
	v_lshl_add_u64 v[244:245], s[54:55], 0, v[182:183]
	s_mov_b32 m0, s57
	s_nop 0
	global_load_lds_dwordx4 v[244:245], off
	s_mov_b32 m0, s60
	s_nop 0
	global_load_lds_dwordx4 v[246:247], off
	s_waitcnt vmcnt(8)
	s_waitcnt lgkmcnt(0)
	s_barrier
; #define PG8_STAGE(bufoff, gbase, voff) do { _Pragma("unroll") for (int _i = 0; _i < 2; ++_i) \
;         __builtin_amdgcn_global_load_lds((const unsigned*)((const char*)(gbase) + (voff)[_i]), (PG8_LAS unsigned*)(lds + (bufoff) + ldsw + _i * 8192), 16, 0, 0); } while (0)
; #define PG8_LDA(dst, b, h) do { _Pragma("unroll") for (int m = 0; m < 4; ++m) _Pragma("unroll") for (int k = 0; k < 2; ++k) dst[m][k] = *(const PG8_LAS bf16x8*)(lds + PG8_SA(b, h) + aoff + m * 2048 + k * 1024); } while (0)
; #define PG8_LDB(dst, b, h) do { _Pragma("unroll") for (int n = 0; n < 2; ++n) _Pragma("unroll") for (int k = 0; k < 2; ++k) dst[n][k] = *(const PG8_LAS bf16x8*)(lds + PG8_SB(b, h) + boff + n * 2048 + k * 1024); } while (0)
; #define PG8_MMA(ai, bj, At, Bt) do { __builtin_amdgcn_s_setprio(1); _Pragma("unroll") for (int m = 0; m < 4; ++m) _Pragma("unroll") for (int n = 0; n < 2; ++n) _Pragma("unroll") for (int k = 0; k < 2; ++k) \
;         acc[ai][bj][m][n] = __builtin_amdgcn_mfma_f32_16x16x32_bf16(Bt[n][k], At[m][k], acc[ai][bj][m][n], 0, 0, 0); __builtin_amdgcn_s_setprio(0); } while (0)
; #define PG8_WAIT_V(n) asm volatile("s_waitcnt vmcnt(" #n ")" ::: "memory")
; #define PG8_WAIT_L(n) asm volatile("s_waitcnt lgkmcnt(" #n ")" ::: "memory")
; #define PG8_BAR __builtin_amdgcn_s_barrier()
; #define PG8_SCHED __builtin_amdgcn_sched_barrier(0)
; template <class Epi, class Sched, bool ALIGN_EPI = false, bool SP2 = false>
; __device__ __forceinline__ void gemm_phase(PG8_LAS unsigned char* lds, const Gemm g, const Sched& S, const Epi& E) {
;     ...
;             PG8_WAIT_V(8); PG8_WAIT_L(0); PG8_BAR; PG8_MMA(1, 0, At, B0); PG8_MMA(1, 1, At, B1); PG8_BAR; PG8_SCHED;
;             PG8_LDB(B0, 1, 0); PG8_LDB(B1, 1, 1); PG8_SCHED; PG8_LDA(At, 1, 0); PG8_STAGE(PG8_SA(0, 1), a2 + hstep, voffA);
;             PG8_WAIT_V(8); PG8_WAIT_L(0); PG8_BAR; PG8_MMA(0, 0, At, B0); PG8_MMA(0, 1, At, B1); PG8_BAR; PG8_SCHED;
	s_setprio 1
	s_waitcnt lgkmcnt(0)
	v_mfma_f32_16x16x32_bf16 v[64:67], v[100:103], v[192:195], v[64:67]
	v_mfma_f32_16x16x32_bf16 v[60:63], v[124:127], v[192:195], v[60:63]
	v_mfma_f32_16x16x32_bf16 v[48:51], v[100:103], v[212:215], v[48:51]
	v_mfma_f32_16x16x32_bf16 v[44:47], v[124:127], v[212:215], v[44:47]
	v_mfma_f32_16x16x32_bf16 v[32:35], v[100:103], v[224:227], v[32:35]
	v_mfma_f32_16x16x32_bf16 v[28:31], v[124:127], v[224:227], v[28:31]
	v_mfma_f32_16x16x32_bf16 v[16:19], v[100:103], v[232:235], v[16:19]
	v_mfma_f32_16x16x32_bf16 v[12:15], v[124:127], v[232:235], v[12:15]
	v_mfma_f32_16x16x32_bf16 v[64:67], v[112:115], v[208:211], v[64:67]
	v_mfma_f32_16x16x32_bf16 v[60:63], v[136:139], v[208:211], v[60:63]
	v_mfma_f32_16x16x32_bf16 v[48:51], v[112:115], v[216:219], v[48:51]
	v_mfma_f32_16x16x32_bf16 v[44:47], v[136:139], v[216:219], v[44:47]
	v_mfma_f32_16x16x32_bf16 v[32:35], v[112:115], v[228:231], v[32:35]
	v_mfma_f32_16x16x32_bf16 v[28:31], v[136:139], v[228:231], v[28:31]
	v_mfma_f32_16x16x32_bf16 v[16:19], v[112:115], v[236:239], v[16:19]
	v_mfma_f32_16x16x32_bf16 v[12:15], v[136:139], v[236:239], v[12:15]
	s_setprio 0
	s_setprio 1
	v_mfma_f32_16x16x32_bf16 v[56:59], v[148:151], v[192:195], v[56:59]
	v_mfma_f32_16x16x32_bf16 v[52:55], v[156:159], v[192:195], v[52:55]
	v_mfma_f32_16x16x32_bf16 v[40:43], v[148:151], v[212:215], v[40:43]
	v_mfma_f32_16x16x32_bf16 v[36:39], v[156:159], v[212:215], v[36:39]
	v_mfma_f32_16x16x32_bf16 v[24:27], v[148:151], v[224:227], v[24:27]
	v_mfma_f32_16x16x32_bf16 v[20:23], v[156:159], v[224:227], v[20:23]
	v_mfma_f32_16x16x32_bf16 v[8:11], v[148:151], v[232:235], v[8:11]
	v_mfma_f32_16x16x32_bf16 v[4:7], v[156:159], v[232:235], v[4:7]
	v_mfma_f32_16x16x32_bf16 v[56:59], v[152:155], v[208:211], v[56:59]
	v_mfma_f32_16x16x32_bf16 v[52:55], v[188:191], v[208:211], v[52:55]
	v_mfma_f32_16x16x32_bf16 v[40:43], v[152:155], v[216:219], v[40:43]
	v_mfma_f32_16x16x32_bf16 v[36:39], v[188:191], v[216:219], v[36:39]
	v_mfma_f32_16x16x32_bf16 v[24:27], v[152:155], v[228:231], v[24:27]
	v_mfma_f32_16x16x32_bf16 v[20:23], v[188:191], v[228:231], v[20:23]
	v_mfma_f32_16x16x32_bf16 v[8:11], v[152:155], v[236:239], v[8:11]
	v_mfma_f32_16x16x32_bf16 v[4:7], v[188:191], v[236:239], v[4:7]
	s_setprio 0
	s_barrier
	s_add_i32 s70, 0, 0x18000
	v_add_u32_e32 v2, s70, v168
	s_add_i32 s71, 0, 0x1c000
	ds_read_b128 v[100:103], v2
	ds_read_b128 v[112:115], v2 offset:1024
	ds_read_b128 v[124:127], v2 offset:2048
	ds_read_b128 v[136:139], v2 offset:3072
	v_add_u32_e32 v2, s71, v168
	ds_read_b128 v[148:151], v2
	ds_read_b128 v[152:155], v2 offset:1024
	ds_read_b128 v[156:159], v2 offset:2048
	ds_read_b128 v[188:191], v2 offset:3072
	s_add_u32 s54, s54, 0x40000
	s_addc_u32 s55, s55, 0
	s_mov_b32 m0, s61
	v_lshl_add_u64 v[248:249], s[54:55], 0, v[182:183]
	ds_read_b128 v[192:195], v197 offset:32768
	ds_read_b128 v[208:211], v197 offset:33792
	ds_read_b128 v[212:215], v197 offset:34816
	ds_read_b128 v[216:219], v197 offset:35840
	ds_read_b128 v[224:227], v197 offset:36864
	ds_read_b128 v[228:231], v197 offset:37888
	ds_read_b128 v[232:235], v197 offset:38912
	ds_read_b128 v[236:239], v197 offset:39936
	global_load_lds_dwordx4 v[248:249], off
	v_lshl_add_u64 v[248:249], s[54:55], 0, v[162:163]
	s_mov_b32 m0, s78
	s_nop 0
	global_load_lds_dwordx4 v[248:249], off
	s_waitcnt vmcnt(8)
	s_waitcnt lgkmcnt(0)
	s_barrier
	s_setprio 1
	s_waitcnt lgkmcnt(0)
	v_mfma_f32_16x16x32_bf16 v[144:147], v[100:103], v[192:195], v[144:147]
	v_mfma_f32_16x16x32_bf16 v[140:143], v[124:127], v[192:195], v[140:143]
	v_mfma_f32_16x16x32_bf16 v[120:123], v[100:103], v[212:215], v[120:123]
	v_mfma_f32_16x16x32_bf16 v[116:119], v[124:127], v[212:215], v[116:119]
	v_mfma_f32_16x16x32_bf16 v[96:99], v[100:103], v[224:227], v[96:99]
	v_mfma_f32_16x16x32_bf16 v[92:95], v[124:127], v[224:227], v[92:95]
	v_mfma_f32_16x16x32_bf16 v[80:83], v[100:103], v[232:235], v[80:83]
	v_mfma_f32_16x16x32_bf16 v[76:79], v[124:127], v[232:235], v[76:79]
	v_mfma_f32_16x16x32_bf16 v[144:147], v[112:115], v[208:211], v[144:147]
	v_mfma_f32_16x16x32_bf16 v[140:143], v[136:139], v[208:211], v[140:143]
	v_mfma_f32_16x16x32_bf16 v[120:123], v[112:115], v[216:219], v[120:123]
	v_mfma_f32_16x16x32_bf16 v[116:119], v[136:139], v[216:219], v[116:119]
	v_mfma_f32_16x16x32_bf16 v[96:99], v[112:115], v[228:231], v[96:99]
	v_mfma_f32_16x16x32_bf16 v[92:95], v[136:139], v[228:231], v[92:95]
	v_mfma_f32_16x16x32_bf16 v[80:83], v[112:115], v[236:239], v[80:83]
	v_mfma_f32_16x16x32_bf16 v[76:79], v[136:139], v[236:239], v[76:79]
	s_setprio 0
	s_setprio 1
	v_mfma_f32_16x16x32_bf16 v[132:135], v[148:151], v[192:195], v[132:135]
	v_mfma_f32_16x16x32_bf16 v[128:131], v[156:159], v[192:195], v[128:131]
	v_mfma_f32_16x16x32_bf16 v[108:111], v[148:151], v[212:215], v[108:111]
	v_mfma_f32_16x16x32_bf16 v[104:107], v[156:159], v[212:215], v[104:107]
	v_mfma_f32_16x16x32_bf16 v[88:91], v[148:151], v[224:227], v[88:91]
	v_mfma_f32_16x16x32_bf16 v[84:87], v[156:159], v[224:227], v[84:87]
	v_mfma_f32_16x16x32_bf16 v[72:75], v[148:151], v[232:235], v[72:75]
	v_mfma_f32_16x16x32_bf16 v[68:71], v[156:159], v[232:235], v[68:71]
	v_mfma_f32_16x16x32_bf16 v[132:135], v[152:155], v[208:211], v[132:135]
	v_mfma_f32_16x16x32_bf16 v[128:131], v[188:191], v[208:211], v[128:131]
	v_mfma_f32_16x16x32_bf16 v[108:111], v[152:155], v[216:219], v[108:111]
	v_mfma_f32_16x16x32_bf16 v[104:107], v[188:191], v[216:219], v[104:107]
	v_mfma_f32_16x16x32_bf16 v[88:91], v[152:155], v[228:231], v[88:91]
	v_mfma_f32_16x16x32_bf16 v[84:87], v[188:191], v[228:231], v[84:87]
	v_mfma_f32_16x16x32_bf16 v[72:75], v[152:155], v[236:239], v[72:75]
	v_mfma_f32_16x16x32_bf16 v[68:71], v[188:191], v[236:239], v[68:71]
	s_setprio 0
	s_barrier
; #define PG8_STAGE(bufoff, gbase, voff) do { _Pragma("unroll") for (int _i = 0; _i < 2; ++_i) \
;         __builtin_amdgcn_global_load_lds((const unsigned*)((const char*)(gbase) + (voff)[_i]), (PG8_LAS unsigned*)(lds + (bufoff) + ldsw + _i * 8192), 16, 0, 0); } while (0)
; #define PG8_LDA(dst, b, h) do { _Pragma("unroll") for (int m = 0; m < 4; ++m) _Pragma("unroll") for (int k = 0; k < 2; ++k) dst[m][k] = *(const PG8_LAS bf16x8*)(lds + PG8_SA(b, h) + aoff + m * 2048 + k * 1024); } while (0)
; #define PG8_MMA(ai, bj, At, Bt) do { __builtin_amdgcn_s_setprio(1); _Pragma("unroll") for (int m = 0; m < 4; ++m) _Pragma("unroll") for (int n = 0; n < 2; ++n) _Pragma("unroll") for (int k = 0; k < 2; ++k) \
;         acc[ai][bj][m][n] = __builtin_amdgcn_mfma_f32_16x16x32_bf16(Bt[n][k], At[m][k], acc[ai][bj][m][n], 0, 0, 0); __builtin_amdgcn_s_setprio(0); } while (0)
; #define PG8_WAIT_V(n) asm volatile("s_waitcnt vmcnt(" #n ")" ::: "memory")
; #define PG8_WAIT_L(n) asm volatile("s_waitcnt lgkmcnt(" #n ")" ::: "memory")
; #define PG8_BAR __builtin_amdgcn_s_barrier()
; #define PG8_SCHED __builtin_amdgcn_sched_barrier(0)
; template <class Epi, class Sched, bool ALIGN_EPI = false, bool SP2 = false>
; __device__ __forceinline__ void gemm_phase(PG8_LAS unsigned char* lds, const Gemm g, const Sched& S, const Epi& E) {
;     ...
;         for (int t = 0; t < nt; t += 2) {
;             const bool last = (t == nt - 2);
;     ...
;             PG8_LDA(At, 1, 1); PG8_STAGE(PG8_SB(1, 0), b3, voffB); PG8_STAGE(PG8_SB(1, 1), b3 + hstep, voffB); PG8_STAGE(PG8_SA(1, 0), a3, voffA);
;             PG8_WAIT_V(8); PG8_WAIT_L(0); PG8_BAR; PG8_MMA(1, 0, At, B0); PG8_MMA(1, 1, At, B1); PG8_BAR; PG8_SCHED;
	s_add_i32 s54, s70, s56
	v_lshl_add_u64 v[240:241], v[240:241], 0, s[14:15]
	s_mov_b32 m0, s54
	ds_read_b128 v[192:195], v197 offset:49152
	ds_read_b128 v[208:211], v197 offset:50176
	ds_read_b128 v[212:215], v197 offset:51200
	ds_read_b128 v[216:219], v197 offset:52224
	ds_read_b128 v[224:227], v197 offset:53248
	ds_read_b128 v[228:231], v197 offset:54272
	ds_read_b128 v[232:235], v197 offset:55296
	ds_read_b128 v[236:239], v197 offset:56320
	global_load_lds_dwordx4 v[240:241], off
	s_add_i32 m0, s54, 0x2000
	s_add_u32 s52, s52, 0x40080
	v_lshl_add_u64 v[240:241], v[242:243], 0, s[14:15]
	s_addc_u32 s53, s53, 0
	s_add_i32 s54, s71, s56
	global_load_lds_dwordx4 v[240:241], off
	v_lshl_add_u64 v[240:241], s[52:53], 0, v[180:181]
	s_mov_b32 m0, s54
	s_nop 0
	global_load_lds_dwordx4 v[240:241], off
	v_lshl_add_u64 v[240:241], s[52:53], 0, v[160:161]
	s_add_i32 m0, s54, 0x2000
	s_nop 0
	global_load_lds_dwordx4 v[240:241], off
	v_lshl_add_u64 v[240:241], v[244:245], 0, s[14:15]
	s_mov_b32 m0, s79
	s_nop 0
	global_load_lds_dwordx4 v[240:241], off
	v_lshl_add_u64 v[240:241], v[246:247], 0, s[14:15]
	s_mov_b32 m0, s80
	s_nop 0
	global_load_lds_dwordx4 v[240:241], off
	s_waitcnt vmcnt(8)
	s_waitcnt lgkmcnt(0)
	s_barrier
	s_setprio 1
	s_waitcnt lgkmcnt(0)
	v_mfma_f32_16x16x32_bf16 v[64:67], v[100:103], v[192:195], v[64:67]
	v_mfma_f32_16x16x32_bf16 v[60:63], v[124:127], v[192:195], v[60:63]
	v_mfma_f32_16x16x32_bf16 v[48:51], v[100:103], v[212:215], v[48:51]
	v_mfma_f32_16x16x32_bf16 v[44:47], v[124:127], v[212:215], v[44:47]
	v_mfma_f32_16x16x32_bf16 v[32:35], v[100:103], v[224:227], v[32:35]
	v_mfma_f32_16x16x32_bf16 v[28:31], v[124:127], v[224:227], v[28:31]
	v_mfma_f32_16x16x32_bf16 v[16:19], v[100:103], v[232:235], v[16:19]
	v_mfma_f32_16x16x32_bf16 v[12:15], v[124:127], v[232:235], v[12:15]
	v_mfma_f32_16x16x32_bf16 v[64:67], v[112:115], v[208:211], v[64:67]
	v_mfma_f32_16x16x32_bf16 v[60:63], v[136:139], v[208:211], v[60:63]
	v_mfma_f32_16x16x32_bf16 v[48:51], v[112:115], v[216:219], v[48:51]
	v_mfma_f32_16x16x32_bf16 v[44:47], v[136:139], v[216:219], v[44:47]
	v_mfma_f32_16x16x32_bf16 v[32:35], v[112:115], v[228:231], v[32:35]
	v_mfma_f32_16x16x32_bf16 v[28:31], v[136:139], v[228:231], v[28:31]
	v_mfma_f32_16x16x32_bf16 v[16:19], v[112:115], v[236:239], v[16:19]
	v_mfma_f32_16x16x32_bf16 v[12:15], v[136:139], v[236:239], v[12:15]
	s_setprio 0
	s_setprio 1
	v_mfma_f32_16x16x32_bf16 v[56:59], v[148:151], v[192:195], v[56:59]
	v_mfma_f32_16x16x32_bf16 v[52:55], v[156:159], v[192:195], v[52:55]
	v_mfma_f32_16x16x32_bf16 v[40:43], v[148:151], v[212:215], v[40:43]
	v_mfma_f32_16x16x32_bf16 v[36:39], v[156:159], v[212:215], v[36:39]
	v_mfma_f32_16x16x32_bf16 v[24:27], v[148:151], v[224:227], v[24:27]
	v_mfma_f32_16x16x32_bf16 v[20:23], v[156:159], v[224:227], v[20:23]
	v_mfma_f32_16x16x32_bf16 v[8:11], v[148:151], v[232:235], v[8:11]
	v_mfma_f32_16x16x32_bf16 v[4:7], v[156:159], v[232:235], v[4:7]
	v_mfma_f32_16x16x32_bf16 v[56:59], v[152:155], v[208:211], v[56:59]
	v_mfma_f32_16x16x32_bf16 v[52:55], v[188:191], v[208:211], v[52:55]
	v_mfma_f32_16x16x32_bf16 v[40:43], v[152:155], v[216:219], v[40:43]
	v_mfma_f32_16x16x32_bf16 v[36:39], v[188:191], v[216:219], v[36:39]
	v_mfma_f32_16x16x32_bf16 v[24:27], v[152:155], v[228:231], v[24:27]
	v_mfma_f32_16x16x32_bf16 v[20:23], v[188:191], v[228:231], v[20:23]
	v_mfma_f32_16x16x32_bf16 v[8:11], v[152:155], v[236:239], v[8:11]
	v_mfma_f32_16x16x32_bf16 v[4:7], v[188:191], v[236:239], v[4:7]
	s_setprio 0
	s_add_i32 s89, s89, 2
	s_add_u32 s50, s50, 0x100
	s_addc_u32 s51, s51, 0
	s_add_u32 s84, s84, 0x100
	s_addc_u32 s85, s85, 0
	s_cmp_gt_u32 s89, 13
	s_barrier
	s_cbranch_scc0 .LBB0_698
	s_and_b64 vcc, exec, s[36:37]
	s_cbranch_vccz .LBB0_701
	s_barrier

; #define PG8_STAGE(bufoff, gbase, voff) do { _Pragma("unroll") for (int _i = 0; _i < 2; ++_i) \
;         __builtin_amdgcn_global_load_lds((const unsigned*)((const char*)(gbase) + (voff)[_i]), (PG8_LAS unsigned*)(lds + (bufoff) + ldsw + _i * 8192), 16, 0, 0); } while (0)
; #define PG8_LDA(dst, b, h) do { _Pragma("unroll") for (int m = 0; m < 4; ++m) _Pragma("unroll") for (int k = 0; k < 2; ++k) dst[m][k] = *(const PG8_LAS bf16x8*)(lds + PG8_SA(b, h) + aoff + m * 2048 + k * 1024); } while (0)
; #define PG8_LDB(dst, b, h) do { _Pragma("unroll") for (int n = 0; n < 2; ++n) _Pragma("unroll") for (int k = 0; k < 2; ++k) dst[n][k] = *(const PG8_LAS bf16x8*)(lds + PG8_SB(b, h) + boff + n * 2048 + k * 1024); } while (0)
; #define PG8_MMA(ai, bj, At, Bt) do { __builtin_amdgcn_s_setprio(1); _Pragma("unroll") for (int m = 0; m < 4; ++m) _Pragma("unroll") for (int n = 0; n < 2; ++n) _Pragma("unroll") for (int k = 0; k < 2; ++k) \
;         acc[ai][bj][m][n] = __builtin_amdgcn_mfma_f32_16x16x32_bf16(Bt[n][k], At[m][k], acc[ai][bj][m][n], 0, 0, 0); __builtin_amdgcn_s_setprio(0); } while (0)
; #define PG8_WAIT_V(n) asm volatile("s_waitcnt vmcnt(" #n ")" ::: "memory")
; #define PG8_WAIT_L(n) asm volatile("s_waitcnt lgkmcnt(" #n ")" ::: "memory")
; template <class Epi, class Sched, bool ALIGN_EPI = false, bool SP2 = false>
; __device__ __forceinline__ void gemm_phase(PG8_LAS unsigned char* lds, const Gemm g, const Sched& S, const Epi& E) {
;     ...
;             const bool last = (t == nt - 2);
;             const char* a1 = cA + (size_t)(t + 1) * kstep;
;             const char* a2 = last ? nA : cA + (size_t)(t + 2) * kstep; const char* b2 = last ? nB : cB + (size_t)(t + 2) * kstep;
;             const char* a3 = a2 + kstep; const char* b3 = b2 + kstep;
;             if (last && has_next) S.a_ready(nxt);
;             if constexpr (SP2) {
;             PG8_LDB(B0, 0, 0); PG8_LDB(B1, 0, 1); PG8_SCHED; PG8_LDA(At, 0, 0); PG8_STAGE(PG8_SA(1, 1), a1 + hstep, voffA);
;             PG8_WAIT_V(8); PG8_WAIT_L(0); PG8_BAR; PG8_MMA(0, 0, At, B0); PG8_MMA(0, 1, At, B1); PG8_BAR; PG8_SCHED;
;             PG8_LDA(At, 0, 1); PG8_STAGE(PG8_SB(0, 0), b2, voffB); PG8_STAGE(PG8_SB(0, 1), b2 + hstep, voffB); PG8_STAGE(PG8_SA(0, 0), a2, voffA);
;             PG8_WAIT_V(8); PG8_WAIT_L(0); PG8_BAR; PG8_MMA(1, 0, At, B0); PG8_MMA(1, 1, At, B1); PG8_BAR; PG8_SCHED;
.LBB0_790:
	s_add_u32 s41, s60, 0xfffc0080
	s_addc_u32 s70, s61, -1
	s_add_i32 s71, 0, 0x10000
	s_cmp_eq_u32 s40, 12
	s_cselect_b32 s85, s6, s70
	s_cselect_b32 s84, s7, s41
	s_cselect_b32 s79, s49, vcc_hi
	s_cselect_b32 s78, s51, vcc_lo
	s_add_i32 s41, 0, 0x14000
	v_add_u32_e32 v144, s71, v168
	v_add_u32_e32 v160, s41, v168
	ds_read_b128 v[132:135], v144
	ds_read_b128 v[136:139], v144 offset:1024
	ds_read_b128 v[140:143], v144 offset:2048
	ds_read_b128 v[144:147], v144 offset:3072
	ds_read_b128 v[148:151], v160
	ds_read_b128 v[152:155], v160 offset:1024
	ds_read_b128 v[156:159], v160 offset:2048
	ds_read_b128 v[160:163], v160 offset:3072
	v_lshl_add_u64 v[218:219], s[60:61], 0, v[186:187]
	s_add_i32 m0, s81, 0xc000
	ds_read_b128 v[190:193], v209
	ds_read_b128 v[194:197], v209 offset:1024
	ds_read_b128 v[210:213], v209 offset:2048
	ds_read_b128 v[214:217], v209 offset:3072
	ds_read_b128 v[224:227], v209 offset:4096
	ds_read_b128 v[228:231], v209 offset:5120
	ds_read_b128 v[232:235], v209 offset:6144
	ds_read_b128 v[236:239], v209 offset:7168
	global_load_lds_dwordx4 v[218:219], off
	v_lshl_add_u64 v[218:219], s[60:61], 0, v[188:189]
	s_add_i32 m0, s81, 0xe000
	s_nop 0
	global_load_lds_dwordx4 v[218:219], off
	s_waitcnt vmcnt(8)
	s_waitcnt lgkmcnt(0)
	s_barrier
	s_setprio 1
	s_waitcnt lgkmcnt(0)
	v_mfma_f32_16x16x32_bf16 v[128:131], v[132:135], v[190:193], v[128:131]
	v_mfma_f32_16x16x32_bf16 v[124:127], v[140:143], v[190:193], v[124:127]
	v_mfma_f32_16x16x32_bf16 v[112:115], v[132:135], v[210:213], v[112:115]
	v_mfma_f32_16x16x32_bf16 v[108:111], v[140:143], v[210:213], v[108:111]
	v_mfma_f32_16x16x32_bf16 v[96:99], v[132:135], v[224:227], v[96:99]
	v_mfma_f32_16x16x32_bf16 v[92:95], v[140:143], v[224:227], v[92:95]
	v_mfma_f32_16x16x32_bf16 v[80:83], v[132:135], v[232:235], v[80:83]
	v_mfma_f32_16x16x32_bf16 v[76:79], v[140:143], v[232:235], v[76:79]
	v_mfma_f32_16x16x32_bf16 v[128:131], v[136:139], v[194:197], v[128:131]
	v_mfma_f32_16x16x32_bf16 v[124:127], v[144:147], v[194:197], v[124:127]
	v_mfma_f32_16x16x32_bf16 v[112:115], v[136:139], v[214:217], v[112:115]
	v_mfma_f32_16x16x32_bf16 v[108:111], v[144:147], v[214:217], v[108:111]
	v_mfma_f32_16x16x32_bf16 v[96:99], v[136:139], v[228:231], v[96:99]
	v_mfma_f32_16x16x32_bf16 v[92:95], v[144:147], v[228:231], v[92:95]
	v_mfma_f32_16x16x32_bf16 v[80:83], v[136:139], v[236:239], v[80:83]
	v_mfma_f32_16x16x32_bf16 v[76:79], v[144:147], v[236:239], v[76:79]
	s_setprio 0
	s_setprio 1
	v_mfma_f32_16x16x32_bf16 v[120:123], v[148:151], v[190:193], v[120:123]
	v_mfma_f32_16x16x32_bf16 v[116:119], v[156:159], v[190:193], v[116:119]
	v_mfma_f32_16x16x32_bf16 v[104:107], v[148:151], v[210:213], v[104:107]
	v_mfma_f32_16x16x32_bf16 v[100:103], v[156:159], v[210:213], v[100:103]
	v_mfma_f32_16x16x32_bf16 v[88:91], v[148:151], v[224:227], v[88:91]
	v_mfma_f32_16x16x32_bf16 v[84:87], v[156:159], v[224:227], v[84:87]
	v_mfma_f32_16x16x32_bf16 v[72:75], v[148:151], v[232:235], v[72:75]
	v_mfma_f32_16x16x32_bf16 v[68:71], v[156:159], v[232:235], v[68:71]
	v_mfma_f32_16x16x32_bf16 v[120:123], v[152:155], v[194:197], v[120:123]
	v_mfma_f32_16x16x32_bf16 v[116:119], v[160:163], v[194:197], v[116:119]
	v_mfma_f32_16x16x32_bf16 v[104:107], v[152:155], v[214:217], v[104:107]
	v_mfma_f32_16x16x32_bf16 v[100:103], v[160:163], v[214:217], v[100:103]
	v_mfma_f32_16x16x32_bf16 v[88:91], v[152:155], v[228:231], v[88:91]
	v_mfma_f32_16x16x32_bf16 v[84:87], v[160:163], v[228:231], v[84:87]
	v_mfma_f32_16x16x32_bf16 v[72:75], v[152:155], v[236:239], v[72:75]
	v_mfma_f32_16x16x32_bf16 v[68:71], v[160:163], v[236:239], v[68:71]
	s_setprio 0
	s_barrier
	s_add_i32 s70, s71, s80
	v_lshl_add_u64 v[218:219], s[78:79], 0, v[2:3]
	s_mov_b32 m0, s70
	ds_read_b128 v[190:193], v209 offset:16384
	ds_read_b128 v[194:197], v209 offset:17408
	ds_read_b128 v[210:213], v209 offset:18432
	ds_read_b128 v[214:217], v209 offset:19456
	ds_read_b128 v[224:227], v209 offset:20480
	ds_read_b128 v[228:231], v209 offset:21504
	ds_read_b128 v[232:235], v209 offset:22528
	ds_read_b128 v[236:239], v209 offset:23552
	global_load_lds_dwordx4 v[218:219], off
	s_add_i32 m0, s70, 0x2000
	s_add_u32 s70, s78, 0x40000
	v_lshl_add_u64 v[240:241], s[78:79], 0, v[180:181]
	s_addc_u32 s71, s79, 0
	s_add_i32 s41, s41, s80
	global_load_lds_dwordx4 v[240:241], off
	v_lshl_add_u64 v[242:243], s[70:71], 0, v[2:3]
	s_mov_b32 m0, s41
	v_lshl_add_u64 v[244:245], s[84:85], 0, v[182:183]
	global_load_lds_dwordx4 v[242:243], off
	v_lshl_add_u64 v[242:243], s[70:71], 0, v[180:181]
	s_add_i32 m0, s41, 0x2000
	s_nop 0
	global_load_lds_dwordx4 v[242:243], off
	v_lshl_add_u64 v[242:243], s[84:85], 0, v[184:185]
	s_mov_b32 m0, s81
	s_nop 0
	global_load_lds_dwordx4 v[242:243], off
	s_mov_b32 m0, s82
	s_nop 0
	global_load_lds_dwordx4 v[244:245], off
	s_waitcnt vmcnt(8)
	s_waitcnt lgkmcnt(0)
	s_barrier
; #define PG8_STAGE(bufoff, gbase, voff) do { _Pragma("unroll") for (int _i = 0; _i < 2; ++_i) \
;         __builtin_amdgcn_global_load_lds((const unsigned*)((const char*)(gbase) + (voff)[_i]), (PG8_LAS unsigned*)(lds + (bufoff) + ldsw + _i * 8192), 16, 0, 0); } while (0)
; #define PG8_LDA(dst, b, h) do { _Pragma("unroll") for (int m = 0; m < 4; ++m) _Pragma("unroll") for (int k = 0; k < 2; ++k) dst[m][k] = *(const PG8_LAS bf16x8*)(lds + PG8_SA(b, h) + aoff + m * 2048 + k * 1024); } while (0)
; #define PG8_LDB(dst, b, h) do { _Pragma("unroll") for (int n = 0; n < 2; ++n) _Pragma("unroll") for (int k = 0; k < 2; ++k) dst[n][k] = *(const PG8_LAS bf16x8*)(lds + PG8_SB(b, h) + boff + n * 2048 + k * 1024); } while (0)
; #define PG8_MMA(ai, bj, At, Bt) do { __builtin_amdgcn_s_setprio(1); _Pragma("unroll") for (int m = 0; m < 4; ++m) _Pragma("unroll") for (int n = 0; n < 2; ++n) _Pragma("unroll") for (int k = 0; k < 2; ++k) \
;         acc[ai][bj][m][n] = __builtin_amdgcn_mfma_f32_16x16x32_bf16(Bt[n][k], At[m][k], acc[ai][bj][m][n], 0, 0, 0); __builtin_amdgcn_s_setprio(0); } while (0)
; #define PG8_WAIT_V(n) asm volatile("s_waitcnt vmcnt(" #n ")" ::: "memory")
; #define PG8_WAIT_L(n) asm volatile("s_waitcnt lgkmcnt(" #n ")" ::: "memory")
; #define PG8_BAR __builtin_amdgcn_s_barrier()
; #define PG8_SCHED __builtin_amdgcn_sched_barrier(0)
; template <class Epi, class Sched, bool ALIGN_EPI = false, bool SP2 = false>
; __device__ __forceinline__ void gemm_phase(PG8_LAS unsigned char* lds, const Gemm g, const Sched& S, const Epi& E) {
;     ...
;             PG8_WAIT_V(8); PG8_WAIT_L(0); PG8_BAR; PG8_MMA(1, 0, At, B0); PG8_MMA(1, 1, At, B1); PG8_BAR; PG8_SCHED;
;             PG8_LDB(B0, 1, 0); PG8_LDB(B1, 1, 1); PG8_SCHED; PG8_LDA(At, 1, 0); PG8_STAGE(PG8_SA(0, 1), a2 + hstep, voffA);
;             PG8_WAIT_V(8); PG8_WAIT_L(0); PG8_BAR; PG8_MMA(0, 0, At, B0); PG8_MMA(0, 1, At, B1); PG8_BAR; PG8_SCHED;
	s_setprio 1
	s_waitcnt lgkmcnt(0)
	v_mfma_f32_16x16x32_bf16 v[64:67], v[132:135], v[190:193], v[64:67]
	v_mfma_f32_16x16x32_bf16 v[60:63], v[140:143], v[190:193], v[60:63]
	v_mfma_f32_16x16x32_bf16 v[48:51], v[132:135], v[210:213], v[48:51]
	v_mfma_f32_16x16x32_bf16 v[44:47], v[140:143], v[210:213], v[44:47]
	v_mfma_f32_16x16x32_bf16 v[32:35], v[132:135], v[224:227], v[32:35]
	v_mfma_f32_16x16x32_bf16 v[28:31], v[140:143], v[224:227], v[28:31]
	v_mfma_f32_16x16x32_bf16 v[16:19], v[132:135], v[232:235], v[16:19]
	v_mfma_f32_16x16x32_bf16 v[12:15], v[140:143], v[232:235], v[12:15]
	v_mfma_f32_16x16x32_bf16 v[64:67], v[136:139], v[194:197], v[64:67]
	v_mfma_f32_16x16x32_bf16 v[60:63], v[144:147], v[194:197], v[60:63]
	v_mfma_f32_16x16x32_bf16 v[48:51], v[136:139], v[214:217], v[48:51]
	v_mfma_f32_16x16x32_bf16 v[44:47], v[144:147], v[214:217], v[44:47]
	v_mfma_f32_16x16x32_bf16 v[32:35], v[136:139], v[228:231], v[32:35]
	v_mfma_f32_16x16x32_bf16 v[28:31], v[144:147], v[228:231], v[28:31]
	v_mfma_f32_16x16x32_bf16 v[16:19], v[136:139], v[236:239], v[16:19]
	v_mfma_f32_16x16x32_bf16 v[12:15], v[144:147], v[236:239], v[12:15]
	s_setprio 0
	s_setprio 1
	v_mfma_f32_16x16x32_bf16 v[56:59], v[148:151], v[190:193], v[56:59]
	v_mfma_f32_16x16x32_bf16 v[52:55], v[156:159], v[190:193], v[52:55]
	v_mfma_f32_16x16x32_bf16 v[40:43], v[148:151], v[210:213], v[40:43]
	v_mfma_f32_16x16x32_bf16 v[36:39], v[156:159], v[210:213], v[36:39]
	v_mfma_f32_16x16x32_bf16 v[24:27], v[148:151], v[224:227], v[24:27]
	v_mfma_f32_16x16x32_bf16 v[20:23], v[156:159], v[224:227], v[20:23]
	v_mfma_f32_16x16x32_bf16 v[8:11], v[148:151], v[232:235], v[8:11]
	v_mfma_f32_16x16x32_bf16 v[4:7], v[156:159], v[232:235], v[4:7]
	v_mfma_f32_16x16x32_bf16 v[56:59], v[152:155], v[194:197], v[56:59]
	v_mfma_f32_16x16x32_bf16 v[52:55], v[160:163], v[194:197], v[52:55]
	v_mfma_f32_16x16x32_bf16 v[40:43], v[152:155], v[214:217], v[40:43]
	v_mfma_f32_16x16x32_bf16 v[36:39], v[160:163], v[214:217], v[36:39]
	v_mfma_f32_16x16x32_bf16 v[24:27], v[152:155], v[228:231], v[24:27]
	v_mfma_f32_16x16x32_bf16 v[20:23], v[160:163], v[228:231], v[20:23]
	v_mfma_f32_16x16x32_bf16 v[8:11], v[152:155], v[236:239], v[8:11]
	v_mfma_f32_16x16x32_bf16 v[4:7], v[160:163], v[236:239], v[4:7]
	s_setprio 0
	s_barrier
	s_add_i32 s41, 0, 0x18000
	s_add_i32 s72, 0, 0x1c000
	v_add_u32_e32 v144, s41, v168
	v_add_u32_e32 v160, s72, v168
	ds_read_b128 v[132:135], v144
	ds_read_b128 v[136:139], v144 offset:1024
	ds_read_b128 v[140:143], v144 offset:2048
	ds_read_b128 v[144:147], v144 offset:3072
	ds_read_b128 v[148:151], v160
	ds_read_b128 v[152:155], v160 offset:1024
	ds_read_b128 v[156:159], v160 offset:2048
	ds_read_b128 v[160:163], v160 offset:3072
	s_add_u32 s70, s84, 0x40000
	s_addc_u32 s71, s85, 0
	s_mov_b32 m0, s83
	v_lshl_add_u64 v[246:247], s[70:71], 0, v[184:185]
	ds_read_b128 v[190:193], v209 offset:32768
	ds_read_b128 v[194:197], v209 offset:33792
	ds_read_b128 v[210:213], v209 offset:34816
	ds_read_b128 v[214:217], v209 offset:35840
	ds_read_b128 v[224:227], v209 offset:36864
	ds_read_b128 v[228:231], v209 offset:37888
	ds_read_b128 v[232:235], v209 offset:38912
	ds_read_b128 v[236:239], v209 offset:39936
	global_load_lds_dwordx4 v[246:247], off
	v_lshl_add_u64 v[246:247], s[70:71], 0, v[182:183]
	s_mov_b32 m0, s89
	s_nop 0
	global_load_lds_dwordx4 v[246:247], off
	s_waitcnt vmcnt(8)
	s_waitcnt lgkmcnt(0)
	s_barrier
	s_setprio 1
	s_waitcnt lgkmcnt(0)
	v_mfma_f32_16x16x32_bf16 v[128:131], v[132:135], v[190:193], v[128:131]
	v_mfma_f32_16x16x32_bf16 v[124:127], v[140:143], v[190:193], v[124:127]
	v_mfma_f32_16x16x32_bf16 v[112:115], v[132:135], v[210:213], v[112:115]
	v_mfma_f32_16x16x32_bf16 v[108:111], v[140:143], v[210:213], v[108:111]
	v_mfma_f32_16x16x32_bf16 v[96:99], v[132:135], v[224:227], v[96:99]
	v_mfma_f32_16x16x32_bf16 v[92:95], v[140:143], v[224:227], v[92:95]
	v_mfma_f32_16x16x32_bf16 v[80:83], v[132:135], v[232:235], v[80:83]
	v_mfma_f32_16x16x32_bf16 v[76:79], v[140:143], v[232:235], v[76:79]
	v_mfma_f32_16x16x32_bf16 v[128:131], v[136:139], v[194:197], v[128:131]
	v_mfma_f32_16x16x32_bf16 v[124:127], v[144:147], v[194:197], v[124:127]
	v_mfma_f32_16x16x32_bf16 v[112:115], v[136:139], v[214:217], v[112:115]
	v_mfma_f32_16x16x32_bf16 v[108:111], v[144:147], v[214:217], v[108:111]
	v_mfma_f32_16x16x32_bf16 v[96:99], v[136:139], v[228:231], v[96:99]
	v_mfma_f32_16x16x32_bf16 v[92:95], v[144:147], v[228:231], v[92:95]
	v_mfma_f32_16x16x32_bf16 v[80:83], v[136:139], v[236:239], v[80:83]
	v_mfma_f32_16x16x32_bf16 v[76:79], v[144:147], v[236:239], v[76:79]
	s_setprio 0
	s_setprio 1
	v_mfma_f32_16x16x32_bf16 v[120:123], v[148:151], v[190:193], v[120:123]
	v_mfma_f32_16x16x32_bf16 v[116:119], v[156:159], v[190:193], v[116:119]
	v_mfma_f32_16x16x32_bf16 v[104:107], v[148:151], v[210:213], v[104:107]
	v_mfma_f32_16x16x32_bf16 v[100:103], v[156:159], v[210:213], v[100:103]
	v_mfma_f32_16x16x32_bf16 v[88:91], v[148:151], v[224:227], v[88:91]
	v_mfma_f32_16x16x32_bf16 v[84:87], v[156:159], v[224:227], v[84:87]
	v_mfma_f32_16x16x32_bf16 v[72:75], v[148:151], v[232:235], v[72:75]
	v_mfma_f32_16x16x32_bf16 v[68:71], v[156:159], v[232:235], v[68:71]
	v_mfma_f32_16x16x32_bf16 v[120:123], v[152:155], v[194:197], v[120:123]
	v_mfma_f32_16x16x32_bf16 v[116:119], v[160:163], v[194:197], v[116:119]
	v_mfma_f32_16x16x32_bf16 v[104:107], v[152:155], v[214:217], v[104:107]
	v_mfma_f32_16x16x32_bf16 v[100:103], v[160:163], v[214:217], v[100:103]
	v_mfma_f32_16x16x32_bf16 v[88:91], v[152:155], v[228:231], v[88:91]
	v_mfma_f32_16x16x32_bf16 v[84:87], v[160:163], v[228:231], v[84:87]
	v_mfma_f32_16x16x32_bf16 v[72:75], v[152:155], v[236:239], v[72:75]
	v_mfma_f32_16x16x32_bf16 v[68:71], v[160:163], v[236:239], v[68:71]
	s_setprio 0
	s_barrier
; #define PG8_STAGE(bufoff, gbase, voff) do { _Pragma("unroll") for (int _i = 0; _i < 2; ++_i) \
;         __builtin_amdgcn_global_load_lds((const unsigned*)((const char*)(gbase) + (voff)[_i]), (PG8_LAS unsigned*)(lds + (bufoff) + ldsw + _i * 8192), 16, 0, 0); } while (0)
; #define PG8_LDA(dst, b, h) do { _Pragma("unroll") for (int m = 0; m < 4; ++m) _Pragma("unroll") for (int k = 0; k < 2; ++k) dst[m][k] = *(const PG8_LAS bf16x8*)(lds + PG8_SA(b, h) + aoff + m * 2048 + k * 1024); } while (0)
; #define PG8_MMA(ai, bj, At, Bt) do { __builtin_amdgcn_s_setprio(1); _Pragma("unroll") for (int m = 0; m < 4; ++m) _Pragma("unroll") for (int n = 0; n < 2; ++n) _Pragma("unroll") for (int k = 0; k < 2; ++k) \
;         acc[ai][bj][m][n] = __builtin_amdgcn_mfma_f32_16x16x32_bf16(Bt[n][k], At[m][k], acc[ai][bj][m][n], 0, 0, 0); __builtin_amdgcn_s_setprio(0); } while (0)
; #define PG8_WAIT_V(n) asm volatile("s_waitcnt vmcnt(" #n ")" ::: "memory")
; #define PG8_WAIT_L(n) asm volatile("s_waitcnt lgkmcnt(" #n ")" ::: "memory")
; #define PG8_BAR __builtin_amdgcn_s_barrier()
; #define PG8_SCHED __builtin_amdgcn_sched_barrier(0)
; template <class Epi, class Sched, bool ALIGN_EPI = false, bool SP2 = false>
; __device__ __forceinline__ void gemm_phase(PG8_LAS unsigned char* lds, const Gemm g, const Sched& S, const Epi& E) {
;     ...
;         for (int t = 0; t < nt; t += 2) {
;             const bool last = (t == nt - 2);
;     ...
;             PG8_LDA(At, 1, 1); PG8_STAGE(PG8_SB(1, 0), b3, voffB); PG8_STAGE(PG8_SB(1, 1), b3 + hstep, voffB); PG8_STAGE(PG8_SA(1, 0), a3, voffA);
;             PG8_WAIT_V(8); PG8_WAIT_L(0); PG8_BAR; PG8_MMA(1, 0, At, B0); PG8_MMA(1, 1, At, B1); PG8_BAR; PG8_SCHED;
	s_add_i32 s41, s41, s80
	v_lshl_add_u64 v[218:219], v[218:219], 0, s[14:15]
	s_mov_b32 m0, s41
	ds_read_b128 v[190:193], v209 offset:49152
	ds_read_b128 v[194:197], v209 offset:50176
	ds_read_b128 v[210:213], v209 offset:51200
	ds_read_b128 v[214:217], v209 offset:52224
	ds_read_b128 v[224:227], v209 offset:53248
	ds_read_b128 v[228:231], v209 offset:54272
	ds_read_b128 v[232:235], v209 offset:55296
	ds_read_b128 v[236:239], v209 offset:56320
	global_load_lds_dwordx4 v[218:219], off
	s_add_i32 m0, s41, 0x2000
	s_add_u32 s70, s78, 0x40080
	v_lshl_add_u64 v[218:219], v[240:241], 0, s[14:15]
	s_addc_u32 s71, s79, 0
	s_add_i32 s41, s72, s80
	global_load_lds_dwordx4 v[218:219], off
	v_lshl_add_u64 v[218:219], s[70:71], 0, v[2:3]
	s_mov_b32 m0, s41
	s_nop 0
	global_load_lds_dwordx4 v[218:219], off
	v_lshl_add_u64 v[218:219], s[70:71], 0, v[180:181]
	s_add_i32 m0, s41, 0x2000
	s_nop 0
	global_load_lds_dwordx4 v[218:219], off
	v_lshl_add_u64 v[218:219], v[242:243], 0, s[14:15]
	s_mov_b32 m0, s28
	s_nop 0
	global_load_lds_dwordx4 v[218:219], off
	v_lshl_add_u64 v[218:219], v[244:245], 0, s[14:15]
	s_mov_b32 m0, s29
	s_nop 0
	global_load_lds_dwordx4 v[218:219], off
	s_waitcnt vmcnt(8)
	s_waitcnt lgkmcnt(0)
	s_barrier
	s_setprio 1
	s_waitcnt lgkmcnt(0)
	v_mfma_f32_16x16x32_bf16 v[64:67], v[132:135], v[190:193], v[64:67]
	v_mfma_f32_16x16x32_bf16 v[60:63], v[140:143], v[190:193], v[60:63]
	v_mfma_f32_16x16x32_bf16 v[48:51], v[132:135], v[210:213], v[48:51]
	v_mfma_f32_16x16x32_bf16 v[44:47], v[140:143], v[210:213], v[44:47]
	v_mfma_f32_16x16x32_bf16 v[32:35], v[132:135], v[224:227], v[32:35]
	v_mfma_f32_16x16x32_bf16 v[28:31], v[140:143], v[224:227], v[28:31]
	v_mfma_f32_16x16x32_bf16 v[16:19], v[132:135], v[232:235], v[16:19]
	v_mfma_f32_16x16x32_bf16 v[12:15], v[140:143], v[232:235], v[12:15]
	v_mfma_f32_16x16x32_bf16 v[64:67], v[136:139], v[194:197], v[64:67]
	v_mfma_f32_16x16x32_bf16 v[60:63], v[144:147], v[194:197], v[60:63]
	v_mfma_f32_16x16x32_bf16 v[48:51], v[136:139], v[214:217], v[48:51]
	v_mfma_f32_16x16x32_bf16 v[44:47], v[144:147], v[214:217], v[44:47]
	v_mfma_f32_16x16x32_bf16 v[32:35], v[136:139], v[228:231], v[32:35]
	v_mfma_f32_16x16x32_bf16 v[28:31], v[144:147], v[228:231], v[28:31]
	v_mfma_f32_16x16x32_bf16 v[16:19], v[136:139], v[236:239], v[16:19]
	v_mfma_f32_16x16x32_bf16 v[12:15], v[144:147], v[236:239], v[12:15]
	s_setprio 0
	s_setprio 1
	v_mfma_f32_16x16x32_bf16 v[56:59], v[148:151], v[190:193], v[56:59]
	v_mfma_f32_16x16x32_bf16 v[52:55], v[156:159], v[190:193], v[52:55]
	v_mfma_f32_16x16x32_bf16 v[40:43], v[148:151], v[210:213], v[40:43]
	v_mfma_f32_16x16x32_bf16 v[36:39], v[156:159], v[210:213], v[36:39]
	v_mfma_f32_16x16x32_bf16 v[24:27], v[148:151], v[224:227], v[24:27]
	v_mfma_f32_16x16x32_bf16 v[20:23], v[156:159], v[224:227], v[20:23]
	v_mfma_f32_16x16x32_bf16 v[8:11], v[148:151], v[232:235], v[8:11]
	v_mfma_f32_16x16x32_bf16 v[4:7], v[156:159], v[232:235], v[4:7]
	v_mfma_f32_16x16x32_bf16 v[56:59], v[152:155], v[194:197], v[56:59]
	v_mfma_f32_16x16x32_bf16 v[52:55], v[160:163], v[194:197], v[52:55]
	v_mfma_f32_16x16x32_bf16 v[40:43], v[152:155], v[214:217], v[40:43]
	v_mfma_f32_16x16x32_bf16 v[36:39], v[160:163], v[214:217], v[36:39]
	v_mfma_f32_16x16x32_bf16 v[24:27], v[152:155], v[228:231], v[24:27]
	v_mfma_f32_16x16x32_bf16 v[20:23], v[160:163], v[228:231], v[20:23]
	v_mfma_f32_16x16x32_bf16 v[8:11], v[152:155], v[236:239], v[8:11]
	v_mfma_f32_16x16x32_bf16 v[4:7], v[160:163], v[236:239], v[4:7]
	s_setprio 0
	s_add_i32 s40, s40, 2
	s_add_u32 s60, s60, 0x100
	s_addc_u32 s61, s61, 0
	s_add_u32 vcc_lo, vcc_lo, 0x100
	s_addc_u32 vcc_hi, vcc_hi, 0
	s_cmp_gt_u32 s40, 13
	s_barrier
	s_cbranch_scc0 .LBB0_790
	s_and_b64 vcc, exec, s[46:47]
	s_cbranch_vccz .LBB0_793
	s_barrier

; #define PG8_STAGE(bufoff, gbase, voff) do { _Pragma("unroll") for (int _i = 0; _i < 2; ++_i) \
;         __builtin_amdgcn_global_load_lds((const unsigned*)((const char*)(gbase) + (voff)[_i]), (PG8_LAS unsigned*)(lds + (bufoff) + ldsw + _i * 8192), 16, 0, 0); } while (0)
; #define PG8_LDA(dst, b, h) do { _Pragma("unroll") for (int m = 0; m < 4; ++m) _Pragma("unroll") for (int k = 0; k < 2; ++k) dst[m][k] = *(const PG8_LAS bf16x8*)(lds + PG8_SA(b, h) + aoff + m * 2048 + k * 1024); } while (0)
; #define PG8_LDB(dst, b, h) do { _Pragma("unroll") for (int n = 0; n < 2; ++n) _Pragma("unroll") for (int k = 0; k < 2; ++k) dst[n][k] = *(const PG8_LAS bf16x8*)(lds + PG8_SB(b, h) + boff + n * 2048 + k * 1024); } while (0)
; #define PG8_MMA(ai, bj, At, Bt) do { __builtin_amdgcn_s_setprio(1); _Pragma("unroll") for (int m = 0; m < 4; ++m) _Pragma("unroll") for (int n = 0; n < 2; ++n) _Pragma("unroll") for (int k = 0; k < 2; ++k) \
;         acc[ai][bj][m][n] = __builtin_amdgcn_mfma_f32_16x16x32_bf16(Bt[n][k], At[m][k], acc[ai][bj][m][n], 0, 0, 0); __builtin_amdgcn_s_setprio(0); } while (0)
; #define PG8_WAIT_V(n) asm volatile("s_waitcnt vmcnt(" #n ")" ::: "memory")
; #define PG8_WAIT_L(n) asm volatile("s_waitcnt lgkmcnt(" #n ")" ::: "memory")
; template <class Epi, class Sched, bool ALIGN_EPI = false, bool SP2 = false>
; __device__ __forceinline__ void gemm_phase(PG8_LAS unsigned char* lds, const Gemm g, const Sched& S, const Epi& E) {
;     ...
;             const bool last = (t == nt - 2);
;             const char* a1 = cA + (size_t)(t + 1) * kstep;
;             const char* a2 = last ? nA : cA + (size_t)(t + 2) * kstep; const char* b2 = last ? nB : cB + (size_t)(t + 2) * kstep;
;             const char* a3 = a2 + kstep; const char* b3 = b2 + kstep;
;             if (last && has_next) S.a_ready(nxt);
;             if constexpr (SP2) {
;             PG8_LDB(B0, 0, 0); PG8_LDB(B1, 0, 1); PG8_SCHED; PG8_LDA(At, 0, 0); PG8_STAGE(PG8_SA(1, 1), a1 + hstep, voffA);
;             PG8_WAIT_V(8); PG8_WAIT_L(0); PG8_BAR; PG8_MMA(0, 0, At, B0); PG8_MMA(0, 1, At, B1); PG8_BAR; PG8_SCHED;
;             PG8_LDA(At, 0, 1); PG8_STAGE(PG8_SB(0, 0), b2, voffB); PG8_STAGE(PG8_SB(0, 1), b2 + hstep, voffB); PG8_STAGE(PG8_SA(0, 0), a2, voffA);
;             PG8_WAIT_V(8); PG8_WAIT_L(0); PG8_BAR; PG8_MMA(1, 0, At, B0); PG8_MMA(1, 1, At, B1); PG8_BAR; PG8_SCHED;
.LBB0_866:
	s_add_u32 s54, s52, 0xfffc0080
	s_addc_u32 s55, s53, -1
	s_add_i32 s70, 0, 0x10000
	s_cmp_eq_u32 s89, 12
	s_cselect_b32 s61, s6, s55
	s_cselect_b32 s60, s7, s54
	v_add_u32_e32 v142, s70, v145
	s_cselect_b32 s55, s45, s85
	s_cselect_b32 s54, s47, s84
	s_add_i32 s72, 0, 0x14000
	ds_read_b128 v[148:151], v142
	ds_read_b128 v[152:155], v142 offset:1024
	ds_read_b128 v[156:159], v142 offset:2048
	ds_read_b128 v[160:163], v142 offset:3072
	v_add_u32_e32 v142, s72, v145
	ds_read_b128 v[180:183], v142
	ds_read_b128 v[184:187], v142 offset:1024
	ds_read_b128 v[188:191], v142 offset:2048
	ds_read_b128 v[192:195], v142 offset:3072
	v_lshl_add_u64 v[142:143], s[52:53], 0, v[138:139]
	s_add_i32 m0, s57, 0xc000
	ds_read_b128 v[208:211], v147
	ds_read_b128 v[212:215], v147 offset:1024
	ds_read_b128 v[216:219], v147 offset:2048
	ds_read_b128 v[224:227], v147 offset:3072
	ds_read_b128 v[228:231], v147 offset:4096
	ds_read_b128 v[232:235], v147 offset:5120
	ds_read_b128 v[236:239], v147 offset:6144
	ds_read_b128 v[240:243], v147 offset:7168
	global_load_lds_dwordx4 v[142:143], off
	v_lshl_add_u64 v[142:143], s[52:53], 0, v[140:141]
	s_add_i32 m0, s57, 0xe000
	s_nop 0
	global_load_lds_dwordx4 v[142:143], off
	s_waitcnt vmcnt(8)
	s_waitcnt lgkmcnt(0)
	s_barrier
	s_setprio 1
	s_waitcnt lgkmcnt(0)
	v_mfma_f32_16x16x32_bf16 v[128:131], v[148:151], v[208:211], v[128:131]
	v_mfma_f32_16x16x32_bf16 v[124:127], v[156:159], v[208:211], v[124:127]
	v_mfma_f32_16x16x32_bf16 v[120:123], v[148:151], v[216:219], v[120:123]
	v_mfma_f32_16x16x32_bf16 v[112:115], v[156:159], v[216:219], v[112:115]
	v_mfma_f32_16x16x32_bf16 v[104:107], v[148:151], v[228:231], v[104:107]
	v_mfma_f32_16x16x32_bf16 v[96:99], v[156:159], v[228:231], v[96:99]
	v_mfma_f32_16x16x32_bf16 v[88:91], v[148:151], v[236:239], v[88:91]
	v_mfma_f32_16x16x32_bf16 v[80:83], v[156:159], v[236:239], v[80:83]
	v_mfma_f32_16x16x32_bf16 v[128:131], v[152:155], v[212:215], v[128:131]
	v_mfma_f32_16x16x32_bf16 v[124:127], v[160:163], v[212:215], v[124:127]
	v_mfma_f32_16x16x32_bf16 v[120:123], v[152:155], v[224:227], v[120:123]
	v_mfma_f32_16x16x32_bf16 v[112:115], v[160:163], v[224:227], v[112:115]
	v_mfma_f32_16x16x32_bf16 v[104:107], v[152:155], v[232:235], v[104:107]
	v_mfma_f32_16x16x32_bf16 v[96:99], v[160:163], v[232:235], v[96:99]
	v_mfma_f32_16x16x32_bf16 v[88:91], v[152:155], v[240:243], v[88:91]
	v_mfma_f32_16x16x32_bf16 v[80:83], v[160:163], v[240:243], v[80:83]
	s_setprio 0
	s_setprio 1
	v_mfma_f32_16x16x32_bf16 v[116:119], v[180:183], v[208:211], v[116:119]
	v_mfma_f32_16x16x32_bf16 v[108:111], v[188:191], v[208:211], v[108:111]
	v_mfma_f32_16x16x32_bf16 v[100:103], v[180:183], v[216:219], v[100:103]
	v_mfma_f32_16x16x32_bf16 v[92:95], v[188:191], v[216:219], v[92:95]
	v_mfma_f32_16x16x32_bf16 v[84:87], v[180:183], v[228:231], v[84:87]
	v_mfma_f32_16x16x32_bf16 v[76:79], v[188:191], v[228:231], v[76:79]
	v_mfma_f32_16x16x32_bf16 v[72:75], v[180:183], v[236:239], v[72:75]
	v_mfma_f32_16x16x32_bf16 v[68:71], v[188:191], v[236:239], v[68:71]
	v_mfma_f32_16x16x32_bf16 v[116:119], v[184:187], v[212:215], v[116:119]
	v_mfma_f32_16x16x32_bf16 v[108:111], v[192:195], v[212:215], v[108:111]
	v_mfma_f32_16x16x32_bf16 v[100:103], v[184:187], v[224:227], v[100:103]
	v_mfma_f32_16x16x32_bf16 v[92:95], v[192:195], v[224:227], v[92:95]
	v_mfma_f32_16x16x32_bf16 v[84:87], v[184:187], v[232:235], v[84:87]
	v_mfma_f32_16x16x32_bf16 v[76:79], v[192:195], v[232:235], v[76:79]
	v_mfma_f32_16x16x32_bf16 v[72:75], v[184:187], v[240:243], v[72:75]
	v_mfma_f32_16x16x32_bf16 v[68:71], v[192:195], v[240:243], v[68:71]
	s_setprio 0
	s_barrier
	s_add_i32 s70, s70, s26
	v_lshl_add_u64 v[142:143], s[54:55], 0, v[2:3]
	s_mov_b32 m0, s70
	ds_read_b128 v[208:211], v147 offset:16384
	ds_read_b128 v[212:215], v147 offset:17408
	ds_read_b128 v[216:219], v147 offset:18432
	ds_read_b128 v[224:227], v147 offset:19456
	ds_read_b128 v[228:231], v147 offset:20480
	ds_read_b128 v[232:235], v147 offset:21504
	ds_read_b128 v[236:239], v147 offset:22528
	ds_read_b128 v[240:243], v147 offset:23552
	global_load_lds_dwordx4 v[142:143], off
	s_add_i32 m0, s70, 0x2000
	s_add_u32 s70, s54, 0x40000
	v_lshl_add_u64 v[170:171], s[54:55], 0, v[132:133]
	s_addc_u32 s71, s55, 0
	s_add_i32 s72, s72, s26
	global_load_lds_dwordx4 v[170:171], off
	v_lshl_add_u64 v[196:197], s[70:71], 0, v[2:3]
	s_mov_b32 m0, s72
	v_lshl_add_u64 v[244:245], s[60:61], 0, v[134:135]
	global_load_lds_dwordx4 v[196:197], off
	v_lshl_add_u64 v[196:197], s[70:71], 0, v[132:133]
	s_add_i32 m0, s72, 0x2000
	s_nop 0
	global_load_lds_dwordx4 v[196:197], off
	v_lshl_add_u64 v[196:197], s[60:61], 0, v[136:137]
	s_mov_b32 m0, s57
	s_nop 0
	global_load_lds_dwordx4 v[196:197], off
	s_mov_b32 m0, s66
	s_nop 0
	global_load_lds_dwordx4 v[244:245], off
	s_waitcnt vmcnt(8)
	s_waitcnt lgkmcnt(0)
	s_barrier
; #define PG8_STAGE(bufoff, gbase, voff) do { _Pragma("unroll") for (int _i = 0; _i < 2; ++_i) \
;         __builtin_amdgcn_global_load_lds((const unsigned*)((const char*)(gbase) + (voff)[_i]), (PG8_LAS unsigned*)(lds + (bufoff) + ldsw + _i * 8192), 16, 0, 0); } while (0)
; #define PG8_LDA(dst, b, h) do { _Pragma("unroll") for (int m = 0; m < 4; ++m) _Pragma("unroll") for (int k = 0; k < 2; ++k) dst[m][k] = *(const PG8_LAS bf16x8*)(lds + PG8_SA(b, h) + aoff + m * 2048 + k * 1024); } while (0)
; #define PG8_LDB(dst, b, h) do { _Pragma("unroll") for (int n = 0; n < 2; ++n) _Pragma("unroll") for (int k = 0; k < 2; ++k) dst[n][k] = *(const PG8_LAS bf16x8*)(lds + PG8_SB(b, h) + boff + n * 2048 + k * 1024); } while (0)
; #define PG8_MMA(ai, bj, At, Bt) do { __builtin_amdgcn_s_setprio(1); _Pragma("unroll") for (int m = 0; m < 4; ++m) _Pragma("unroll") for (int n = 0; n < 2; ++n) _Pragma("unroll") for (int k = 0; k < 2; ++k) \
;         acc[ai][bj][m][n] = __builtin_amdgcn_mfma_f32_16x16x32_bf16(Bt[n][k], At[m][k], acc[ai][bj][m][n], 0, 0, 0); __builtin_amdgcn_s_setprio(0); } while (0)
; #define PG8_WAIT_V(n) asm volatile("s_waitcnt vmcnt(" #n ")" ::: "memory")
; #define PG8_WAIT_L(n) asm volatile("s_waitcnt lgkmcnt(" #n ")" ::: "memory")
; #define PG8_BAR __builtin_amdgcn_s_barrier()
; #define PG8_SCHED __builtin_amdgcn_sched_barrier(0)
; template <class Epi, class Sched, bool ALIGN_EPI = false, bool SP2 = false>
; __device__ __forceinline__ void gemm_phase(PG8_LAS unsigned char* lds, const Gemm g, const Sched& S, const Epi& E) {
;     ...
;             PG8_WAIT_V(8); PG8_WAIT_L(0); PG8_BAR; PG8_MMA(1, 0, At, B0); PG8_MMA(1, 1, At, B1); PG8_BAR; PG8_SCHED;
;             PG8_LDB(B0, 1, 0); PG8_LDB(B1, 1, 1); PG8_SCHED; PG8_LDA(At, 1, 0); PG8_STAGE(PG8_SA(0, 1), a2 + hstep, voffA);
;             PG8_WAIT_V(8); PG8_WAIT_L(0); PG8_BAR; PG8_MMA(0, 0, At, B0); PG8_MMA(0, 1, At, B1); PG8_BAR; PG8_SCHED;
	s_setprio 1
	s_waitcnt lgkmcnt(0)
	v_mfma_f32_16x16x32_bf16 v[64:67], v[148:151], v[208:211], v[64:67]
	v_mfma_f32_16x16x32_bf16 v[60:63], v[156:159], v[208:211], v[60:63]
	v_mfma_f32_16x16x32_bf16 v[56:59], v[148:151], v[216:219], v[56:59]
	v_mfma_f32_16x16x32_bf16 v[48:51], v[156:159], v[216:219], v[48:51]
	v_mfma_f32_16x16x32_bf16 v[40:43], v[148:151], v[228:231], v[40:43]
	v_mfma_f32_16x16x32_bf16 v[32:35], v[156:159], v[228:231], v[32:35]
	v_mfma_f32_16x16x32_bf16 v[24:27], v[148:151], v[236:239], v[24:27]
	v_mfma_f32_16x16x32_bf16 v[16:19], v[156:159], v[236:239], v[16:19]
	v_mfma_f32_16x16x32_bf16 v[64:67], v[152:155], v[212:215], v[64:67]
	v_mfma_f32_16x16x32_bf16 v[60:63], v[160:163], v[212:215], v[60:63]
	v_mfma_f32_16x16x32_bf16 v[56:59], v[152:155], v[224:227], v[56:59]
	v_mfma_f32_16x16x32_bf16 v[48:51], v[160:163], v[224:227], v[48:51]
	v_mfma_f32_16x16x32_bf16 v[40:43], v[152:155], v[232:235], v[40:43]
	v_mfma_f32_16x16x32_bf16 v[32:35], v[160:163], v[232:235], v[32:35]
	v_mfma_f32_16x16x32_bf16 v[24:27], v[152:155], v[240:243], v[24:27]
	v_mfma_f32_16x16x32_bf16 v[16:19], v[160:163], v[240:243], v[16:19]
	s_setprio 0
	s_setprio 1
	v_mfma_f32_16x16x32_bf16 v[52:55], v[180:183], v[208:211], v[52:55]
	v_mfma_f32_16x16x32_bf16 v[44:47], v[188:191], v[208:211], v[44:47]
	v_mfma_f32_16x16x32_bf16 v[36:39], v[180:183], v[216:219], v[36:39]
	v_mfma_f32_16x16x32_bf16 v[28:31], v[188:191], v[216:219], v[28:31]
	v_mfma_f32_16x16x32_bf16 v[20:23], v[180:183], v[228:231], v[20:23]
	v_mfma_f32_16x16x32_bf16 v[12:15], v[188:191], v[228:231], v[12:15]
	v_mfma_f32_16x16x32_bf16 v[8:11], v[180:183], v[236:239], v[8:11]
	v_mfma_f32_16x16x32_bf16 v[4:7], v[188:191], v[236:239], v[4:7]
	v_mfma_f32_16x16x32_bf16 v[52:55], v[184:187], v[212:215], v[52:55]
	v_mfma_f32_16x16x32_bf16 v[44:47], v[192:195], v[212:215], v[44:47]
	v_mfma_f32_16x16x32_bf16 v[36:39], v[184:187], v[224:227], v[36:39]
	v_mfma_f32_16x16x32_bf16 v[28:31], v[192:195], v[224:227], v[28:31]
	v_mfma_f32_16x16x32_bf16 v[20:23], v[184:187], v[232:235], v[20:23]
	v_mfma_f32_16x16x32_bf16 v[12:15], v[192:195], v[232:235], v[12:15]
	v_mfma_f32_16x16x32_bf16 v[8:11], v[184:187], v[240:243], v[8:11]
	v_mfma_f32_16x16x32_bf16 v[4:7], v[192:195], v[240:243], v[4:7]
	s_setprio 0
	s_barrier
	s_add_i32 s70, 0, 0x18000
	s_add_i32 s71, 0, 0x1c000
	v_add_u32_e32 v160, s70, v145
	v_add_u32_e32 v167, s71, v145
	ds_read_b128 v[148:151], v160
	ds_read_b128 v[152:155], v160 offset:1024
	ds_read_b128 v[156:159], v160 offset:2048
	ds_read_b128 v[160:163], v160 offset:3072
	ds_read_b128 v[180:183], v167
	ds_read_b128 v[184:187], v167 offset:1024
	ds_read_b128 v[188:191], v167 offset:2048
	ds_read_b128 v[192:195], v167 offset:3072
	s_add_u32 s60, s60, 0x40000
	s_addc_u32 s61, s61, 0
	s_mov_b32 m0, s67
	v_lshl_add_u64 v[246:247], s[60:61], 0, v[136:137]
	ds_read_b128 v[208:211], v147 offset:32768
	ds_read_b128 v[212:215], v147 offset:33792
	ds_read_b128 v[216:219], v147 offset:34816
	ds_read_b128 v[224:227], v147 offset:35840
	ds_read_b128 v[228:231], v147 offset:36864
	ds_read_b128 v[232:235], v147 offset:37888
	ds_read_b128 v[236:239], v147 offset:38912
	ds_read_b128 v[240:243], v147 offset:39936
	global_load_lds_dwordx4 v[246:247], off
	v_lshl_add_u64 v[246:247], s[60:61], 0, v[134:135]
	s_mov_b32 m0, s78
	s_nop 0
	global_load_lds_dwordx4 v[246:247], off
	s_waitcnt vmcnt(8)
	s_waitcnt lgkmcnt(0)
	s_barrier
	s_setprio 1
	s_waitcnt lgkmcnt(0)
	v_mfma_f32_16x16x32_bf16 v[128:131], v[148:151], v[208:211], v[128:131]
	v_mfma_f32_16x16x32_bf16 v[124:127], v[156:159], v[208:211], v[124:127]
	v_mfma_f32_16x16x32_bf16 v[120:123], v[148:151], v[216:219], v[120:123]
	v_mfma_f32_16x16x32_bf16 v[112:115], v[156:159], v[216:219], v[112:115]
	v_mfma_f32_16x16x32_bf16 v[104:107], v[148:151], v[228:231], v[104:107]
	v_mfma_f32_16x16x32_bf16 v[96:99], v[156:159], v[228:231], v[96:99]
	v_mfma_f32_16x16x32_bf16 v[88:91], v[148:151], v[236:239], v[88:91]
	v_mfma_f32_16x16x32_bf16 v[80:83], v[156:159], v[236:239], v[80:83]
	v_mfma_f32_16x16x32_bf16 v[128:131], v[152:155], v[212:215], v[128:131]
	v_mfma_f32_16x16x32_bf16 v[124:127], v[160:163], v[212:215], v[124:127]
	v_mfma_f32_16x16x32_bf16 v[120:123], v[152:155], v[224:227], v[120:123]
	v_mfma_f32_16x16x32_bf16 v[112:115], v[160:163], v[224:227], v[112:115]
	v_mfma_f32_16x16x32_bf16 v[104:107], v[152:155], v[232:235], v[104:107]
	v_mfma_f32_16x16x32_bf16 v[96:99], v[160:163], v[232:235], v[96:99]
	v_mfma_f32_16x16x32_bf16 v[88:91], v[152:155], v[240:243], v[88:91]
	v_mfma_f32_16x16x32_bf16 v[80:83], v[160:163], v[240:243], v[80:83]
	s_setprio 0
	s_setprio 1
	v_mfma_f32_16x16x32_bf16 v[116:119], v[180:183], v[208:211], v[116:119]
	v_mfma_f32_16x16x32_bf16 v[108:111], v[188:191], v[208:211], v[108:111]
	v_mfma_f32_16x16x32_bf16 v[100:103], v[180:183], v[216:219], v[100:103]
	v_mfma_f32_16x16x32_bf16 v[92:95], v[188:191], v[216:219], v[92:95]
	v_mfma_f32_16x16x32_bf16 v[84:87], v[180:183], v[228:231], v[84:87]
	v_mfma_f32_16x16x32_bf16 v[76:79], v[188:191], v[228:231], v[76:79]
	v_mfma_f32_16x16x32_bf16 v[72:75], v[180:183], v[236:239], v[72:75]
	v_mfma_f32_16x16x32_bf16 v[68:71], v[188:191], v[236:239], v[68:71]
	v_mfma_f32_16x16x32_bf16 v[116:119], v[184:187], v[212:215], v[116:119]
	v_mfma_f32_16x16x32_bf16 v[108:111], v[192:195], v[212:215], v[108:111]
	v_mfma_f32_16x16x32_bf16 v[100:103], v[184:187], v[224:227], v[100:103]
	v_mfma_f32_16x16x32_bf16 v[92:95], v[192:195], v[224:227], v[92:95]
	v_mfma_f32_16x16x32_bf16 v[84:87], v[184:187], v[232:235], v[84:87]
	v_mfma_f32_16x16x32_bf16 v[76:79], v[192:195], v[232:235], v[76:79]
	v_mfma_f32_16x16x32_bf16 v[72:75], v[184:187], v[240:243], v[72:75]
	v_mfma_f32_16x16x32_bf16 v[68:71], v[192:195], v[240:243], v[68:71]
	s_setprio 0
	s_barrier
; #define PG8_STAGE(bufoff, gbase, voff) do { _Pragma("unroll") for (int _i = 0; _i < 2; ++_i) \
;         __builtin_amdgcn_global_load_lds((const unsigned*)((const char*)(gbase) + (voff)[_i]), (PG8_LAS unsigned*)(lds + (bufoff) + ldsw + _i * 8192), 16, 0, 0); } while (0)
; #define PG8_LDA(dst, b, h) do { _Pragma("unroll") for (int m = 0; m < 4; ++m) _Pragma("unroll") for (int k = 0; k < 2; ++k) dst[m][k] = *(const PG8_LAS bf16x8*)(lds + PG8_SA(b, h) + aoff + m * 2048 + k * 1024); } while (0)
; #define PG8_MMA(ai, bj, At, Bt) do { __builtin_amdgcn_s_setprio(1); _Pragma("unroll") for (int m = 0; m < 4; ++m) _Pragma("unroll") for (int n = 0; n < 2; ++n) _Pragma("unroll") for (int k = 0; k < 2; ++k) \
;         acc[ai][bj][m][n] = __builtin_amdgcn_mfma_f32_16x16x32_bf16(Bt[n][k], At[m][k], acc[ai][bj][m][n], 0, 0, 0); __builtin_amdgcn_s_setprio(0); } while (0)
; #define PG8_WAIT_V(n) asm volatile("s_waitcnt vmcnt(" #n ")" ::: "memory")
; #define PG8_WAIT_L(n) asm volatile("s_waitcnt lgkmcnt(" #n ")" ::: "memory")
; #define PG8_BAR __builtin_amdgcn_s_barrier()
; #define PG8_SCHED __builtin_amdgcn_sched_barrier(0)
; template <class Epi, class Sched, bool ALIGN_EPI = false, bool SP2 = false>
; __device__ __forceinline__ void gemm_phase(PG8_LAS unsigned char* lds, const Gemm g, const Sched& S, const Epi& E) {
;     ...
;         for (int t = 0; t < nt; t += 2) {
;             const bool last = (t == nt - 2);
;     ...
;             PG8_LDA(At, 1, 1); PG8_STAGE(PG8_SB(1, 0), b3, voffB); PG8_STAGE(PG8_SB(1, 1), b3 + hstep, voffB); PG8_STAGE(PG8_SA(1, 0), a3, voffA);
;             PG8_WAIT_V(8); PG8_WAIT_L(0); PG8_BAR; PG8_MMA(1, 0, At, B0); PG8_MMA(1, 1, At, B1); PG8_BAR; PG8_SCHED;
	s_add_i32 s60, s70, s26
	v_lshl_add_u64 v[142:143], v[142:143], 0, s[14:15]
	s_mov_b32 m0, s60
	ds_read_b128 v[208:211], v147 offset:49152
	ds_read_b128 v[212:215], v147 offset:50176
	ds_read_b128 v[216:219], v147 offset:51200
	ds_read_b128 v[224:227], v147 offset:52224
	ds_read_b128 v[228:231], v147 offset:53248
	ds_read_b128 v[232:235], v147 offset:54272
	ds_read_b128 v[236:239], v147 offset:55296
	ds_read_b128 v[240:243], v147 offset:56320
	global_load_lds_dwordx4 v[142:143], off
	s_add_i32 m0, s60, 0x2000
	s_add_u32 s54, s54, 0x40080
	v_lshl_add_u64 v[142:143], v[170:171], 0, s[14:15]
	s_addc_u32 s55, s55, 0
	s_add_i32 s60, s71, s26
	global_load_lds_dwordx4 v[142:143], off
	v_lshl_add_u64 v[142:143], s[54:55], 0, v[2:3]
	s_mov_b32 m0, s60
	s_nop 0
	global_load_lds_dwordx4 v[142:143], off
	v_lshl_add_u64 v[142:143], s[54:55], 0, v[132:133]
	s_add_i32 m0, s60, 0x2000
	s_nop 0
	global_load_lds_dwordx4 v[142:143], off
	v_lshl_add_u64 v[142:143], v[196:197], 0, s[14:15]
	s_mov_b32 m0, s79
	s_nop 0
	global_load_lds_dwordx4 v[142:143], off
	v_lshl_add_u64 v[142:143], v[244:245], 0, s[14:15]
	s_mov_b32 m0, s80
	s_nop 0
	global_load_lds_dwordx4 v[142:143], off
	s_waitcnt vmcnt(8)
	s_waitcnt lgkmcnt(0)
	s_barrier
	s_setprio 1
	s_waitcnt lgkmcnt(0)
	v_mfma_f32_16x16x32_bf16 v[64:67], v[148:151], v[208:211], v[64:67]
	v_mfma_f32_16x16x32_bf16 v[60:63], v[156:159], v[208:211], v[60:63]
	v_mfma_f32_16x16x32_bf16 v[56:59], v[148:151], v[216:219], v[56:59]
	v_mfma_f32_16x16x32_bf16 v[48:51], v[156:159], v[216:219], v[48:51]
	v_mfma_f32_16x16x32_bf16 v[40:43], v[148:151], v[228:231], v[40:43]
	v_mfma_f32_16x16x32_bf16 v[32:35], v[156:159], v[228:231], v[32:35]
	v_mfma_f32_16x16x32_bf16 v[24:27], v[148:151], v[236:239], v[24:27]
	v_mfma_f32_16x16x32_bf16 v[16:19], v[156:159], v[236:239], v[16:19]
	v_mfma_f32_16x16x32_bf16 v[64:67], v[152:155], v[212:215], v[64:67]
	v_mfma_f32_16x16x32_bf16 v[60:63], v[160:163], v[212:215], v[60:63]
	v_mfma_f32_16x16x32_bf16 v[56:59], v[152:155], v[224:227], v[56:59]
	v_mfma_f32_16x16x32_bf16 v[48:51], v[160:163], v[224:227], v[48:51]
	v_mfma_f32_16x16x32_bf16 v[40:43], v[152:155], v[232:235], v[40:43]
	v_mfma_f32_16x16x32_bf16 v[32:35], v[160:163], v[232:235], v[32:35]
	v_mfma_f32_16x16x32_bf16 v[24:27], v[152:155], v[240:243], v[24:27]
	v_mfma_f32_16x16x32_bf16 v[16:19], v[160:163], v[240:243], v[16:19]
	s_setprio 0
	s_setprio 1
	v_mfma_f32_16x16x32_bf16 v[52:55], v[180:183], v[208:211], v[52:55]
	v_mfma_f32_16x16x32_bf16 v[44:47], v[188:191], v[208:211], v[44:47]
	v_mfma_f32_16x16x32_bf16 v[36:39], v[180:183], v[216:219], v[36:39]
	v_mfma_f32_16x16x32_bf16 v[28:31], v[188:191], v[216:219], v[28:31]
	v_mfma_f32_16x16x32_bf16 v[20:23], v[180:183], v[228:231], v[20:23]
	v_mfma_f32_16x16x32_bf16 v[12:15], v[188:191], v[228:231], v[12:15]
	v_mfma_f32_16x16x32_bf16 v[8:11], v[180:183], v[236:239], v[8:11]
	v_mfma_f32_16x16x32_bf16 v[4:7], v[188:191], v[236:239], v[4:7]
	v_mfma_f32_16x16x32_bf16 v[52:55], v[184:187], v[212:215], v[52:55]
	v_mfma_f32_16x16x32_bf16 v[44:47], v[192:195], v[212:215], v[44:47]
	v_mfma_f32_16x16x32_bf16 v[36:39], v[184:187], v[224:227], v[36:39]
	v_mfma_f32_16x16x32_bf16 v[28:31], v[192:195], v[224:227], v[28:31]
	v_mfma_f32_16x16x32_bf16 v[20:23], v[184:187], v[232:235], v[20:23]
	v_mfma_f32_16x16x32_bf16 v[12:15], v[192:195], v[232:235], v[12:15]
	v_mfma_f32_16x16x32_bf16 v[8:11], v[184:187], v[240:243], v[8:11]
	v_mfma_f32_16x16x32_bf16 v[4:7], v[192:195], v[240:243], v[4:7]
	s_setprio 0
	s_add_i32 s89, s89, 2
	s_add_u32 s52, s52, 0x100
	s_addc_u32 s53, s53, 0
	s_add_u32 s84, s84, 0x100
	s_addc_u32 s85, s85, 0
	s_cmp_gt_u32 s89, 13
	s_barrier
	s_cbranch_scc0 .LBB0_866
	s_and_b64 vcc, exec, s[42:43]
	s_cbranch_vccz .LBB0_869
	s_barrier
